# unrolled GEMM tile loops: stage-1 LDS-DMA group issued before the tile's first barrier (wait stage 0 only); token_c q-row loads batched
# speedup vs baseline: 1.0098x; 1.0019x over previous
; #define WAIT_V0() asm volatile("s_waitcnt vmcnt(0)" ::: "memory")
; DI int glds_row(int i) { const int tid = ltid(); return ((tid >> 6) * 4 + i) * 8 + ((tid & 63) >> 3); }
; DI int glds_chunk(int row) { return (ltid() & 7) ^ ((row >> 1) & 7); }
; DI void gemm_core(char* smem, int nk, const char* Ab, const char* Bb, const unsigned (&aoff)[4], const unsigned (&boff)[4],
;                   f32x16 (&acc)[2][2]) {
;     ...
;   auto stage = [&](int buf, int kt) __attribute__((always_inline)) {
;     const char* ak = Ab + kt * 128;
;     const char* bk = Bb + kt * 128;
;     char* sa = smem + buf * STAGE_B + w * 4096;
; #pragma unroll
;     for (int i = 0; i < 4; ++i) {
;       __builtin_amdgcn_global_load_lds((const unsigned*)(ak + aoff[i]), (unsigned*)(sa + i * 1024), 16, 0, 0);
;       __builtin_amdgcn_global_load_lds((const unsigned*)(bk + boff[i]), (unsigned*)(sa + 16384 + i * 1024), 16, 0, 0);
;     }
;   };
;   stage(0, 0);
;   WAIT_V0();
;   __syncthreads();
;   for (int kt = 0; kt < nk; ++kt) {
;     const int cur = kt & 1;
;     if (kt + 1 < nk) stage(cur ^ 1, kt + 1);
; DI void phase_up(const Params& P, int layer, char* smem) {
;     ...
;   for (int t0 = blockIdx.x; t0 < MT * NT; t0 += gridDim.x) {
;     const int tl = xcd_tile(t0, MT * NT) - (t0 & 7) * ((MT * NT) >> 3);
;     const int mt = (t0 & 1) * 131 + tl / 11, nt = ((t0 & 7) >> 1) * 11 + tl % 11;
;     const int b = mt / 131, i = mt % 131;
;     const int tb0 = i * 126 - 2;
;     unsigned aoff[4], boff[4];
;     const char* Abase = (const char*)(hn + (size_t)b * S_ * 1024);
;     const unsigned zoff = (unsigned)((P.ws + OFF_ZPAGE) - Abase);
; #pragma unroll
;     for (int q = 0; q < 4; ++q) {
;       const int r = glds_row(q), ch = glds_chunk(r);
;       const int tb = tb0 + r;
;       const bool ok = (tb >= 0) && (tb < S_);
;       aoff[q] = ok ? (unsigned)((tb * 1024 + ch * 8) * 2) : zoff;
;       const int wr = (r < 64) ? (nt * 64 + r) : (DFF + nt * 64 + r - 64);
;       boff[q] = (unsigned)((wr * 1024 + ch * 8) * 2);
;     }
;     f32x16 acc[2][2];
;     gemm_core(smem, 16, Abase, (const char*)wup, aoff, boff, acc);
.LBB0_25:
	s_ashr_i32 s18, s2, 3
	s_and_b32 s19, s18, 0xffffffc0
	s_lshl_b32 s20, s18, 1
	s_bfe_u32 s21, s18, 0x10005
	s_and_b32 s20, s20, 62
	s_or_b32 s19, s21, s19
	s_or_b32 s19, s19, s20
	s_or_b32 s20, s18, 63
	s_cmpk_lt_i32 s20, 0x5a1
	s_cselect_b32 s18, s19, s18
	s_bitcmp1_b32 s2, 0
	s_mul_hi_i32 s20, s18, 0x2e8ba2e9
	s_cselect_b32 s19, 0x83, 0
	s_lshr_b32 s21, s20, 31
	s_ashr_i32 s20, s20, 1
	s_add_i32 s21, s20, s21
	s_add_i32 s20, s21, s19
	s_bfe_u32 s19, s2, 0x20001
	s_mul_i32 s21, s21, 11
	s_mul_i32 s19, s19, 11
	s_sub_i32 s18, s18, s21
	s_add_i32 s21, s18, s19
	s_mul_hi_i32 s18, s20, 0x3e88cb3d
	s_lshr_b32 s19, s18, 31
	s_ashr_i32 s18, s18, 5
	v_mov_b32_e32 v0, v161
	s_add_i32 s68, s18, s19
	s_mul_i32 s18, s68, 0x83
	v_ashrrev_i32_e32 v1, 1, v0
	v_lshrrev_b32_e32 v2, 3, v0
	v_bfe_u32 v0, v0, 3, 3
	s_movk_i32 s3, 0xffe0
	s_sub_i32 s28, s20, s18
	v_and_or_b32 v0, v1, s3, v0
	v_mov_b32_e32 v1, v161
	s_mulk_i32 s28, 0x7e
	s_ashr_i32 s69, s68, 31
	v_bfe_u32 v2, v2, 1, 2
	s_add_i32 s29, s28, -2
	s_lshl_b64 s[22:23], s[68:69], 25
	v_xor_b32_e32 v1, v2, v1
	s_add_u32 s18, s84, s22
	v_lshlrev_b32_e32 v1, 4, v1
	s_addc_u32 s19, s85, s23
	s_sub_i32 s22, 0x1b508000, s22
	s_lshl_b32 s21, s21, 6
	v_add_u32_e32 v2, s29, v0
	v_and_b32_e32 v1, 0x70, v1
	s_movk_i32 s3, 0x4000
	s_add_i32 s23, s21, 0xac0
	v_lshl_or_b32 v3, v2, 11, v1
	v_mov_b32_e32 v4, s22
	v_cmp_gt_u32_e32 vcc, s3, v2
	v_mov_b32_e32 v5, s21
	v_mov_b32_e32 v12, v161
	v_cndmask_b32_e32 v136, v4, v3, vcc
	v_mov_b32_e32 v3, s23
	v_cmp_gt_i32_e32 vcc, 64, v0
	v_lshl_add_u64 v[64:65], s[18:19], 0, v[136:137]
	s_mov_b64 s[4:5], 0x100
	v_cndmask_b32_e32 v2, v3, v5, vcc
	v_add_u32_e32 v0, v2, v0
	v_lshl_or_b32 v76, v0, 11, v1
	v_mov_b32_e32 v0, v161
	s_mov_b64 s[6:7], 0x780
	v_ashrrev_i32_e32 v1, 1, v0
	v_and_b32_e32 v1, 0xffffffe0, v1
	v_bfe_u32 v0, v0, 3, 3
	v_or3_b32 v1, v1, v0, 8
	v_mov_b32_e32 v0, v161
	v_lshrrev_b32_e32 v2, 1, v1
	v_xor_b32_e32 v0, v2, v0
	v_lshlrev_b32_e32 v0, 4, v0
	v_add_u32_e32 v2, s29, v1
	v_and_b32_e32 v6, 0x70, v0
	v_lshl_or_b32 v0, v2, 11, v6
	v_cmp_gt_u32_e32 vcc, s3, v2
	s_nop 1
	v_cndmask_b32_e32 v0, v4, v0, vcc
	v_cmp_gt_i32_e32 vcc, 64, v1
	s_nop 1
	v_cndmask_b32_e32 v2, v3, v5, vcc
	v_add_u32_e32 v1, v2, v1
	v_lshl_or_b32 v77, v1, 11, v6
	v_mov_b32_e32 v1, v161
	s_nop 0
	v_ashrrev_i32_e32 v2, 1, v1
	v_and_b32_e32 v2, 0xffffffe0, v2
	v_lshrrev_b32_e32 v6, 3, v1
	v_bfe_u32 v1, v1, 3, 3
	v_or3_b32 v1, v2, v1, 16
	v_mov_b32_e32 v2, v161
	v_bfe_u32 v6, v6, 1, 2
	v_xor_b32_e32 v2, v6, v2
	v_lshlrev_b32_e32 v2, 4, v2
	v_add_u32_e32 v6, s29, v1
	v_and_b32_e32 v7, 0x70, v2
	v_lshl_or_b32 v2, v6, 11, v7
	v_cmp_gt_u32_e32 vcc, s3, v6
	s_nop 1
	v_cndmask_b32_e32 v2, v4, v2, vcc
	v_cmp_gt_i32_e32 vcc, 64, v1
	s_nop 1
	v_cndmask_b32_e32 v6, v3, v5, vcc
	v_add_u32_e32 v1, v6, v1
	v_lshl_or_b32 v78, v1, 11, v7
	v_mov_b32_e32 v1, v161
	s_nop 0
	v_ashrrev_i32_e32 v6, 1, v1
	v_and_b32_e32 v6, 0xffffffe0, v6
	v_bfe_u32 v1, v1, 3, 3
	v_or3_b32 v1, v6, v1, 24
	v_mov_b32_e32 v6, v161
	v_lshrrev_b32_e32 v7, 1, v1
	v_xor_b32_e32 v6, v7, v6
	v_lshlrev_b32_e32 v6, 4, v6
	v_add_u32_e32 v7, s29, v1
	v_and_b32_e32 v6, 0x70, v6
	v_lshl_or_b32 v8, v7, 11, v6
	v_cmp_gt_u32_e32 vcc, s3, v7
	s_mov_b32 s3, 0x1ffffc0
	v_bfe_u32 v86, v12, 1, 3
	v_cndmask_b32_e32 v4, v4, v8, vcc
	v_cmp_gt_i32_e32 vcc, 64, v1
	v_bfe_u32 v117, v12, 5, 1
	s_nop 0
	v_cndmask_b32_e32 v3, v3, v5, vcc
	v_add_u32_e32 v1, v3, v1
	v_lshl_or_b32 v84, v1, 11, v6
	v_and_b32_e32 v1, 31, v12
	v_lshrrev_b32_e32 v5, 1, v12
	v_and_or_b32 v1, v5, s3, v1
	v_lshlrev_b32_e32 v87, 7, v1
	v_lshlrev_b32_e32 v1, 6, v12
	v_and_b32_e32 v97, 0xfffff000, v1
	v_add_u32_e32 v96, 0x4000, v97
	v_readfirstlane_b32 s84, v97
	s_mov_b32 m0, s84
	v_readfirstlane_b32 s85, v96
	v_or_b32_e32 v98, 0x400, v97
	global_load_lds_dwordx4 v136, s[18:19]
	s_mov_b32 m0, s85
	v_readfirstlane_b32 s86, v98
	v_add_u32_e32 v99, 0x4400, v97
	global_load_lds_dwordx4 v76, s[0:1]
	s_mov_b32 m0, s86
	v_readfirstlane_b32 s87, v99
	v_or_b32_e32 v100, 0x800, v97
	global_load_lds_dwordx4 v0, s[18:19]
	s_mov_b32 m0, s87
	v_readfirstlane_b32 s88, v100
	v_add_u32_e32 v101, 0x4800, v97
	v_lshrrev_b32_e32 v3, 5, v12
	global_load_lds_dwordx4 v77, s[0:1]
	s_mov_b32 m0, s88
	v_readfirstlane_b32 s89, v101
	v_or_b32_e32 v102, 0xc00, v97
	v_bitop3_b32 v3, v3, v86, 1 bitop3:0x6c
	global_load_lds_dwordx4 v2, s[18:19]
	s_mov_b32 m0, s89
	v_readfirstlane_b32 s90, v102
	v_add_u32_e32 v103, 0x4c00, v97
	v_lshlrev_b32_e32 v6, 4, v3
	v_mov_b32_e32 v1, v137
	v_mov_b32_e32 v3, v137
	global_load_lds_dwordx4 v78, s[0:1]
	v_mov_b32_e32 v5, v137
	s_mov_b32 m0, s90
	v_readfirstlane_b32 s91, v103
	v_add_u32_e32 v89, 0x8000, v97
	v_lshl_add_u64 v[66:67], s[18:19], 0, v[0:1]
	v_lshl_add_u64 v[68:69], s[18:19], 0, v[2:3]
	v_lshl_add_u64 v[70:71], s[18:19], 0, v[4:5]
	global_load_lds_dwordx4 v4, s[18:19]
	s_mov_b32 m0, s91
	v_add_u32_e32 v88, 0xc000, v97
	v_readfirstlane_b32 s18, v89
	global_load_lds_dwordx4 v84, s[0:1]
	v_lshl_add_u64 v[0:1], v[64:65], 0, s[94:95]
	s_mov_b32 m0, s18
	v_readfirstlane_b32 s19, v88
	v_add_u32_e32 v90, 0x8400, v97
	global_load_lds_dwordx4 v[0:1], off
	s_mov_b32 m0, s19
	v_readfirstlane_b32 s22, v90
	v_add_u32_e32 v91, 0xc400, v97
	global_load_lds_dwordx4 v76, s[14:15]
	v_lshl_add_u64 v[0:1], v[66:67], 0, s[94:95]
	s_mov_b32 m0, s22
	v_readfirstlane_b32 s23, v91
	v_add_u32_e32 v92, 0x8800, v97
	global_load_lds_dwordx4 v[0:1], off
	s_mov_b32 m0, s23
	v_readfirstlane_b32 s29, v92
	v_add_u32_e32 v93, 0xc800, v97
	global_load_lds_dwordx4 v77, s[14:15]
	v_lshl_add_u64 v[0:1], v[68:69], 0, s[94:95]
	s_mov_b32 m0, s29
	v_readfirstlane_b32 s69, v93
	v_add_u32_e32 v94, 0x8c00, v97
	global_load_lds_dwordx4 v[0:1], off
	s_mov_b32 m0, s69
	v_readfirstlane_b32 s70, v94
	v_add_u32_e32 v95, 0xcc00, v97
	global_load_lds_dwordx4 v78, s[14:15]
	v_lshl_add_u64 v[0:1], v[70:71], 0, s[94:95]
	s_mov_b32 m0, s70
	v_readfirstlane_b32 s71, v95
	global_load_lds_dwordx4 v[0:1], off
	s_mov_b32 m0, s71
	v_or_b32_e32 v79, v87, v6
	global_load_lds_dwordx4 v84, s[14:15]
	s_waitcnt vmcnt(8)
	s_waitcnt vmcnt(8) lgkmcnt(0)
	s_barrier
; #define WAIT_V0() asm volatile("s_waitcnt vmcnt(0)" ::: "memory")
; DI void gemm_core(char* smem, int nk, const char* Ab, const char* Bb, const unsigned (&aoff)[4], const unsigned (&boff)[4],
;                   f32x16 (&acc)[2][2]) {
;     ...
;   for (int kt = 0; kt < nk; ++kt) {
;     const int cur = kt & 1;
;     if (kt + 1 < nk) stage(cur ^ 1, kt + 1);
;     const char* sb = smem + cur * STAGE_B;
; #pragma unroll
;     for (int ks = 0; ks < 4; ++ks) {
;       bf16x8 af[2], bfr[2];
; #pragma unroll
;       for (int mb = 0; mb < 2; ++mb) af[mb] = *(const bf16x8*)(sb + a_base + mb * 4096 + xo[ks]);
; #pragma unroll
;       for (int nb = 0; nb < 2; ++nb) bfr[nb] = *(const bf16x8*)(sb + b_base + nb * 4096 + xo[ks]);
; #pragma unroll
;       for (int mb = 0; mb < 2; ++mb)
; #pragma unroll
;         for (int nb = 0; nb < 2; ++nb)
;           acc[mb][nb] = __builtin_amdgcn_mfma_f32_32x32x16_bf16(af[mb], bfr[nb], acc[mb][nb], 0, 0, 0);
;     }
;     WAIT_V0();
;     __syncthreads();
;   }
	ds_read_b128 v[0:3], v79
	v_lshlrev_b32_e32 v4, 7, v12
	v_and_b32_e32 v116, 0x2f80, v4
	v_or_b32_e32 v81, v116, v6
	ds_read_b128 v[4:7], v81 offset:16384
	ds_read_b128 v[8:11], v81 offset:20480
	s_waitcnt lgkmcnt(0)
	v_mfma_f32_32x32x16_bf16 v[48:63], v[0:3], v[4:7], 0
	s_mov_b32 m0, s84
	s_mov_b32 s3, 0xfffffc0
	v_mfma_f32_32x32x16_bf16 v[32:47], v[0:3], v[8:11], 0
	ds_read_b128 v[0:3], v79 offset:4096
	s_waitcnt lgkmcnt(0)
	v_mfma_f32_32x32x16_bf16 v[16:31], v[0:3], v[4:7], 0
	v_bitop3_b32 v4, v117, v86, 2 bitop3:0x36
	v_lshlrev_b32_e32 v82, 4, v4
	v_or_b32_e32 v80, v87, v82
	ds_read_b128 v[104:107], v80
	v_or_b32_e32 v83, v116, v82
	ds_read_b128 v[108:111], v83 offset:16384
	ds_read_b128 v[112:115], v83 offset:20480
	s_waitcnt lgkmcnt(0)
	v_mfma_f32_32x32x16_bf16 v[48:63], v[104:107], v[108:111], v[48:63]
	v_bitop3_b32 v82, v117, v86, 4 bitop3:0x36
	v_lshlrev_b32_e32 v85, 4, v82
	v_or_b32_e32 v82, v87, v85
	v_or_b32_e32 v85, v116, v85
	v_bitop3_b32 v86, v117, v86, 6 bitop3:0x36
	v_mfma_f32_32x32x16_bf16 v[32:47], v[104:107], v[112:115], v[32:47]
	ds_read_b128 v[104:107], v80 offset:4096
	v_mfma_f32_32x32x16_bf16 v[0:15], v[0:3], v[8:11], 0
	s_waitcnt lgkmcnt(0)
	v_mfma_f32_32x32x16_bf16 v[16:31], v[104:107], v[108:111], v[16:31]
	ds_read_b128 v[108:111], v85 offset:16384
	v_mfma_f32_32x32x16_bf16 v[0:15], v[104:107], v[112:115], v[0:15]
	ds_read_b128 v[104:107], v82
	ds_read_b128 v[112:115], v85 offset:20480
	s_waitcnt lgkmcnt(0)
	v_mfma_f32_32x32x16_bf16 v[48:63], v[104:107], v[108:111], v[48:63]
	v_mfma_f32_32x32x16_bf16 v[32:47], v[104:107], v[112:115], v[32:47]
	ds_read_b128 v[104:107], v82 offset:4096
	s_waitcnt lgkmcnt(0)
	v_mfma_f32_32x32x16_bf16 v[16:31], v[104:107], v[108:111], v[16:31]
	v_lshlrev_b32_e32 v108, 4, v86
	v_or_b32_e32 v86, v87, v108
	v_or_b32_e32 v87, v116, v108
	ds_read_b128 v[108:111], v87 offset:16384
	v_mfma_f32_32x32x16_bf16 v[0:15], v[104:107], v[112:115], v[0:15]
	ds_read_b128 v[104:107], v86
	ds_read_b128 v[112:115], v87 offset:20480
	s_waitcnt lgkmcnt(0)
	v_mfma_f32_32x32x16_bf16 v[48:63], v[104:107], v[108:111], v[48:63]
	v_mfma_f32_32x32x16_bf16 v[32:47], v[104:107], v[112:115], v[32:47]
	ds_read_b128 v[104:107], v86 offset:4096
	s_waitcnt vmcnt(0)
	s_waitcnt vmcnt(0) lgkmcnt(0)
	s_barrier
	v_mfma_f32_32x32x16_bf16 v[16:31], v[104:107], v[108:111], v[16:31]
	v_mfma_f32_32x32x16_bf16 v[0:15], v[104:107], v[112:115], v[0:15]
	v_lshl_add_u64 v[104:105], v[64:65], 0, s[4:5]
	global_load_lds_dwordx4 v[104:105], off
	s_mov_b32 m0, s85
	v_lshl_add_u64 v[104:105], v[66:67], 0, s[4:5]
	global_load_lds_dwordx4 v76, s[16:17]
	s_mov_b32 m0, s86
	s_nop 0
	global_load_lds_dwordx4 v[104:105], off
	s_mov_b32 m0, s87
	v_lshl_add_u64 v[104:105], v[68:69], 0, s[4:5]
	global_load_lds_dwordx4 v77, s[16:17]
	s_mov_b32 m0, s88
	s_nop 0
	global_load_lds_dwordx4 v[104:105], off
	s_mov_b32 m0, s89
	v_lshl_add_u64 v[104:105], v[70:71], 0, s[4:5]
	global_load_lds_dwordx4 v78, s[16:17]
	s_mov_b32 m0, s90
	s_mov_b64 s[4:5], 0x180
	global_load_lds_dwordx4 v[104:105], off
	s_mov_b32 m0, s91
	s_nop 0
	global_load_lds_dwordx4 v84, s[16:17]
	ds_read_b128 v[104:107], v79 offset:32768
	ds_read_b128 v[108:111], v81 offset:49152
	ds_read_b128 v[112:115], v81 offset:53248
	s_waitcnt lgkmcnt(0)
	v_mfma_f32_32x32x16_bf16 v[48:63], v[104:107], v[108:111], v[48:63]
	s_mov_b32 m0, s18
	v_mfma_f32_32x32x16_bf16 v[32:47], v[104:107], v[112:115], v[32:47]
	ds_read_b128 v[104:107], v79 offset:36864
	s_waitcnt lgkmcnt(0)
	v_mfma_f32_32x32x16_bf16 v[16:31], v[104:107], v[108:111], v[16:31]
	v_mfma_f32_32x32x16_bf16 v[0:15], v[104:107], v[112:115], v[0:15]
	ds_read_b128 v[104:107], v80 offset:32768
	ds_read_b128 v[108:111], v83 offset:49152
	ds_read_b128 v[112:115], v83 offset:53248
	s_waitcnt lgkmcnt(0)
	v_mfma_f32_32x32x16_bf16 v[48:63], v[104:107], v[108:111], v[48:63]
	v_mfma_f32_32x32x16_bf16 v[32:47], v[104:107], v[112:115], v[32:47]
	ds_read_b128 v[104:107], v80 offset:36864
	s_waitcnt lgkmcnt(0)
	v_mfma_f32_32x32x16_bf16 v[16:31], v[104:107], v[108:111], v[16:31]
	v_mfma_f32_32x32x16_bf16 v[0:15], v[104:107], v[112:115], v[0:15]
	ds_read_b128 v[104:107], v82 offset:32768
	ds_read_b128 v[108:111], v85 offset:49152
	ds_read_b128 v[112:115], v85 offset:53248
	s_waitcnt lgkmcnt(0)
	v_mfma_f32_32x32x16_bf16 v[48:63], v[104:107], v[108:111], v[48:63]
	v_mfma_f32_32x32x16_bf16 v[32:47], v[104:107], v[112:115], v[32:47]
	ds_read_b128 v[104:107], v82 offset:36864
	s_waitcnt lgkmcnt(0)
	v_mfma_f32_32x32x16_bf16 v[16:31], v[104:107], v[108:111], v[16:31]
	v_mfma_f32_32x32x16_bf16 v[0:15], v[104:107], v[112:115], v[0:15]
	ds_read_b128 v[104:107], v86 offset:32768
	ds_read_b128 v[108:111], v87 offset:49152
	ds_read_b128 v[112:115], v87 offset:53248
	s_waitcnt lgkmcnt(0)
	v_mfma_f32_32x32x16_bf16 v[48:63], v[104:107], v[108:111], v[48:63]
	v_mfma_f32_32x32x16_bf16 v[32:47], v[104:107], v[112:115], v[32:47]
	ds_read_b128 v[104:107], v86 offset:36864
	s_waitcnt vmcnt(0)
	s_waitcnt vmcnt(0) lgkmcnt(0)
	s_barrier
; #define WAIT_V0() asm volatile("s_waitcnt vmcnt(0)" ::: "memory")
; DI void gemm_core(char* smem, int nk, const char* Ab, const char* Bb, const unsigned (&aoff)[4], const unsigned (&boff)[4],
;                   f32x16 (&acc)[2][2]) {
;     ...
;   for (int kt = 0; kt < nk; ++kt) {
;     const int cur = kt & 1;
;     if (kt + 1 < nk) stage(cur ^ 1, kt + 1);
;     const char* sb = smem + cur * STAGE_B;
; #pragma unroll
;     for (int ks = 0; ks < 4; ++ks) {
;       bf16x8 af[2], bfr[2];
; #pragma unroll
;       for (int mb = 0; mb < 2; ++mb) af[mb] = *(const bf16x8*)(sb + a_base + mb * 4096 + xo[ks]);
; #pragma unroll
;       for (int nb = 0; nb < 2; ++nb) bfr[nb] = *(const bf16x8*)(sb + b_base + nb * 4096 + xo[ks]);
; #pragma unroll
;       for (int mb = 0; mb < 2; ++mb)
; #pragma unroll
;         for (int nb = 0; nb < 2; ++nb)
;           acc[mb][nb] = __builtin_amdgcn_mfma_f32_32x32x16_bf16(af[mb], bfr[nb], acc[mb][nb], 0, 0, 0);
;     }
;     WAIT_V0();
;     __syncthreads();
;   }
	v_mfma_f32_32x32x16_bf16 v[16:31], v[104:107], v[108:111], v[16:31]
	v_mfma_f32_32x32x16_bf16 v[0:15], v[104:107], v[112:115], v[0:15]
	v_lshl_add_u64 v[104:105], v[64:65], 0, s[4:5]
	global_load_lds_dwordx4 v[104:105], off
	s_mov_b32 m0, s19
	v_lshl_add_u64 v[104:105], v[66:67], 0, s[4:5]
	global_load_lds_dwordx4 v76, s[42:43]
	s_mov_b32 m0, s22
	s_nop 0
	global_load_lds_dwordx4 v[104:105], off
	s_mov_b32 m0, s23
	v_lshl_add_u64 v[104:105], v[68:69], 0, s[4:5]
	global_load_lds_dwordx4 v77, s[42:43]
	s_mov_b32 m0, s29
	s_nop 0
	global_load_lds_dwordx4 v[104:105], off
	s_mov_b32 m0, s69
	v_lshl_add_u64 v[104:105], v[70:71], 0, s[4:5]
	global_load_lds_dwordx4 v78, s[42:43]
	s_mov_b32 m0, s70
	s_mov_b64 s[4:5], 0x280
	global_load_lds_dwordx4 v[104:105], off
	s_mov_b32 m0, s71
	s_nop 0
	global_load_lds_dwordx4 v84, s[42:43]
	ds_read_b128 v[104:107], v79
	ds_read_b128 v[108:111], v81 offset:16384
	ds_read_b128 v[112:115], v81 offset:20480
	s_waitcnt lgkmcnt(0)
	v_mfma_f32_32x32x16_bf16 v[48:63], v[104:107], v[108:111], v[48:63]
	s_mov_b32 m0, s84
	v_mfma_f32_32x32x16_bf16 v[32:47], v[104:107], v[112:115], v[32:47]
	ds_read_b128 v[104:107], v79 offset:4096
	s_waitcnt lgkmcnt(0)
	v_mfma_f32_32x32x16_bf16 v[16:31], v[104:107], v[108:111], v[16:31]
	v_mfma_f32_32x32x16_bf16 v[0:15], v[104:107], v[112:115], v[0:15]
	ds_read_b128 v[104:107], v80
	ds_read_b128 v[108:111], v83 offset:16384
	ds_read_b128 v[112:115], v83 offset:20480
	s_waitcnt lgkmcnt(0)
	v_mfma_f32_32x32x16_bf16 v[48:63], v[104:107], v[108:111], v[48:63]
	v_mfma_f32_32x32x16_bf16 v[32:47], v[104:107], v[112:115], v[32:47]
	ds_read_b128 v[104:107], v80 offset:4096
	s_waitcnt lgkmcnt(0)
	v_mfma_f32_32x32x16_bf16 v[16:31], v[104:107], v[108:111], v[16:31]
	v_mfma_f32_32x32x16_bf16 v[0:15], v[104:107], v[112:115], v[0:15]
	ds_read_b128 v[104:107], v82
	ds_read_b128 v[108:111], v85 offset:16384
	ds_read_b128 v[112:115], v85 offset:20480
	s_waitcnt lgkmcnt(0)
	v_mfma_f32_32x32x16_bf16 v[48:63], v[104:107], v[108:111], v[48:63]
	v_mfma_f32_32x32x16_bf16 v[32:47], v[104:107], v[112:115], v[32:47]
	ds_read_b128 v[104:107], v82 offset:4096
	s_waitcnt lgkmcnt(0)
	v_mfma_f32_32x32x16_bf16 v[16:31], v[104:107], v[108:111], v[16:31]
	v_mfma_f32_32x32x16_bf16 v[0:15], v[104:107], v[112:115], v[0:15]
	ds_read_b128 v[104:107], v86
	ds_read_b128 v[108:111], v87 offset:16384
	ds_read_b128 v[112:115], v87 offset:20480
	s_waitcnt lgkmcnt(0)
	v_mfma_f32_32x32x16_bf16 v[48:63], v[104:107], v[108:111], v[48:63]
	v_mfma_f32_32x32x16_bf16 v[32:47], v[104:107], v[112:115], v[32:47]
	ds_read_b128 v[104:107], v86 offset:4096
	s_waitcnt vmcnt(0)
	s_waitcnt vmcnt(0) lgkmcnt(0)
	s_barrier
	v_mfma_f32_32x32x16_bf16 v[16:31], v[104:107], v[108:111], v[16:31]
	v_mfma_f32_32x32x16_bf16 v[0:15], v[104:107], v[112:115], v[0:15]
	v_lshl_add_u64 v[104:105], v[64:65], 0, s[30:31]
	global_load_lds_dwordx4 v[104:105], off
	s_mov_b32 m0, s85
	v_lshl_add_u64 v[104:105], v[66:67], 0, s[30:31]
	global_load_lds_dwordx4 v76, s[44:45]
	s_mov_b32 m0, s86
	s_nop 0
	global_load_lds_dwordx4 v[104:105], off
	s_mov_b32 m0, s87
	v_lshl_add_u64 v[104:105], v[68:69], 0, s[30:31]
	global_load_lds_dwordx4 v77, s[44:45]
	s_mov_b32 m0, s88
	s_nop 0
	global_load_lds_dwordx4 v[104:105], off
	s_mov_b32 m0, s89
	v_lshl_add_u64 v[104:105], v[70:71], 0, s[30:31]
	global_load_lds_dwordx4 v78, s[44:45]
	s_mov_b32 m0, s90
	s_nop 0
	global_load_lds_dwordx4 v[104:105], off
	s_mov_b32 m0, s91
	s_nop 0
	global_load_lds_dwordx4 v84, s[44:45]
	ds_read_b128 v[104:107], v79 offset:32768
	ds_read_b128 v[108:111], v81 offset:49152
	ds_read_b128 v[112:115], v81 offset:53248
	s_waitcnt lgkmcnt(0)
	v_mfma_f32_32x32x16_bf16 v[48:63], v[104:107], v[108:111], v[48:63]
	s_mov_b32 m0, s18
	v_mfma_f32_32x32x16_bf16 v[32:47], v[104:107], v[112:115], v[32:47]
	ds_read_b128 v[104:107], v79 offset:36864
	s_waitcnt lgkmcnt(0)
	v_mfma_f32_32x32x16_bf16 v[16:31], v[104:107], v[108:111], v[16:31]
	v_mfma_f32_32x32x16_bf16 v[0:15], v[104:107], v[112:115], v[0:15]
	ds_read_b128 v[104:107], v80 offset:32768
	ds_read_b128 v[108:111], v83 offset:49152
	ds_read_b128 v[112:115], v83 offset:53248
	s_waitcnt lgkmcnt(0)
	v_mfma_f32_32x32x16_bf16 v[48:63], v[104:107], v[108:111], v[48:63]
	v_mfma_f32_32x32x16_bf16 v[32:47], v[104:107], v[112:115], v[32:47]
	ds_read_b128 v[104:107], v80 offset:36864
	s_waitcnt lgkmcnt(0)
	v_mfma_f32_32x32x16_bf16 v[16:31], v[104:107], v[108:111], v[16:31]
	v_mfma_f32_32x32x16_bf16 v[0:15], v[104:107], v[112:115], v[0:15]
	ds_read_b128 v[104:107], v82 offset:32768
	ds_read_b128 v[108:111], v85 offset:49152
	ds_read_b128 v[112:115], v85 offset:53248
	s_waitcnt lgkmcnt(0)
	v_mfma_f32_32x32x16_bf16 v[48:63], v[104:107], v[108:111], v[48:63]
	v_mfma_f32_32x32x16_bf16 v[32:47], v[104:107], v[112:115], v[32:47]
	ds_read_b128 v[104:107], v82 offset:36864
	s_waitcnt lgkmcnt(0)
	v_mfma_f32_32x32x16_bf16 v[16:31], v[104:107], v[108:111], v[16:31]
	v_mfma_f32_32x32x16_bf16 v[0:15], v[104:107], v[112:115], v[0:15]
	ds_read_b128 v[104:107], v86 offset:32768
	ds_read_b128 v[108:111], v87 offset:49152
	ds_read_b128 v[112:115], v87 offset:53248
	s_waitcnt lgkmcnt(0)
	v_mfma_f32_32x32x16_bf16 v[48:63], v[104:107], v[108:111], v[48:63]
	v_mfma_f32_32x32x16_bf16 v[32:47], v[104:107], v[112:115], v[32:47]
	ds_read_b128 v[104:107], v86 offset:36864
	s_waitcnt vmcnt(0)
	s_waitcnt vmcnt(0) lgkmcnt(0)
	s_barrier
; #define WAIT_V0() asm volatile("s_waitcnt vmcnt(0)" ::: "memory")
; DI void gemm_core(char* smem, int nk, const char* Ab, const char* Bb, const unsigned (&aoff)[4], const unsigned (&boff)[4],
;                   f32x16 (&acc)[2][2]) {
;     ...
;   for (int kt = 0; kt < nk; ++kt) {
;     const int cur = kt & 1;
;     if (kt + 1 < nk) stage(cur ^ 1, kt + 1);
;     const char* sb = smem + cur * STAGE_B;
; #pragma unroll
;     for (int ks = 0; ks < 4; ++ks) {
;       bf16x8 af[2], bfr[2];
; #pragma unroll
;       for (int mb = 0; mb < 2; ++mb) af[mb] = *(const bf16x8*)(sb + a_base + mb * 4096 + xo[ks]);
; #pragma unroll
;       for (int nb = 0; nb < 2; ++nb) bfr[nb] = *(const bf16x8*)(sb + b_base + nb * 4096 + xo[ks]);
; #pragma unroll
;       for (int mb = 0; mb < 2; ++mb)
; #pragma unroll
;         for (int nb = 0; nb < 2; ++nb)
;           acc[mb][nb] = __builtin_amdgcn_mfma_f32_32x32x16_bf16(af[mb], bfr[nb], acc[mb][nb], 0, 0, 0);
;     }
;     WAIT_V0();
;     __syncthreads();
;   }
	v_mfma_f32_32x32x16_bf16 v[16:31], v[104:107], v[108:111], v[16:31]
	v_mfma_f32_32x32x16_bf16 v[0:15], v[104:107], v[112:115], v[0:15]
	v_lshl_add_u64 v[104:105], v[64:65], 0, s[4:5]
	global_load_lds_dwordx4 v[104:105], off
	s_mov_b32 m0, s19
	v_lshl_add_u64 v[104:105], v[66:67], 0, s[4:5]
	global_load_lds_dwordx4 v76, s[46:47]
	s_mov_b32 m0, s22
	s_nop 0
	global_load_lds_dwordx4 v[104:105], off
	s_mov_b32 m0, s23
	v_lshl_add_u64 v[104:105], v[68:69], 0, s[4:5]
	global_load_lds_dwordx4 v77, s[46:47]
	s_mov_b32 m0, s29
	s_nop 0
	global_load_lds_dwordx4 v[104:105], off
	s_mov_b32 m0, s69
	v_lshl_add_u64 v[104:105], v[70:71], 0, s[4:5]
	global_load_lds_dwordx4 v78, s[46:47]
	s_mov_b32 m0, s70
	s_mov_b64 s[4:5], 0x300
	global_load_lds_dwordx4 v[104:105], off
	s_mov_b32 m0, s71
	s_nop 0
	global_load_lds_dwordx4 v84, s[46:47]
	ds_read_b128 v[104:107], v79
	ds_read_b128 v[108:111], v81 offset:16384
	ds_read_b128 v[112:115], v81 offset:20480
	s_waitcnt lgkmcnt(0)
	v_mfma_f32_32x32x16_bf16 v[48:63], v[104:107], v[108:111], v[48:63]
	s_mov_b32 m0, s84
	v_mfma_f32_32x32x16_bf16 v[32:47], v[104:107], v[112:115], v[32:47]
	ds_read_b128 v[104:107], v79 offset:4096
	s_waitcnt lgkmcnt(0)
	v_mfma_f32_32x32x16_bf16 v[16:31], v[104:107], v[108:111], v[16:31]
	v_mfma_f32_32x32x16_bf16 v[0:15], v[104:107], v[112:115], v[0:15]
	ds_read_b128 v[104:107], v80
	ds_read_b128 v[108:111], v83 offset:16384
	ds_read_b128 v[112:115], v83 offset:20480
	s_waitcnt lgkmcnt(0)
	v_mfma_f32_32x32x16_bf16 v[48:63], v[104:107], v[108:111], v[48:63]
	v_mfma_f32_32x32x16_bf16 v[32:47], v[104:107], v[112:115], v[32:47]
	ds_read_b128 v[104:107], v80 offset:4096
	s_waitcnt lgkmcnt(0)
	v_mfma_f32_32x32x16_bf16 v[16:31], v[104:107], v[108:111], v[16:31]
	v_mfma_f32_32x32x16_bf16 v[0:15], v[104:107], v[112:115], v[0:15]
	ds_read_b128 v[104:107], v82
	ds_read_b128 v[108:111], v85 offset:16384
	ds_read_b128 v[112:115], v85 offset:20480
	s_waitcnt lgkmcnt(0)
	v_mfma_f32_32x32x16_bf16 v[48:63], v[104:107], v[108:111], v[48:63]
	v_mfma_f32_32x32x16_bf16 v[32:47], v[104:107], v[112:115], v[32:47]
	ds_read_b128 v[104:107], v82 offset:4096
	s_waitcnt lgkmcnt(0)
	v_mfma_f32_32x32x16_bf16 v[16:31], v[104:107], v[108:111], v[16:31]
	v_mfma_f32_32x32x16_bf16 v[0:15], v[104:107], v[112:115], v[0:15]
	ds_read_b128 v[104:107], v86
	ds_read_b128 v[108:111], v87 offset:16384
	ds_read_b128 v[112:115], v87 offset:20480
	s_waitcnt lgkmcnt(0)
	v_mfma_f32_32x32x16_bf16 v[48:63], v[104:107], v[108:111], v[48:63]
	v_mfma_f32_32x32x16_bf16 v[32:47], v[104:107], v[112:115], v[32:47]
	ds_read_b128 v[104:107], v86 offset:4096
	s_waitcnt vmcnt(0)
	s_waitcnt vmcnt(0) lgkmcnt(0)
	s_barrier
	v_mfma_f32_32x32x16_bf16 v[16:31], v[104:107], v[108:111], v[16:31]
	v_mfma_f32_32x32x16_bf16 v[0:15], v[104:107], v[112:115], v[0:15]
	v_lshl_add_u64 v[104:105], v[64:65], 0, s[4:5]
	global_load_lds_dwordx4 v[104:105], off
	s_mov_b32 m0, s85
	v_lshl_add_u64 v[104:105], v[66:67], 0, s[4:5]
	global_load_lds_dwordx4 v76, s[48:49]
	s_mov_b32 m0, s86
	s_nop 0
	global_load_lds_dwordx4 v[104:105], off
	s_mov_b32 m0, s87
	v_lshl_add_u64 v[104:105], v[68:69], 0, s[4:5]
	global_load_lds_dwordx4 v77, s[48:49]
	s_mov_b32 m0, s88
	s_nop 0
	global_load_lds_dwordx4 v[104:105], off
	s_mov_b32 m0, s89
	v_lshl_add_u64 v[104:105], v[70:71], 0, s[4:5]
	global_load_lds_dwordx4 v78, s[48:49]
	s_mov_b32 m0, s90
	s_mov_b64 s[4:5], 0x380
	global_load_lds_dwordx4 v[104:105], off
	s_mov_b32 m0, s91
	s_nop 0
	global_load_lds_dwordx4 v84, s[48:49]
	ds_read_b128 v[104:107], v79 offset:32768
	ds_read_b128 v[108:111], v81 offset:49152
	ds_read_b128 v[112:115], v81 offset:53248
	s_waitcnt lgkmcnt(0)
	v_mfma_f32_32x32x16_bf16 v[48:63], v[104:107], v[108:111], v[48:63]
	s_mov_b32 m0, s18
	v_mfma_f32_32x32x16_bf16 v[32:47], v[104:107], v[112:115], v[32:47]
	ds_read_b128 v[104:107], v79 offset:36864
	s_waitcnt lgkmcnt(0)
	v_mfma_f32_32x32x16_bf16 v[16:31], v[104:107], v[108:111], v[16:31]
	v_mfma_f32_32x32x16_bf16 v[0:15], v[104:107], v[112:115], v[0:15]
	ds_read_b128 v[104:107], v80 offset:32768
	ds_read_b128 v[108:111], v83 offset:49152
	ds_read_b128 v[112:115], v83 offset:53248
	s_waitcnt lgkmcnt(0)
	v_mfma_f32_32x32x16_bf16 v[48:63], v[104:107], v[108:111], v[48:63]
	v_mfma_f32_32x32x16_bf16 v[32:47], v[104:107], v[112:115], v[32:47]
	ds_read_b128 v[104:107], v80 offset:36864
	s_waitcnt lgkmcnt(0)
	v_mfma_f32_32x32x16_bf16 v[16:31], v[104:107], v[108:111], v[16:31]
	v_mfma_f32_32x32x16_bf16 v[0:15], v[104:107], v[112:115], v[0:15]
	ds_read_b128 v[104:107], v82 offset:32768
	ds_read_b128 v[108:111], v85 offset:49152
	ds_read_b128 v[112:115], v85 offset:53248
	s_waitcnt lgkmcnt(0)
	v_mfma_f32_32x32x16_bf16 v[48:63], v[104:107], v[108:111], v[48:63]
	v_mfma_f32_32x32x16_bf16 v[32:47], v[104:107], v[112:115], v[32:47]
	ds_read_b128 v[104:107], v82 offset:36864
	s_waitcnt lgkmcnt(0)
	v_mfma_f32_32x32x16_bf16 v[16:31], v[104:107], v[108:111], v[16:31]
	v_mfma_f32_32x32x16_bf16 v[0:15], v[104:107], v[112:115], v[0:15]
	ds_read_b128 v[104:107], v86 offset:32768
	ds_read_b128 v[108:111], v87 offset:49152
	ds_read_b128 v[112:115], v87 offset:53248
	s_waitcnt lgkmcnt(0)
	v_mfma_f32_32x32x16_bf16 v[48:63], v[104:107], v[108:111], v[48:63]
	v_mfma_f32_32x32x16_bf16 v[32:47], v[104:107], v[112:115], v[32:47]
	ds_read_b128 v[104:107], v86 offset:36864
	s_waitcnt vmcnt(0)
	s_waitcnt vmcnt(0) lgkmcnt(0)
	s_barrier
; #define WAIT_V0() asm volatile("s_waitcnt vmcnt(0)" ::: "memory")
; DI void gemm_core(char* smem, int nk, const char* Ab, const char* Bb, const unsigned (&aoff)[4], const unsigned (&boff)[4],
;                   f32x16 (&acc)[2][2]) {
;     ...
;   for (int kt = 0; kt < nk; ++kt) {
;     const int cur = kt & 1;
;     if (kt + 1 < nk) stage(cur ^ 1, kt + 1);
;     const char* sb = smem + cur * STAGE_B;
; #pragma unroll
;     for (int ks = 0; ks < 4; ++ks) {
;       bf16x8 af[2], bfr[2];
; #pragma unroll
;       for (int mb = 0; mb < 2; ++mb) af[mb] = *(const bf16x8*)(sb + a_base + mb * 4096 + xo[ks]);
; #pragma unroll
;       for (int nb = 0; nb < 2; ++nb) bfr[nb] = *(const bf16x8*)(sb + b_base + nb * 4096 + xo[ks]);
; #pragma unroll
;       for (int mb = 0; mb < 2; ++mb)
; #pragma unroll
;         for (int nb = 0; nb < 2; ++nb)
;           acc[mb][nb] = __builtin_amdgcn_mfma_f32_32x32x16_bf16(af[mb], bfr[nb], acc[mb][nb], 0, 0, 0);
;     }
;     WAIT_V0();
;     __syncthreads();
;   }
	v_mfma_f32_32x32x16_bf16 v[16:31], v[104:107], v[108:111], v[16:31]
	v_mfma_f32_32x32x16_bf16 v[0:15], v[104:107], v[112:115], v[0:15]
	v_lshl_add_u64 v[104:105], v[64:65], 0, s[4:5]
	global_load_lds_dwordx4 v[104:105], off
	s_mov_b32 m0, s19
	v_lshl_add_u64 v[104:105], v[66:67], 0, s[4:5]
	global_load_lds_dwordx4 v76, s[50:51]
	s_mov_b32 m0, s22
	s_nop 0
	global_load_lds_dwordx4 v[104:105], off
	s_mov_b32 m0, s23
	v_lshl_add_u64 v[104:105], v[68:69], 0, s[4:5]
	global_load_lds_dwordx4 v77, s[50:51]
	s_mov_b32 m0, s29
	s_nop 0
	global_load_lds_dwordx4 v[104:105], off
	s_mov_b32 m0, s69
	v_lshl_add_u64 v[104:105], v[70:71], 0, s[4:5]
	global_load_lds_dwordx4 v78, s[50:51]
	s_mov_b32 m0, s70
	s_mov_b64 s[4:5], 0x400
	global_load_lds_dwordx4 v[104:105], off
	s_mov_b32 m0, s71
	s_nop 0
	global_load_lds_dwordx4 v84, s[50:51]
	ds_read_b128 v[104:107], v79
	ds_read_b128 v[108:111], v81 offset:16384
	ds_read_b128 v[112:115], v81 offset:20480
	s_waitcnt lgkmcnt(0)
	v_mfma_f32_32x32x16_bf16 v[48:63], v[104:107], v[108:111], v[48:63]
	s_mov_b32 m0, s84
	v_readfirstlane_b32 s84, v89
	v_mfma_f32_32x32x16_bf16 v[32:47], v[104:107], v[112:115], v[32:47]
	ds_read_b128 v[104:107], v79 offset:4096
	s_waitcnt lgkmcnt(0)
	v_mfma_f32_32x32x16_bf16 v[16:31], v[104:107], v[108:111], v[16:31]
	v_mfma_f32_32x32x16_bf16 v[0:15], v[104:107], v[112:115], v[0:15]
	ds_read_b128 v[104:107], v80
	ds_read_b128 v[108:111], v83 offset:16384
	ds_read_b128 v[112:115], v83 offset:20480
	s_waitcnt lgkmcnt(0)
	v_mfma_f32_32x32x16_bf16 v[48:63], v[104:107], v[108:111], v[48:63]
	v_mfma_f32_32x32x16_bf16 v[32:47], v[104:107], v[112:115], v[32:47]
	ds_read_b128 v[104:107], v80 offset:4096
	s_waitcnt lgkmcnt(0)
	v_mfma_f32_32x32x16_bf16 v[16:31], v[104:107], v[108:111], v[16:31]
	v_mfma_f32_32x32x16_bf16 v[0:15], v[104:107], v[112:115], v[0:15]
	ds_read_b128 v[104:107], v82
	ds_read_b128 v[108:111], v85 offset:16384
	ds_read_b128 v[112:115], v85 offset:20480
	s_waitcnt lgkmcnt(0)
	v_mfma_f32_32x32x16_bf16 v[48:63], v[104:107], v[108:111], v[48:63]
	v_mfma_f32_32x32x16_bf16 v[32:47], v[104:107], v[112:115], v[32:47]
	ds_read_b128 v[104:107], v82 offset:4096
	s_waitcnt lgkmcnt(0)
	v_mfma_f32_32x32x16_bf16 v[16:31], v[104:107], v[108:111], v[16:31]
	v_mfma_f32_32x32x16_bf16 v[0:15], v[104:107], v[112:115], v[0:15]
	ds_read_b128 v[104:107], v86
	ds_read_b128 v[108:111], v87 offset:16384
	ds_read_b128 v[112:115], v87 offset:20480
	s_waitcnt lgkmcnt(0)
	v_mfma_f32_32x32x16_bf16 v[48:63], v[104:107], v[108:111], v[48:63]
	v_mfma_f32_32x32x16_bf16 v[32:47], v[104:107], v[112:115], v[32:47]
	ds_read_b128 v[104:107], v86 offset:4096
	s_waitcnt vmcnt(0)
	s_waitcnt vmcnt(0) lgkmcnt(0)
	s_barrier
	v_mfma_f32_32x32x16_bf16 v[16:31], v[104:107], v[108:111], v[16:31]
	v_mfma_f32_32x32x16_bf16 v[0:15], v[104:107], v[112:115], v[0:15]
	v_lshl_add_u64 v[104:105], v[64:65], 0, s[4:5]
	global_load_lds_dwordx4 v[104:105], off
	s_mov_b32 m0, s85
	v_lshl_add_u64 v[104:105], v[66:67], 0, s[4:5]
	global_load_lds_dwordx4 v76, s[52:53]
	s_mov_b32 m0, s86
	v_readfirstlane_b32 s85, v88
	global_load_lds_dwordx4 v[104:105], off
	s_mov_b32 m0, s87
	v_lshl_add_u64 v[104:105], v[68:69], 0, s[4:5]
	global_load_lds_dwordx4 v77, s[52:53]
	s_mov_b32 m0, s88
	v_readfirstlane_b32 s86, v90
	global_load_lds_dwordx4 v[104:105], off
	s_mov_b32 m0, s89
	v_lshl_add_u64 v[104:105], v[70:71], 0, s[4:5]
	global_load_lds_dwordx4 v78, s[52:53]
	s_mov_b32 m0, s90
	s_mov_b64 s[4:5], 0x480
	global_load_lds_dwordx4 v[104:105], off
	s_mov_b32 m0, s91
	v_readfirstlane_b32 s87, v91
	global_load_lds_dwordx4 v84, s[52:53]
	ds_read_b128 v[104:107], v79 offset:32768
	ds_read_b128 v[108:111], v81 offset:49152
	ds_read_b128 v[112:115], v81 offset:53248
	s_waitcnt lgkmcnt(0)
	v_mfma_f32_32x32x16_bf16 v[48:63], v[104:107], v[108:111], v[48:63]
	s_mov_b32 m0, s18
	v_readfirstlane_b32 s18, v97
	v_readfirstlane_b32 s88, v92
	v_readfirstlane_b32 s89, v93
	v_readfirstlane_b32 s90, v94
	v_readfirstlane_b32 s91, v95
	v_mfma_f32_32x32x16_bf16 v[32:47], v[104:107], v[112:115], v[32:47]
	ds_read_b128 v[104:107], v79 offset:36864
	s_waitcnt lgkmcnt(0)
	v_mfma_f32_32x32x16_bf16 v[16:31], v[104:107], v[108:111], v[16:31]
	v_mfma_f32_32x32x16_bf16 v[0:15], v[104:107], v[112:115], v[0:15]
	ds_read_b128 v[104:107], v80 offset:32768
	ds_read_b128 v[108:111], v83 offset:49152
	ds_read_b128 v[112:115], v83 offset:53248
	s_waitcnt lgkmcnt(0)
	v_mfma_f32_32x32x16_bf16 v[48:63], v[104:107], v[108:111], v[48:63]
	v_mfma_f32_32x32x16_bf16 v[32:47], v[104:107], v[112:115], v[32:47]
	ds_read_b128 v[104:107], v80 offset:36864
	s_waitcnt lgkmcnt(0)
	v_mfma_f32_32x32x16_bf16 v[16:31], v[104:107], v[108:111], v[16:31]
	v_mfma_f32_32x32x16_bf16 v[0:15], v[104:107], v[112:115], v[0:15]
	ds_read_b128 v[104:107], v82 offset:32768
	ds_read_b128 v[108:111], v85 offset:49152
	ds_read_b128 v[112:115], v85 offset:53248
	s_waitcnt lgkmcnt(0)
	v_mfma_f32_32x32x16_bf16 v[48:63], v[104:107], v[108:111], v[48:63]
	v_mfma_f32_32x32x16_bf16 v[32:47], v[104:107], v[112:115], v[32:47]
	ds_read_b128 v[104:107], v82 offset:36864
	s_waitcnt lgkmcnt(0)
	v_mfma_f32_32x32x16_bf16 v[16:31], v[104:107], v[108:111], v[16:31]
	v_mfma_f32_32x32x16_bf16 v[0:15], v[104:107], v[112:115], v[0:15]
	ds_read_b128 v[104:107], v86 offset:32768
	ds_read_b128 v[108:111], v87 offset:49152
	ds_read_b128 v[112:115], v87 offset:53248
	s_waitcnt lgkmcnt(0)
	v_mfma_f32_32x32x16_bf16 v[48:63], v[104:107], v[108:111], v[48:63]
	v_mfma_f32_32x32x16_bf16 v[32:47], v[104:107], v[112:115], v[32:47]
	ds_read_b128 v[104:107], v86 offset:36864
	s_waitcnt vmcnt(0)
	s_waitcnt vmcnt(0) lgkmcnt(0)
	s_barrier
; #define WAIT_V0() asm volatile("s_waitcnt vmcnt(0)" ::: "memory")
; DI void gemm_core(char* smem, int nk, const char* Ab, const char* Bb, const unsigned (&aoff)[4], const unsigned (&boff)[4],
;                   f32x16 (&acc)[2][2]) {
;     ...
;   for (int kt = 0; kt < nk; ++kt) {
;     const int cur = kt & 1;
;     if (kt + 1 < nk) stage(cur ^ 1, kt + 1);
;     const char* sb = smem + cur * STAGE_B;
; #pragma unroll
;     for (int ks = 0; ks < 4; ++ks) {
;       bf16x8 af[2], bfr[2];
; #pragma unroll
;       for (int mb = 0; mb < 2; ++mb) af[mb] = *(const bf16x8*)(sb + a_base + mb * 4096 + xo[ks]);
; #pragma unroll
;       for (int nb = 0; nb < 2; ++nb) bfr[nb] = *(const bf16x8*)(sb + b_base + nb * 4096 + xo[ks]);
; #pragma unroll
;       for (int mb = 0; mb < 2; ++mb)
; #pragma unroll
;         for (int nb = 0; nb < 2; ++nb)
;           acc[mb][nb] = __builtin_amdgcn_mfma_f32_32x32x16_bf16(af[mb], bfr[nb], acc[mb][nb], 0, 0, 0);
;     }
;     WAIT_V0();
;     __syncthreads();
;   }
	v_mfma_f32_32x32x16_bf16 v[16:31], v[104:107], v[108:111], v[16:31]
	v_mfma_f32_32x32x16_bf16 v[0:15], v[104:107], v[112:115], v[0:15]
	v_lshl_add_u64 v[104:105], v[64:65], 0, s[4:5]
	global_load_lds_dwordx4 v[104:105], off
	s_mov_b32 m0, s19
	v_lshl_add_u64 v[104:105], v[66:67], 0, s[4:5]
	global_load_lds_dwordx4 v76, s[54:55]
	s_mov_b32 m0, s22
	v_readfirstlane_b32 s19, v96
	global_load_lds_dwordx4 v[104:105], off
	s_mov_b32 m0, s23
	v_lshl_add_u64 v[104:105], v[68:69], 0, s[4:5]
	global_load_lds_dwordx4 v77, s[54:55]
	s_mov_b32 m0, s29
	v_readfirstlane_b32 s22, v98
	global_load_lds_dwordx4 v[104:105], off
	s_mov_b32 m0, s69
	v_lshl_add_u64 v[104:105], v[70:71], 0, s[4:5]
	global_load_lds_dwordx4 v78, s[54:55]
	s_mov_b32 m0, s70
	s_mov_b64 s[4:5], 0x500
	global_load_lds_dwordx4 v[104:105], off
	s_mov_b32 m0, s71
	v_lshl_add_u64 v[96:97], v[66:67], 0, s[4:5]
	global_load_lds_dwordx4 v84, s[54:55]
	ds_read_b128 v[104:107], v79
	ds_read_b128 v[108:111], v81 offset:16384
	ds_read_b128 v[112:115], v81 offset:20480
	s_waitcnt lgkmcnt(0)
	v_mfma_f32_32x32x16_bf16 v[48:63], v[104:107], v[108:111], v[48:63]
	s_mov_b32 m0, s18
	v_readfirstlane_b32 s23, v99
	v_readfirstlane_b32 s29, v100
	v_readfirstlane_b32 s69, v101
	v_readfirstlane_b32 s70, v102
	v_readfirstlane_b32 s71, v103
	v_mfma_f32_32x32x16_bf16 v[32:47], v[104:107], v[112:115], v[32:47]
	ds_read_b128 v[104:107], v79 offset:4096
	s_waitcnt lgkmcnt(0)
	v_mfma_f32_32x32x16_bf16 v[16:31], v[104:107], v[108:111], v[16:31]
	v_mfma_f32_32x32x16_bf16 v[0:15], v[104:107], v[112:115], v[0:15]
	ds_read_b128 v[104:107], v80
	ds_read_b128 v[108:111], v83 offset:16384
	ds_read_b128 v[112:115], v83 offset:20480
	s_waitcnt lgkmcnt(0)
	v_mfma_f32_32x32x16_bf16 v[48:63], v[104:107], v[108:111], v[48:63]
	v_mfma_f32_32x32x16_bf16 v[32:47], v[104:107], v[112:115], v[32:47]
	ds_read_b128 v[104:107], v80 offset:4096
	s_waitcnt lgkmcnt(0)
	v_mfma_f32_32x32x16_bf16 v[16:31], v[104:107], v[108:111], v[16:31]
	v_mfma_f32_32x32x16_bf16 v[0:15], v[104:107], v[112:115], v[0:15]
	ds_read_b128 v[104:107], v82
	ds_read_b128 v[108:111], v85 offset:16384
	ds_read_b128 v[112:115], v85 offset:20480
	s_waitcnt lgkmcnt(0)
	v_mfma_f32_32x32x16_bf16 v[48:63], v[104:107], v[108:111], v[48:63]
	v_mfma_f32_32x32x16_bf16 v[32:47], v[104:107], v[112:115], v[32:47]
	ds_read_b128 v[104:107], v82 offset:4096
	s_waitcnt lgkmcnt(0)
	v_mfma_f32_32x32x16_bf16 v[16:31], v[104:107], v[108:111], v[16:31]
	v_mfma_f32_32x32x16_bf16 v[0:15], v[104:107], v[112:115], v[0:15]
	ds_read_b128 v[104:107], v86
	ds_read_b128 v[108:111], v87 offset:16384
	ds_read_b128 v[112:115], v87 offset:20480
	s_waitcnt lgkmcnt(0)
	v_mfma_f32_32x32x16_bf16 v[48:63], v[104:107], v[108:111], v[48:63]
	v_mfma_f32_32x32x16_bf16 v[32:47], v[104:107], v[112:115], v[32:47]
	ds_read_b128 v[104:107], v86 offset:4096
	s_waitcnt vmcnt(0)
	s_waitcnt vmcnt(0) lgkmcnt(0)
	s_barrier
	v_mfma_f32_32x32x16_bf16 v[16:31], v[104:107], v[108:111], v[16:31]
	v_mfma_f32_32x32x16_bf16 v[0:15], v[104:107], v[112:115], v[0:15]
	v_lshl_add_u64 v[104:105], v[64:65], 0, s[4:5]
	global_load_lds_dwordx4 v[104:105], off
	s_mov_b32 m0, s19
	s_nop 0
	global_load_lds_dwordx4 v76, s[56:57]
	s_mov_b32 m0, s22
	s_nop 0
	global_load_lds_dwordx4 v[96:97], off
	s_mov_b32 m0, s23
	v_lshl_add_u64 v[96:97], v[68:69], 0, s[4:5]
	global_load_lds_dwordx4 v77, s[56:57]
	s_mov_b32 m0, s29
	s_nop 0
	global_load_lds_dwordx4 v[96:97], off
	s_mov_b32 m0, s69
	v_lshl_add_u64 v[96:97], v[70:71], 0, s[4:5]
	global_load_lds_dwordx4 v78, s[56:57]
	s_mov_b32 m0, s70
	s_mov_b64 s[4:5], 0x580
	global_load_lds_dwordx4 v[96:97], off
	s_mov_b32 m0, s71
	v_lshl_add_u64 v[88:89], v[66:67], 0, s[4:5]
	global_load_lds_dwordx4 v84, s[56:57]
	ds_read_b128 v[96:99], v79 offset:32768
	ds_read_b128 v[100:103], v81 offset:49152
	ds_read_b128 v[104:107], v81 offset:53248
	s_waitcnt lgkmcnt(0)
	v_mfma_f32_32x32x16_bf16 v[48:63], v[96:99], v[100:103], v[48:63]
	s_mov_b32 m0, s84
	v_mfma_f32_32x32x16_bf16 v[32:47], v[96:99], v[104:107], v[32:47]
	ds_read_b128 v[96:99], v79 offset:36864
	s_waitcnt lgkmcnt(0)
	v_mfma_f32_32x32x16_bf16 v[16:31], v[96:99], v[100:103], v[16:31]
	v_mfma_f32_32x32x16_bf16 v[0:15], v[96:99], v[104:107], v[0:15]
	ds_read_b128 v[96:99], v80 offset:32768
	ds_read_b128 v[100:103], v83 offset:49152
	ds_read_b128 v[104:107], v83 offset:53248
	s_waitcnt lgkmcnt(0)
	v_mfma_f32_32x32x16_bf16 v[48:63], v[96:99], v[100:103], v[48:63]
	v_mfma_f32_32x32x16_bf16 v[32:47], v[96:99], v[104:107], v[32:47]
	ds_read_b128 v[96:99], v80 offset:36864
	s_waitcnt lgkmcnt(0)
	v_mfma_f32_32x32x16_bf16 v[16:31], v[96:99], v[100:103], v[16:31]
	v_mfma_f32_32x32x16_bf16 v[0:15], v[96:99], v[104:107], v[0:15]
	ds_read_b128 v[96:99], v82 offset:32768
	ds_read_b128 v[100:103], v85 offset:49152
	ds_read_b128 v[104:107], v85 offset:53248
	s_waitcnt lgkmcnt(0)
	v_mfma_f32_32x32x16_bf16 v[48:63], v[96:99], v[100:103], v[48:63]
	v_mfma_f32_32x32x16_bf16 v[32:47], v[96:99], v[104:107], v[32:47]
	ds_read_b128 v[96:99], v82 offset:36864
	s_waitcnt lgkmcnt(0)
	v_mfma_f32_32x32x16_bf16 v[16:31], v[96:99], v[100:103], v[16:31]
	v_mfma_f32_32x32x16_bf16 v[0:15], v[96:99], v[104:107], v[0:15]
	ds_read_b128 v[96:99], v86 offset:32768
	ds_read_b128 v[100:103], v87 offset:49152
	ds_read_b128 v[104:107], v87 offset:53248
	s_waitcnt lgkmcnt(0)
	v_mfma_f32_32x32x16_bf16 v[48:63], v[96:99], v[100:103], v[48:63]
	v_mfma_f32_32x32x16_bf16 v[32:47], v[96:99], v[104:107], v[32:47]
	ds_read_b128 v[96:99], v86 offset:36864
	s_waitcnt vmcnt(0)
	s_waitcnt vmcnt(0) lgkmcnt(0)
	s_barrier
; #define WAIT_V0() asm volatile("s_waitcnt vmcnt(0)" ::: "memory")
; DI void gemm_core(char* smem, int nk, const char* Ab, const char* Bb, const unsigned (&aoff)[4], const unsigned (&boff)[4],
;                   f32x16 (&acc)[2][2]) {
;     ...
;   for (int kt = 0; kt < nk; ++kt) {
;     const int cur = kt & 1;
;     if (kt + 1 < nk) stage(cur ^ 1, kt + 1);
;     const char* sb = smem + cur * STAGE_B;
; #pragma unroll
;     for (int ks = 0; ks < 4; ++ks) {
;       bf16x8 af[2], bfr[2];
; #pragma unroll
;       for (int mb = 0; mb < 2; ++mb) af[mb] = *(const bf16x8*)(sb + a_base + mb * 4096 + xo[ks]);
; #pragma unroll
;       for (int nb = 0; nb < 2; ++nb) bfr[nb] = *(const bf16x8*)(sb + b_base + nb * 4096 + xo[ks]);
; #pragma unroll
;       for (int mb = 0; mb < 2; ++mb)
; #pragma unroll
;         for (int nb = 0; nb < 2; ++nb)
;           acc[mb][nb] = __builtin_amdgcn_mfma_f32_32x32x16_bf16(af[mb], bfr[nb], acc[mb][nb], 0, 0, 0);
;     }
;     WAIT_V0();
;     __syncthreads();
;   }
	v_mfma_f32_32x32x16_bf16 v[16:31], v[96:99], v[100:103], v[16:31]
	v_mfma_f32_32x32x16_bf16 v[0:15], v[96:99], v[104:107], v[0:15]
	v_lshl_add_u64 v[96:97], v[64:65], 0, s[4:5]
	global_load_lds_dwordx4 v[96:97], off
	s_mov_b32 m0, s85
	s_nop 0
	global_load_lds_dwordx4 v76, s[58:59]
	s_mov_b32 m0, s86
	s_nop 0
	global_load_lds_dwordx4 v[88:89], off
	s_mov_b32 m0, s87
	v_lshl_add_u64 v[88:89], v[68:69], 0, s[4:5]
	global_load_lds_dwordx4 v77, s[58:59]
	s_mov_b32 m0, s88
	s_nop 0
	global_load_lds_dwordx4 v[88:89], off
	s_mov_b32 m0, s89
	v_lshl_add_u64 v[88:89], v[70:71], 0, s[4:5]
	global_load_lds_dwordx4 v78, s[58:59]
	s_mov_b32 m0, s90
	s_mov_b64 s[4:5], 0x600
	global_load_lds_dwordx4 v[88:89], off
	s_mov_b32 m0, s91
	s_nop 0
	global_load_lds_dwordx4 v84, s[58:59]
	ds_read_b128 v[88:91], v79
	ds_read_b128 v[92:95], v81 offset:16384
	ds_read_b128 v[96:99], v81 offset:20480
	s_waitcnt lgkmcnt(0)
	v_mfma_f32_32x32x16_bf16 v[48:63], v[88:91], v[92:95], v[48:63]
	s_mov_b32 m0, s18
	v_mfma_f32_32x32x16_bf16 v[32:47], v[88:91], v[96:99], v[32:47]
	ds_read_b128 v[88:91], v79 offset:4096
	s_waitcnt lgkmcnt(0)
	v_mfma_f32_32x32x16_bf16 v[16:31], v[88:91], v[92:95], v[16:31]
	v_mfma_f32_32x32x16_bf16 v[0:15], v[88:91], v[96:99], v[0:15]
	ds_read_b128 v[88:91], v80
	ds_read_b128 v[92:95], v83 offset:16384
	ds_read_b128 v[96:99], v83 offset:20480
	s_waitcnt lgkmcnt(0)
	v_mfma_f32_32x32x16_bf16 v[48:63], v[88:91], v[92:95], v[48:63]
	v_mfma_f32_32x32x16_bf16 v[32:47], v[88:91], v[96:99], v[32:47]
	ds_read_b128 v[88:91], v80 offset:4096
	s_waitcnt lgkmcnt(0)
	v_mfma_f32_32x32x16_bf16 v[16:31], v[88:91], v[92:95], v[16:31]
	v_mfma_f32_32x32x16_bf16 v[0:15], v[88:91], v[96:99], v[0:15]
	ds_read_b128 v[88:91], v82
	ds_read_b128 v[92:95], v85 offset:16384
	ds_read_b128 v[96:99], v85 offset:20480
	s_waitcnt lgkmcnt(0)
	v_mfma_f32_32x32x16_bf16 v[48:63], v[88:91], v[92:95], v[48:63]
	v_mfma_f32_32x32x16_bf16 v[32:47], v[88:91], v[96:99], v[32:47]
	ds_read_b128 v[88:91], v82 offset:4096
	s_waitcnt lgkmcnt(0)
	v_mfma_f32_32x32x16_bf16 v[16:31], v[88:91], v[92:95], v[16:31]
	v_mfma_f32_32x32x16_bf16 v[0:15], v[88:91], v[96:99], v[0:15]
	ds_read_b128 v[88:91], v86
	ds_read_b128 v[92:95], v87 offset:16384
	ds_read_b128 v[96:99], v87 offset:20480
	s_waitcnt lgkmcnt(0)
	v_mfma_f32_32x32x16_bf16 v[48:63], v[88:91], v[92:95], v[48:63]
	v_mfma_f32_32x32x16_bf16 v[32:47], v[88:91], v[96:99], v[32:47]
	ds_read_b128 v[88:91], v86 offset:4096
	s_waitcnt vmcnt(0)
	s_waitcnt vmcnt(0) lgkmcnt(0)
	s_barrier
	v_mfma_f32_32x32x16_bf16 v[16:31], v[88:91], v[92:95], v[16:31]
	v_mfma_f32_32x32x16_bf16 v[0:15], v[88:91], v[96:99], v[0:15]
	v_lshl_add_u64 v[88:89], v[64:65], 0, s[4:5]
	global_load_lds_dwordx4 v[88:89], off
	s_mov_b32 m0, s19
	v_lshl_add_u64 v[88:89], v[66:67], 0, s[4:5]
	global_load_lds_dwordx4 v76, s[60:61]
	s_mov_b32 m0, s22
	s_nop 0
	global_load_lds_dwordx4 v[88:89], off
	s_mov_b32 m0, s23
	v_lshl_add_u64 v[88:89], v[68:69], 0, s[4:5]
	global_load_lds_dwordx4 v77, s[60:61]
	s_mov_b32 m0, s29
	s_nop 0
	global_load_lds_dwordx4 v[88:89], off
	s_mov_b32 m0, s69
	v_lshl_add_u64 v[88:89], v[70:71], 0, s[4:5]
	global_load_lds_dwordx4 v78, s[60:61]
	s_mov_b32 m0, s70
	s_mov_b64 s[4:5], 0x680
	global_load_lds_dwordx4 v[88:89], off
	s_mov_b32 m0, s71
	s_nop 0
	global_load_lds_dwordx4 v84, s[60:61]
	ds_read_b128 v[88:91], v79 offset:32768
	ds_read_b128 v[92:95], v81 offset:49152
	ds_read_b128 v[96:99], v81 offset:53248
	s_waitcnt lgkmcnt(0)
	v_mfma_f32_32x32x16_bf16 v[48:63], v[88:91], v[92:95], v[48:63]
	s_mov_b32 m0, s84
	v_mfma_f32_32x32x16_bf16 v[32:47], v[88:91], v[96:99], v[32:47]
	ds_read_b128 v[88:91], v79 offset:36864
	s_waitcnt lgkmcnt(0)
	v_mfma_f32_32x32x16_bf16 v[16:31], v[88:91], v[92:95], v[16:31]
	v_mfma_f32_32x32x16_bf16 v[0:15], v[88:91], v[96:99], v[0:15]
	ds_read_b128 v[88:91], v80 offset:32768
	ds_read_b128 v[92:95], v83 offset:49152
	ds_read_b128 v[96:99], v83 offset:53248
	s_waitcnt lgkmcnt(0)
	v_mfma_f32_32x32x16_bf16 v[48:63], v[88:91], v[92:95], v[48:63]
	v_mfma_f32_32x32x16_bf16 v[32:47], v[88:91], v[96:99], v[32:47]
	ds_read_b128 v[88:91], v80 offset:36864
	s_waitcnt lgkmcnt(0)
	v_mfma_f32_32x32x16_bf16 v[16:31], v[88:91], v[92:95], v[16:31]
	v_mfma_f32_32x32x16_bf16 v[0:15], v[88:91], v[96:99], v[0:15]
	ds_read_b128 v[88:91], v82 offset:32768
	ds_read_b128 v[92:95], v85 offset:49152
	ds_read_b128 v[96:99], v85 offset:53248
	s_waitcnt lgkmcnt(0)
	v_mfma_f32_32x32x16_bf16 v[48:63], v[88:91], v[92:95], v[48:63]
	v_mfma_f32_32x32x16_bf16 v[32:47], v[88:91], v[96:99], v[32:47]
	ds_read_b128 v[88:91], v82 offset:36864
	s_waitcnt lgkmcnt(0)
	v_mfma_f32_32x32x16_bf16 v[16:31], v[88:91], v[92:95], v[16:31]
	v_mfma_f32_32x32x16_bf16 v[0:15], v[88:91], v[96:99], v[0:15]
	ds_read_b128 v[88:91], v86 offset:32768
	ds_read_b128 v[92:95], v87 offset:49152
	ds_read_b128 v[96:99], v87 offset:53248
	s_waitcnt lgkmcnt(0)
	v_mfma_f32_32x32x16_bf16 v[48:63], v[88:91], v[92:95], v[48:63]
	v_mfma_f32_32x32x16_bf16 v[32:47], v[88:91], v[96:99], v[32:47]
	ds_read_b128 v[88:91], v86 offset:36864
	s_waitcnt vmcnt(0)
	s_waitcnt vmcnt(0) lgkmcnt(0)
	s_barrier
; #define WAIT_V0() asm volatile("s_waitcnt vmcnt(0)" ::: "memory")
; DI void gemm_core(char* smem, int nk, const char* Ab, const char* Bb, const unsigned (&aoff)[4], const unsigned (&boff)[4],
;                   f32x16 (&acc)[2][2]) {
;     ...
;   for (int kt = 0; kt < nk; ++kt) {
;     const int cur = kt & 1;
;     if (kt + 1 < nk) stage(cur ^ 1, kt + 1);
;     const char* sb = smem + cur * STAGE_B;
; #pragma unroll
;     for (int ks = 0; ks < 4; ++ks) {
;       bf16x8 af[2], bfr[2];
; #pragma unroll
;       for (int mb = 0; mb < 2; ++mb) af[mb] = *(const bf16x8*)(sb + a_base + mb * 4096 + xo[ks]);
; #pragma unroll
;       for (int nb = 0; nb < 2; ++nb) bfr[nb] = *(const bf16x8*)(sb + b_base + nb * 4096 + xo[ks]);
; #pragma unroll
;       for (int mb = 0; mb < 2; ++mb)
; #pragma unroll
;         for (int nb = 0; nb < 2; ++nb)
;           acc[mb][nb] = __builtin_amdgcn_mfma_f32_32x32x16_bf16(af[mb], bfr[nb], acc[mb][nb], 0, 0, 0);
;     }
;     WAIT_V0();
;     __syncthreads();
;   }
	v_mfma_f32_32x32x16_bf16 v[16:31], v[88:91], v[92:95], v[16:31]
	v_mfma_f32_32x32x16_bf16 v[0:15], v[88:91], v[96:99], v[0:15]
	v_lshl_add_u64 v[88:89], v[64:65], 0, s[4:5]
	global_load_lds_dwordx4 v[88:89], off
	s_mov_b32 m0, s85
	v_lshl_add_u64 v[88:89], v[66:67], 0, s[4:5]
	global_load_lds_dwordx4 v76, s[62:63]
	s_mov_b32 m0, s86
	s_nop 0
	global_load_lds_dwordx4 v[88:89], off
	s_mov_b32 m0, s87
	v_lshl_add_u64 v[88:89], v[68:69], 0, s[4:5]
	global_load_lds_dwordx4 v77, s[62:63]
	s_mov_b32 m0, s88
	s_nop 0
	global_load_lds_dwordx4 v[88:89], off
	s_mov_b32 m0, s89
	v_lshl_add_u64 v[88:89], v[70:71], 0, s[4:5]
	global_load_lds_dwordx4 v78, s[62:63]
	s_mov_b32 m0, s90
	s_mov_b64 s[4:5], 0x700
	global_load_lds_dwordx4 v[88:89], off
	s_mov_b32 m0, s91
	s_nop 0
	global_load_lds_dwordx4 v84, s[62:63]
	ds_read_b128 v[88:91], v79
	ds_read_b128 v[92:95], v81 offset:16384
	ds_read_b128 v[96:99], v81 offset:20480
	s_waitcnt lgkmcnt(0)
	v_mfma_f32_32x32x16_bf16 v[48:63], v[88:91], v[92:95], v[48:63]
	s_mov_b32 m0, s18
	v_mfma_f32_32x32x16_bf16 v[32:47], v[88:91], v[96:99], v[32:47]
	ds_read_b128 v[88:91], v79 offset:4096
	s_waitcnt lgkmcnt(0)
	v_mfma_f32_32x32x16_bf16 v[16:31], v[88:91], v[92:95], v[16:31]
	v_mfma_f32_32x32x16_bf16 v[0:15], v[88:91], v[96:99], v[0:15]
	ds_read_b128 v[88:91], v80
	ds_read_b128 v[92:95], v83 offset:16384
	ds_read_b128 v[96:99], v83 offset:20480
	s_waitcnt lgkmcnt(0)
	v_mfma_f32_32x32x16_bf16 v[48:63], v[88:91], v[92:95], v[48:63]
	v_mfma_f32_32x32x16_bf16 v[32:47], v[88:91], v[96:99], v[32:47]
	ds_read_b128 v[88:91], v80 offset:4096
	s_waitcnt lgkmcnt(0)
	v_mfma_f32_32x32x16_bf16 v[16:31], v[88:91], v[92:95], v[16:31]
	v_mfma_f32_32x32x16_bf16 v[0:15], v[88:91], v[96:99], v[0:15]
	ds_read_b128 v[88:91], v82
	ds_read_b128 v[92:95], v85 offset:16384
	ds_read_b128 v[96:99], v85 offset:20480
	s_waitcnt lgkmcnt(0)
	v_mfma_f32_32x32x16_bf16 v[48:63], v[88:91], v[92:95], v[48:63]
	v_mfma_f32_32x32x16_bf16 v[32:47], v[88:91], v[96:99], v[32:47]
	ds_read_b128 v[88:91], v82 offset:4096
	s_waitcnt lgkmcnt(0)
	v_mfma_f32_32x32x16_bf16 v[16:31], v[88:91], v[92:95], v[16:31]
	v_mfma_f32_32x32x16_bf16 v[0:15], v[88:91], v[96:99], v[0:15]
	ds_read_b128 v[88:91], v86
	ds_read_b128 v[92:95], v87 offset:16384
	ds_read_b128 v[96:99], v87 offset:20480
	s_waitcnt lgkmcnt(0)
	v_mfma_f32_32x32x16_bf16 v[48:63], v[88:91], v[92:95], v[48:63]
	v_mfma_f32_32x32x16_bf16 v[32:47], v[88:91], v[96:99], v[32:47]
	ds_read_b128 v[88:91], v86 offset:4096
	s_waitcnt vmcnt(0)
	s_waitcnt vmcnt(0) lgkmcnt(0)
	s_barrier
	v_mfma_f32_32x32x16_bf16 v[16:31], v[88:91], v[92:95], v[16:31]
	v_mfma_f32_32x32x16_bf16 v[0:15], v[88:91], v[96:99], v[0:15]
	v_lshl_add_u64 v[88:89], v[64:65], 0, s[4:5]
	global_load_lds_dwordx4 v[88:89], off
	s_mov_b32 m0, s19
	v_lshl_add_u64 v[88:89], v[66:67], 0, s[4:5]
	global_load_lds_dwordx4 v76, s[64:65]
	s_mov_b32 m0, s22
	s_nop 0
	global_load_lds_dwordx4 v[88:89], off
	s_mov_b32 m0, s23
	v_lshl_add_u64 v[88:89], v[68:69], 0, s[4:5]
	global_load_lds_dwordx4 v77, s[64:65]
	s_mov_b32 m0, s29
	s_nop 0
	global_load_lds_dwordx4 v[88:89], off
	s_mov_b32 m0, s69
	v_lshl_add_u64 v[88:89], v[70:71], 0, s[4:5]
	global_load_lds_dwordx4 v78, s[64:65]
	s_mov_b32 m0, s70
	s_mov_b64 s[4:5], 0x780
	global_load_lds_dwordx4 v[88:89], off
	s_mov_b32 m0, s71
	v_lshl_add_u64 v[64:65], v[64:65], 0, s[4:5]
	global_load_lds_dwordx4 v84, s[64:65]
	ds_read_b128 v[88:91], v79 offset:32768
	ds_read_b128 v[92:95], v81 offset:49152
	ds_read_b128 v[96:99], v81 offset:53248
	s_waitcnt lgkmcnt(0)
	v_mfma_f32_32x32x16_bf16 v[48:63], v[88:91], v[92:95], v[48:63]
	s_mov_b32 m0, s84
	s_movk_i32 s4, 0x4000
	v_mfma_f32_32x32x16_bf16 v[32:47], v[88:91], v[96:99], v[32:47]
	ds_read_b128 v[88:91], v79 offset:36864
	s_waitcnt lgkmcnt(0)
	v_mfma_f32_32x32x16_bf16 v[16:31], v[88:91], v[92:95], v[16:31]
	v_mfma_f32_32x32x16_bf16 v[0:15], v[88:91], v[96:99], v[0:15]
	ds_read_b128 v[88:91], v80 offset:32768
	ds_read_b128 v[92:95], v83 offset:49152
	ds_read_b128 v[96:99], v83 offset:53248
	s_waitcnt lgkmcnt(0)
	v_mfma_f32_32x32x16_bf16 v[48:63], v[88:91], v[92:95], v[48:63]
	v_mfma_f32_32x32x16_bf16 v[32:47], v[88:91], v[96:99], v[32:47]
	ds_read_b128 v[88:91], v80 offset:36864
	s_waitcnt lgkmcnt(0)
	v_mfma_f32_32x32x16_bf16 v[16:31], v[88:91], v[92:95], v[16:31]
	v_mfma_f32_32x32x16_bf16 v[0:15], v[88:91], v[96:99], v[0:15]
	ds_read_b128 v[88:91], v82 offset:32768
	ds_read_b128 v[92:95], v85 offset:49152
	ds_read_b128 v[96:99], v85 offset:53248
	s_waitcnt lgkmcnt(0)
	v_mfma_f32_32x32x16_bf16 v[48:63], v[88:91], v[92:95], v[48:63]
	v_mfma_f32_32x32x16_bf16 v[32:47], v[88:91], v[96:99], v[32:47]
	ds_read_b128 v[88:91], v82 offset:36864
	s_waitcnt lgkmcnt(0)
	v_mfma_f32_32x32x16_bf16 v[16:31], v[88:91], v[92:95], v[16:31]
	v_mfma_f32_32x32x16_bf16 v[0:15], v[88:91], v[96:99], v[0:15]
	ds_read_b128 v[88:91], v86 offset:32768
	ds_read_b128 v[92:95], v87 offset:49152
	ds_read_b128 v[96:99], v87 offset:53248
	s_waitcnt lgkmcnt(0)
	v_mfma_f32_32x32x16_bf16 v[48:63], v[88:91], v[92:95], v[48:63]
	v_mfma_f32_32x32x16_bf16 v[32:47], v[88:91], v[96:99], v[32:47]
	ds_read_b128 v[88:91], v86 offset:36864
	s_waitcnt vmcnt(0)
	s_waitcnt vmcnt(0) lgkmcnt(0)
	s_barrier
; #define WAIT_V0() asm volatile("s_waitcnt vmcnt(0)" ::: "memory")
; DI void gemm_core(char* smem, int nk, const char* Ab, const char* Bb, const unsigned (&aoff)[4], const unsigned (&boff)[4],
;                   f32x16 (&acc)[2][2]) {
;     ...
;   for (int kt = 0; kt < nk; ++kt) {
;     const int cur = kt & 1;
;     if (kt + 1 < nk) stage(cur ^ 1, kt + 1);
;     const char* sb = smem + cur * STAGE_B;
; #pragma unroll
;     for (int ks = 0; ks < 4; ++ks) {
;       bf16x8 af[2], bfr[2];
; #pragma unroll
;       for (int mb = 0; mb < 2; ++mb) af[mb] = *(const bf16x8*)(sb + a_base + mb * 4096 + xo[ks]);
; #pragma unroll
;       for (int nb = 0; nb < 2; ++nb) bfr[nb] = *(const bf16x8*)(sb + b_base + nb * 4096 + xo[ks]);
; #pragma unroll
;       for (int mb = 0; mb < 2; ++mb)
; #pragma unroll
;         for (int nb = 0; nb < 2; ++nb)
;           acc[mb][nb] = __builtin_amdgcn_mfma_f32_32x32x16_bf16(af[mb], bfr[nb], acc[mb][nb], 0, 0, 0);
;     }
;     WAIT_V0();
;     __syncthreads();
;   }
	global_load_lds_dwordx4 v[64:65], off
	s_mov_b32 m0, s85
	v_lshl_add_u64 v[64:65], v[66:67], 0, s[6:7]
	global_load_lds_dwordx4 v76, s[66:67]
	s_mov_b32 m0, s86
	v_mfma_f32_32x32x16_bf16 v[16:31], v[88:91], v[92:95], v[16:31]
	global_load_lds_dwordx4 v[64:65], off
	s_mov_b32 m0, s87
	v_lshl_add_u64 v[64:65], v[68:69], 0, s[6:7]
	global_load_lds_dwordx4 v77, s[66:67]
	s_mov_b32 m0, s88
	v_mfma_f32_32x32x16_bf16 v[0:15], v[88:91], v[96:99], v[0:15]
	global_load_lds_dwordx4 v[64:65], off
	s_mov_b32 m0, s89
	v_lshl_add_u64 v[64:65], v[70:71], 0, s[6:7]
	global_load_lds_dwordx4 v78, s[66:67]
	s_mov_b32 m0, s90
	v_readlane_b32 s86, v254, 58
	global_load_lds_dwordx4 v[64:65], off
	s_mov_b32 m0, s91
	v_readlane_b32 s87, v254, 59
	global_load_lds_dwordx4 v84, s[66:67]
	ds_read_b128 v[64:67], v79
	ds_read_b128 v[68:71], v81 offset:16384
	ds_read_b128 v[88:91], v81 offset:20480
	s_waitcnt lgkmcnt(0)
	v_mfma_f32_32x32x16_bf16 v[48:63], v[64:67], v[68:71], v[48:63]
	v_mfma_f32_32x32x16_bf16 v[32:47], v[64:67], v[88:91], v[32:47]
	ds_read_b128 v[64:67], v79 offset:4096
	s_waitcnt lgkmcnt(0)
	v_mfma_f32_32x32x16_bf16 v[16:31], v[64:67], v[68:71], v[16:31]
	v_mfma_f32_32x32x16_bf16 v[0:15], v[64:67], v[88:91], v[0:15]
	ds_read_b128 v[64:67], v80
	ds_read_b128 v[68:71], v83 offset:16384
	ds_read_b128 v[88:91], v83 offset:20480
	s_waitcnt lgkmcnt(0)
	v_mfma_f32_32x32x16_bf16 v[48:63], v[64:67], v[68:71], v[48:63]
	v_mfma_f32_32x32x16_bf16 v[32:47], v[64:67], v[88:91], v[32:47]
	ds_read_b128 v[64:67], v80 offset:4096
	s_waitcnt lgkmcnt(0)
	v_mfma_f32_32x32x16_bf16 v[16:31], v[64:67], v[68:71], v[16:31]
	v_mfma_f32_32x32x16_bf16 v[0:15], v[64:67], v[88:91], v[0:15]
	ds_read_b128 v[64:67], v82
	ds_read_b128 v[68:71], v85 offset:16384
	ds_read_b128 v[88:91], v85 offset:20480
	s_waitcnt lgkmcnt(0)
	v_mfma_f32_32x32x16_bf16 v[48:63], v[64:67], v[68:71], v[48:63]
	v_mfma_f32_32x32x16_bf16 v[32:47], v[64:67], v[88:91], v[32:47]
	ds_read_b128 v[64:67], v82 offset:4096
	s_waitcnt lgkmcnt(0)
	v_mfma_f32_32x32x16_bf16 v[16:31], v[64:67], v[68:71], v[16:31]
	v_mfma_f32_32x32x16_bf16 v[0:15], v[64:67], v[88:91], v[0:15]
	ds_read_b128 v[64:67], v86
	ds_read_b128 v[68:71], v87 offset:16384
	ds_read_b128 v[88:91], v87 offset:20480
	s_waitcnt lgkmcnt(0)
	v_mfma_f32_32x32x16_bf16 v[48:63], v[64:67], v[68:71], v[48:63]
	v_mfma_f32_32x32x16_bf16 v[32:47], v[64:67], v[88:91], v[32:47]
	ds_read_b128 v[64:67], v86 offset:4096
	s_waitcnt vmcnt(0)
	s_waitcnt vmcnt(0) lgkmcnt(0)
	s_barrier
	v_mfma_f32_32x32x16_bf16 v[16:31], v[64:67], v[68:71], v[16:31]
	v_mfma_f32_32x32x16_bf16 v[0:15], v[64:67], v[88:91], v[0:15]
	ds_read_b128 v[64:67], v79 offset:32768
	ds_read_b128 v[68:71], v81 offset:49152
	ds_read_b128 v[88:91], v81 offset:53248
	s_waitcnt lgkmcnt(1)
	v_mfma_f32_32x32x16_bf16 v[48:63], v[64:67], v[68:71], v[48:63]
	s_waitcnt lgkmcnt(0)
	v_mfma_f32_32x32x16_bf16 v[32:47], v[64:67], v[88:91], v[32:47]
	ds_read_b128 v[64:67], v79 offset:36864
	s_waitcnt lgkmcnt(0)
	v_mfma_f32_32x32x16_bf16 v[16:31], v[64:67], v[68:71], v[16:31]
	v_mfma_f32_32x32x16_bf16 v[0:15], v[64:67], v[88:91], v[0:15]
	ds_read_b128 v[64:67], v80 offset:32768
	ds_read_b128 v[68:71], v83 offset:49152
	ds_read_b128 v[76:79], v83 offset:53248
	s_waitcnt lgkmcnt(1)
	v_mfma_f32_32x32x16_bf16 v[48:63], v[64:67], v[68:71], v[48:63]
	s_waitcnt lgkmcnt(0)
	v_mfma_f32_32x32x16_bf16 v[32:47], v[64:67], v[76:79], v[32:47]
	ds_read_b128 v[64:67], v80 offset:36864
	s_waitcnt lgkmcnt(0)
	v_mfma_f32_32x32x16_bf16 v[16:31], v[64:67], v[68:71], v[16:31]
	v_mfma_f32_32x32x16_bf16 v[0:15], v[64:67], v[76:79], v[0:15]
	ds_read_b128 v[64:67], v82 offset:32768
	ds_read_b128 v[68:71], v85 offset:49152
	ds_read_b128 v[76:79], v85 offset:53248
	s_waitcnt lgkmcnt(1)
	v_mfma_f32_32x32x16_bf16 v[48:63], v[64:67], v[68:71], v[48:63]
	s_waitcnt lgkmcnt(0)
	v_mfma_f32_32x32x16_bf16 v[32:47], v[64:67], v[76:79], v[32:47]
	ds_read_b128 v[64:67], v82 offset:36864
	s_waitcnt lgkmcnt(0)
	v_mfma_f32_32x32x16_bf16 v[16:31], v[64:67], v[68:71], v[16:31]
	ds_read_b128 v[68:71], v87 offset:53248
	ds_read_b128 v[80:83], v87 offset:49152
	ds_read_b128 v[88:91], v86 offset:36864
	ds_read_b128 v[84:87], v86 offset:32768
	s_waitcnt vmcnt(0)
	s_waitcnt lgkmcnt(0)
	s_barrier
; template <class F>
; DI void epi_foreach(const f32x16 (&acc)[2][2], F f) {
;     ...
;   for (int mb = 0; mb < 2; ++mb)
; #pragma unroll
;     for (int nb = 0; nb < 2; ++nb)
; #pragma unroll
;       for (int r = 0; r < 16; ++r) {
;         const int row = wm * 64 + mb * 32 + (r & 3) + 8 * (r >> 2) + 4 * (lane >> 5);
;         const int col = wn * 64 + nb * 32 + (lane & 31);
;         f(row, col, acc[mb][nb][r]);
;         if ((r & 7) == 7) __builtin_amdgcn_sched_barrier(0);
; DI void phase_up(const Params& P, int layer, char* smem) {
;     ...
;     epi_foreach(acc, [&](int row, int col, float v) __attribute__((always_inline)) { Cs[row * 136 + col] = f2bf(v); });
;     __syncthreads();
;     {
;       const int col = tid & 63, rb = tid >> 6;
;       const int cv = nt * 64 + col, cg_ = DFF + nt * 64 + col;
;       const float w0v = cw[cv], w1v = cw[5632 + cv], w2v = cw[2 * 5632 + cv], bv = cb[cv];
;       const float w0g = cw[cg_], w1g = cw[5632 + cg_], w2g = cw[2 * 5632 + cg_], bgt = cb[cg_];
	v_mfma_f32_32x32x16_bf16 v[48:63], v[84:87], v[80:83], v[48:63]
	v_mfma_f32_32x32x16_bf16 v[0:15], v[64:67], v[76:79], v[0:15]
	v_mov_b32_e32 v64, v161
	v_mov_b32_e32 v65, v161
	v_lshrrev_b32_e32 v67, 3, v64
	v_and_b32_e32 v67, 4, v67
	v_lshrrev_b32_e32 v66, 1, v65
	v_and_b32_e32 v64, 31, v64
	v_and_or_b32 v64, v65, 64, v64
	v_and_or_b32 v65, v66, s3, v67
	v_mul_lo_u32 v65, v65, s97
	s_nop 1
	v_cvt_pk_bf16_f32 v48, v48, s0
	v_lshl_add_u32 v64, v64, 1, v65
	ds_write_b16 v64, v48
	v_cvt_pk_bf16_f32 v48, v49, s0
	ds_write_b16 v64, v48 offset:272
	v_cvt_pk_bf16_f32 v48, v50, s0
	ds_write_b16 v64, v48 offset:544
	v_cvt_pk_bf16_f32 v48, v51, s0
	ds_write_b16 v64, v48 offset:816
	v_cvt_pk_bf16_f32 v48, v52, s0
	ds_write_b16 v64, v48 offset:2176
	v_cvt_pk_bf16_f32 v48, v53, s0
	ds_write_b16 v64, v48 offset:2448
	v_cvt_pk_bf16_f32 v48, v54, s0
	ds_write_b16 v64, v48 offset:2720
	v_cvt_pk_bf16_f32 v48, v55, s0
	v_mfma_f32_32x32x16_bf16 v[32:47], v[84:87], v[68:71], v[32:47]
	ds_write_b16 v64, v48 offset:2992
	v_mfma_f32_32x32x16_bf16 v[16:31], v[88:91], v[80:83], v[16:31]
	v_mfma_f32_32x32x16_bf16 v[0:15], v[88:91], v[68:71], v[0:15]
	v_cvt_pk_bf16_f32 v48, v56, s0
	ds_write_b16 v64, v48 offset:4352
	v_cvt_pk_bf16_f32 v48, v57, s0
	ds_write_b16 v64, v48 offset:4624
	v_cvt_pk_bf16_f32 v48, v58, s0
	ds_write_b16 v64, v48 offset:4896
	v_cvt_pk_bf16_f32 v48, v59, s0
	ds_write_b16 v64, v48 offset:5168
	v_cvt_pk_bf16_f32 v48, v60, s0
	ds_write_b16 v64, v48 offset:6528
	v_cvt_pk_bf16_f32 v48, v61, s0
	ds_write_b16 v64, v48 offset:6800
	v_cvt_pk_bf16_f32 v48, v62, s0
	ds_write_b16 v64, v48 offset:7072
	v_cvt_pk_bf16_f32 v48, v63, s0
	ds_write_b16 v64, v48 offset:7344
	v_cvt_pk_bf16_f32 v32, v32, s0
	ds_write_b16 v64, v32 offset:64
	v_cvt_pk_bf16_f32 v32, v33, s0
	ds_write_b16 v64, v32 offset:336
	v_cvt_pk_bf16_f32 v32, v34, s0
	ds_write_b16 v64, v32 offset:608
	v_cvt_pk_bf16_f32 v32, v35, s0
	ds_write_b16 v64, v32 offset:880
	v_cvt_pk_bf16_f32 v32, v36, s0
	ds_write_b16 v64, v32 offset:2240
	v_cvt_pk_bf16_f32 v32, v37, s0
	ds_write_b16 v64, v32 offset:2512
	v_cvt_pk_bf16_f32 v32, v38, s0
	ds_write_b16 v64, v32 offset:2784
	v_cvt_pk_bf16_f32 v32, v39, s0
	ds_write_b16 v64, v32 offset:3056
	v_cvt_pk_bf16_f32 v32, v40, s0
	ds_write_b16 v64, v32 offset:4416
	v_cvt_pk_bf16_f32 v32, v41, s0
	ds_write_b16 v64, v32 offset:4688
	v_cvt_pk_bf16_f32 v32, v42, s0
	ds_write_b16 v64, v32 offset:4960
	v_cvt_pk_bf16_f32 v32, v43, s0
	ds_write_b16 v64, v32 offset:5232
	v_cvt_pk_bf16_f32 v32, v44, s0
	ds_write_b16 v64, v32 offset:6592
	v_cvt_pk_bf16_f32 v32, v45, s0
	ds_write_b16 v64, v32 offset:6864
	v_cvt_pk_bf16_f32 v32, v46, s0
	ds_write_b16 v64, v32 offset:7136
	v_cvt_pk_bf16_f32 v32, v47, s0
	ds_write_b16 v64, v32 offset:7408
	v_cvt_pk_bf16_f32 v16, v16, s0
	ds_write_b16 v64, v16 offset:8704
	v_cvt_pk_bf16_f32 v16, v17, s0
	ds_write_b16 v64, v16 offset:8976
	v_cvt_pk_bf16_f32 v16, v18, s0
	ds_write_b16 v64, v16 offset:9248
	v_cvt_pk_bf16_f32 v16, v19, s0
	ds_write_b16 v64, v16 offset:9520
	v_cvt_pk_bf16_f32 v16, v20, s0
	ds_write_b16 v64, v16 offset:10880
	v_cvt_pk_bf16_f32 v16, v21, s0
	ds_write_b16 v64, v16 offset:11152
	v_cvt_pk_bf16_f32 v16, v22, s0
	ds_write_b16 v64, v16 offset:11424
	v_cvt_pk_bf16_f32 v16, v23, s0
	ds_write_b16 v64, v16 offset:11696
	v_cvt_pk_bf16_f32 v16, v24, s0
	ds_write_b16 v64, v16 offset:13056
	v_cvt_pk_bf16_f32 v16, v25, s0
	ds_write_b16 v64, v16 offset:13328
	v_cvt_pk_bf16_f32 v16, v26, s0
	ds_write_b16 v64, v16 offset:13600
	v_cvt_pk_bf16_f32 v16, v27, s0
	ds_write_b16 v64, v16 offset:13872
	v_cvt_pk_bf16_f32 v16, v28, s0
	ds_write_b16 v64, v16 offset:15232
	v_cvt_pk_bf16_f32 v16, v29, s0
	ds_write_b16 v64, v16 offset:15504
	v_cvt_pk_bf16_f32 v16, v30, s0
	ds_write_b16 v64, v16 offset:15776
	v_cvt_pk_bf16_f32 v16, v31, s0
	ds_write_b16 v64, v16 offset:16048
	v_cvt_pk_bf16_f32 v0, v0, s0
	ds_write_b16 v64, v0 offset:8768
	v_cvt_pk_bf16_f32 v0, v1, s0
	ds_write_b16 v64, v0 offset:9040
	v_cvt_pk_bf16_f32 v0, v2, s0
	ds_write_b16 v64, v0 offset:9312
	v_cvt_pk_bf16_f32 v0, v3, s0
	ds_write_b16 v64, v0 offset:9584
	v_cvt_pk_bf16_f32 v0, v4, s0
	ds_write_b16 v64, v0 offset:10944
	v_cvt_pk_bf16_f32 v0, v5, s0
	ds_write_b16 v64, v0 offset:11216
	v_cvt_pk_bf16_f32 v0, v6, s0
	ds_write_b16 v64, v0 offset:11488
	v_cvt_pk_bf16_f32 v0, v7, s0
	ds_write_b16 v64, v0 offset:11760
	v_cvt_pk_bf16_f32 v0, v8, s0
	ds_write_b16 v64, v0 offset:13120
	v_cvt_pk_bf16_f32 v0, v9, s0
	ds_write_b16 v64, v0 offset:13392
	v_cvt_pk_bf16_f32 v0, v10, s0
	ds_write_b16 v64, v0 offset:13664
	v_cvt_pk_bf16_f32 v0, v11, s0
	ds_write_b16 v64, v0 offset:13936
	v_cvt_pk_bf16_f32 v0, v12, s0
	ds_write_b16 v64, v0 offset:15296
	v_cvt_pk_bf16_f32 v0, v13, s0
	ds_write_b16 v64, v0 offset:15568
	v_cvt_pk_bf16_f32 v0, v14, s0
	ds_write_b16 v64, v0 offset:15840
	v_cvt_pk_bf16_f32 v0, v15, s0
	ds_write_b16 v64, v0 offset:16112
	s_waitcnt lgkmcnt(0)
	s_barrier
	s_and_saveexec_b64 s[18:19], s[40:41]
	s_mov_b32 s3, 0xb000
	s_cbranch_execz .LBB0_24
	v_add_u32_e32 v136, s21, v74
	v_lshlrev_b64 v[4:5], 2, v[136:137]
	v_lshl_add_u64 v[8:9], s[10:11], 0, v[4:5]
	v_or_b32_e32 v10, s21, v72
	v_lshlrev_b32_e32 v126, 1, v10
	v_lshl_add_u64 v[2:3], s[12:13], 0, v[4:5]
	v_add_co_u32_e32 v4, vcc, 0xb000, v8
	v_ashrrev_i32_e32 v11, 31, v10
	s_nop 0
	v_addc_co_u32_e32 v5, vcc, 0, v9, vcc
	v_lshl_add_u64 v[0:1], v[10:11], 1, s[86:87]
	v_add_co_u32_e32 v6, vcc, 0x5000, v8
	v_lshlrev_b64 v[10:11], 2, v[10:11]
	s_nop 0
	v_addc_co_u32_e32 v7, vcc, 0, v9, vcc
	v_lshl_add_u64 v[12:13], s[12:13], 0, v[10:11]
	v_lshl_add_u64 v[10:11], s[10:11], 0, v[10:11]
	global_load_dword v3, v[2:3], off
	s_mulk_i32 s20, 0x7e
	global_load_dword v5, v[4:5], off
	s_nop 0
	global_load_dword v7, v[6:7], off offset:2048
	s_nop 0
	global_load_dword v9, v[8:9], off
	s_mul_i32 s21, s68, 0x7a
	global_load_dword v2, v[12:13], off
	v_add_co_u32_e32 v12, vcc, s3, v10
	s_sub_i32 s29, s20, s21
	s_nop 0
	v_addc_co_u32_e32 v13, vcc, 0, v11, vcc
	global_load_dword v4, v[12:13], off
	v_add_co_u32_e32 v12, vcc, 0x5000, v10
	s_mov_b64 s[20:21], 0
	s_nop 0
	v_addc_co_u32_e32 v13, vcc, 0, v11, vcc
	global_load_dword v6, v[12:13], off offset:2048
	global_load_dword v8, v[10:11], off
	v_mov_b32_e32 v11, v73
	v_mul_u32_u24_e32 v10, 0x110, v73
	s_waitcnt vmcnt(0)
	v_readfirstlane_b32 s22, v73
	v_add_u32_e32 v10, v75, v10
	v_add_u32_e32 v127, 0x1600, v126
	s_lshl_b32 s22, s22, 1
	s_add_i32 s23, s29, s22
	s_mul_hi_i32 s21, s23, 0x1600
	s_mul_i32 s20, s23, 0x1600
	s_add_u32 s20, s20, s86
	s_addc_u32 s21, s21, s87
	s_branch .LBB0_28

; template <class T> DI T* uoff(T* base, unsigned byteoff) { return (T*)((char*)base + byteoff); }
; template <class T> DI const T* uoff(const T* base, unsigned byteoff) { return (const T*)((const char*)base + byteoff); }
; DI void phase_out(const Params& P, int layer, const float* xin, char* smem) {
;     ...
;   for (int t0 = blockIdx.x; t0 < 256 * 8; t0 += gridDim.x) {
;     const int t = xcd_tile(t0, 256 * 8);
;     const int m0 = (t >> 3) * 128, n0 = (t & 7) * 128;
;     f32x16 acc[2][2];
;     float xr[2][2][16];
;     const unsigned obase_b = 4u * (unsigned)((m0 + wm * 64 + 4 * (lane >> 5)) * 1024 + n0 + wn * 64 + (lane & 31));
; #pragma unroll
;     for (int mb = 0; mb < 2; ++mb)
; #pragma unroll
;       for (int nb = 0; nb < 2; ++nb)
; #pragma unroll
;         for (int r = 0; r < 16; ++r) xr[mb][nb][r] = (*uoff(xin + ((mb * 32 + (r & 3) + 8 * (r >> 2)) * 1024 + nb * 32), obase_b));
.LBB0_43:
	s_ashr_i32 s0, s14, 3
	s_and_b32 s1, s0, 0xffffffc0
	s_lshl_b32 s10, s0, 1
	s_bfe_u32 s11, s0, 0x10005
	s_and_b32 s10, s10, 62
	s_or_b32 s1, s11, s1
	s_or_b32 s1, s1, s10
	s_and_b32 s10, s13, 0x700
	s_or_b32 s11, s0, 63
	s_cmpk_lt_i32 s11, 0x100
	s_cselect_b32 s1, s1, s0
	s_add_i32 s0, s1, s10
	s_lshl_b32 s0, s0, 4
	s_and_b32 s0, s0, 0xffffff80
	s_lshl_b32 s1, s1, 7
	s_and_b32 s15, s1, 0x380
	v_add_lshl_u32 v0, v80, s0, 10
	v_or3_b32 v0, v0, v81, s15
	v_lshlrev_b32_e32 v136, 2, v0
	v_lshl_add_u64 v[0:1], s[18:19], 0, v[136:137]
	v_add_co_u32_e32 v2, vcc, s17, v0
	s_mov_b32 s2, 0x13000
	s_nop 0
	v_addc_co_u32_e32 v3, vcc, 0, v1, vcc
	v_add_co_u32_e32 v4, vcc, s16, v0
	s_mov_b32 s68, 0x18000
	s_nop 0
	v_addc_co_u32_e32 v5, vcc, 0, v1, vcc
	v_add_co_u32_e32 v6, vcc, s20, v0
	s_mov_b32 s3, 0x1b000
	s_nop 0
	v_addc_co_u32_e32 v7, vcc, 0, v1, vcc
	v_add_co_u32_e32 v8, vcc, s9, v0
	global_load_dword v147, v136, s[18:19]
	s_nop 0
	v_addc_co_u32_e32 v9, vcc, 0, v1, vcc
	v_add_co_u32_e32 v10, vcc, s21, v0
	global_load_dword v148, v[4:5], off offset:-4096
	global_load_dword v145, v[4:5], off
	v_addc_co_u32_e32 v11, vcc, 0, v1, vcc
	v_add_co_u32_e32 v12, vcc, s22, v0
	global_load_dword v146, v[6:7], off
	s_nop 0
	v_addc_co_u32_e32 v13, vcc, 0, v1, vcc
	v_add_co_u32_e32 v14, vcc, s23, v0
	global_load_dword v144, v[10:11], off offset:-4096
	global_load_dword v142, v[10:11], off
	v_addc_co_u32_e32 v15, vcc, 0, v1, vcc
	v_add_co_u32_e32 v16, vcc, s28, v0
	global_load_dword v143, v[14:15], off offset:-4096
	global_load_dword v140, v[14:15], off
	v_addc_co_u32_e32 v17, vcc, 0, v1, vcc
	v_add_co_u32_e32 v18, vcc, s29, v0
	s_mov_b32 s6, 0x21000
	s_nop 0
	v_addc_co_u32_e32 v19, vcc, 0, v1, vcc
	v_add_co_u32_e32 v20, vcc, s42, v0
	global_load_dword v141, v[18:19], off offset:-4096
	global_load_dword v135, v[18:19], off
	v_addc_co_u32_e32 v21, vcc, 0, v1, vcc
	v_add_co_u32_e32 v22, vcc, s2, v0
	s_mov_b32 s2, 0x19000
	s_nop 0
	v_addc_co_u32_e32 v23, vcc, 0, v1, vcc
	v_add_co_u32_e32 v24, vcc, s68, v0
	s_mov_b32 s68, 0x1a000
	s_nop 0
	v_addc_co_u32_e32 v25, vcc, 0, v1, vcc
	v_add_co_u32_e32 v26, vcc, s2, v0
	global_load_dword v139, v[22:23], off offset:-4096
	global_load_dword v133, v[22:23], off
	v_addc_co_u32_e32 v27, vcc, 0, v1, vcc
	v_add_co_u32_e32 v28, vcc, s68, v0
	global_load_dword v134, v[26:27], off offset:-4096
	global_load_dword v131, v[26:27], off
	v_addc_co_u32_e32 v29, vcc, 0, v1, vcc
	v_add_co_u32_e32 v30, vcc, s3, v0
	s_mov_b32 s3, 0x20000
	s_nop 0
	v_addc_co_u32_e32 v31, vcc, 0, v1, vcc
	global_load_dword v132, v[30:31], off offset:-4096
	global_load_dword v130, v[30:31], off
	global_load_dword v129, v136, s[18:19] offset:128
	global_load_dword v128, v[2:3], off offset:128
	global_load_dword v127, v[4:5], off offset:128
	global_load_dword v126, v[6:7], off offset:128
	global_load_dword v125, v[8:9], off offset:128
	global_load_dword v124, v[10:11], off offset:128
	global_load_dword v123, v[12:13], off offset:128
	global_load_dword v122, v[14:15], off offset:128
	global_load_dword v121, v[16:17], off offset:128
	global_load_dword v120, v[18:19], off offset:128
	global_load_dword v119, v[20:21], off offset:128
	global_load_dword v117, v[22:23], off offset:128
	global_load_dword v116, v[24:25], off offset:128
	global_load_dword v115, v[26:27], off offset:128
	global_load_dword v114, v[28:29], off offset:128
	global_load_dword v113, v[30:31], off offset:128
	v_add_co_u32_e32 v2, vcc, s3, v0
	s_mov_b32 s12, 0x23000
	s_nop 0
	v_addc_co_u32_e32 v3, vcc, 0, v1, vcc
	v_add_co_u32_e32 v4, vcc, s6, v0
	s_mov_b32 s6, 0x22000
	s_nop 0
	v_addc_co_u32_e32 v5, vcc, 0, v1, vcc
	v_add_co_u32_e32 v6, vcc, s6, v0
	s_mov_b32 s8, 0x28000
	s_nop 0
	v_addc_co_u32_e32 v7, vcc, 0, v1, vcc
	v_add_co_u32_e32 v8, vcc, s12, v0
	s_mov_b32 s64, 0x2a000
	s_nop 0
	v_addc_co_u32_e32 v9, vcc, 0, v1, vcc
	v_add_co_u32_e32 v10, vcc, s8, v0
	s_mov_b32 s8, 0x29000
	s_nop 0
	v_addc_co_u32_e32 v11, vcc, 0, v1, vcc
	v_add_co_u32_e32 v12, vcc, s8, v0
	s_mov_b32 s65, 0x30000
	s_nop 0
	v_addc_co_u32_e32 v13, vcc, 0, v1, vcc
	v_add_co_u32_e32 v14, vcc, s64, v0
	s_mov_b32 s64, 0x2b000
	s_nop 0
	v_addc_co_u32_e32 v15, vcc, 0, v1, vcc
	v_add_co_u32_e32 v16, vcc, s64, v0
	s_mov_b32 s66, 0x32000
	s_nop 0
	v_addc_co_u32_e32 v17, vcc, 0, v1, vcc
	v_add_co_u32_e32 v18, vcc, s65, v0
	s_mov_b32 s65, 0x31000
	s_nop 0
	v_addc_co_u32_e32 v19, vcc, 0, v1, vcc
	v_add_co_u32_e32 v20, vcc, s65, v0
	s_mov_b32 s67, 0x38000
	s_nop 0
	v_addc_co_u32_e32 v21, vcc, 0, v1, vcc
	v_add_co_u32_e32 v22, vcc, s66, v0
	s_mov_b32 s66, 0x33000
	s_nop 0
	v_addc_co_u32_e32 v23, vcc, 0, v1, vcc
	v_add_co_u32_e32 v24, vcc, s66, v0
	global_load_dword v118, v[4:5], off offset:-4096
	global_load_dword v111, v[4:5], off
	v_addc_co_u32_e32 v25, vcc, 0, v1, vcc
	v_add_co_u32_e32 v26, vcc, s67, v0
	s_mov_b32 s67, 0x39000
	s_nop 0
	v_addc_co_u32_e32 v27, vcc, 0, v1, vcc
	v_add_co_u32_e32 v28, vcc, s67, v0
	global_load_dword v112, v[8:9], off offset:-4096
	global_load_dword v109, v[8:9], off
	v_addc_co_u32_e32 v29, vcc, 0, v1, vcc
	v_add_co_u32_e32 v30, vcc, s69, v0
	global_load_dword v110, v[12:13], off offset:-4096
	global_load_dword v107, v[12:13], off
	v_addc_co_u32_e32 v31, vcc, 0, v1, vcc
	v_add_co_u32_e32 v0, vcc, s71, v0
	global_load_dword v108, v[16:17], off offset:-4096
	global_load_dword v105, v[16:17], off
	v_addc_co_u32_e32 v1, vcc, 0, v1, vcc
	global_load_dword v106, v[20:21], off offset:-4096
	global_load_dword v103, v[20:21], off
	global_load_dword v104, v[24:25], off offset:-4096
	global_load_dword v101, v[24:25], off
	global_load_dword v102, v[28:29], off offset:-4096
	global_load_dword v99, v[28:29], off
; #define WAIT_V0() asm volatile("s_waitcnt vmcnt(0)" ::: "memory")
; DI int glds_row(int i) { const int tid = ltid(); return ((tid >> 6) * 4 + i) * 8 + ((tid & 63) >> 3); }
; DI int glds_chunk(int row) { return (ltid() & 7) ^ ((row >> 1) & 7); }
; DI void gemm_core(char* smem, int nk, const char* Ab, const char* Bb, const unsigned (&aoff)[4], const unsigned (&boff)[4],
;                   f32x16 (&acc)[2][2]) {
;     ...
;   auto stage = [&](int buf, int kt) __attribute__((always_inline)) {
;     const char* ak = Ab + kt * 128;
;     const char* bk = Bb + kt * 128;
;     char* sa = smem + buf * STAGE_B + w * 4096;
; #pragma unroll
;     for (int i = 0; i < 4; ++i) {
;       __builtin_amdgcn_global_load_lds((const unsigned*)(ak + aoff[i]), (unsigned*)(sa + i * 1024), 16, 0, 0);
;       __builtin_amdgcn_global_load_lds((const unsigned*)(bk + boff[i]), (unsigned*)(sa + 16384 + i * 1024), 16, 0, 0);
;     }
;   };
;   stage(0, 0);
;   WAIT_V0();
;   __syncthreads();
;   for (int kt = 0; kt < nk; ++kt) {
;     const int cur = kt & 1;
;     if (kt + 1 < nk) stage(cur ^ 1, kt + 1);
; DI void gemm_tile(char* smem, int nk, const bf16* A, int lda, int m0, const bf16* Bt, int ldb, int n0, f32x16 (&acc)[2][2]) {
;   unsigned aoff[4], boff[4];
; #pragma unroll
;   for (int i = 0; i < 4; ++i) {
;     const int row = glds_row(i), ch = glds_chunk(row);
;     aoff[i] = (unsigned)((row * lda + ch * 8) * 2);
;     boff[i] = (unsigned)((row * ldb + ch * 8) * 2);
;   }
;   gemm_core(smem, nk, (const char*)(A + (size_t)m0 * lda), (const char*)(Bt + (size_t)n0 * ldb), aoff, boff, acc);
	global_load_dword v100, v[0:1], off offset:-4096
	global_load_dword v98, v[0:1], off
	global_load_dword v97, v[2:3], off offset:128
	global_load_dword v96, v[4:5], off offset:128
	global_load_dword v95, v[6:7], off offset:128
	global_load_dword v94, v[8:9], off offset:128
	global_load_dword v93, v[10:11], off offset:128
	global_load_dword v92, v[12:13], off offset:128
	global_load_dword v91, v[14:15], off offset:128
	global_load_dword v90, v[16:17], off offset:128
	global_load_dword v89, v[18:19], off offset:128
	global_load_dword v88, v[20:21], off offset:128
	global_load_dword v87, v[22:23], off offset:128
	global_load_dword v86, v[24:25], off offset:128
	global_load_dword v85, v[26:27], off offset:128
	global_load_dword v84, v[28:29], off offset:128
	global_load_dword v83, v[30:31], off offset:128
	global_load_dword v82, v[0:1], off offset:128
	v_mov_b32_e32 v0, v161
	s_ashr_i32 s1, s0, 31
	v_lshrrev_b32_e32 v1, 1, v0
	v_lshrrev_b32_e32 v2, 3, v0
	v_bfe_u32 v0, v0, 3, 3
	v_and_or_b32 v0, v1, s43, v0
	v_mov_b32_e32 v1, v161
	v_bfe_u32 v2, v2, 1, 2
	v_xor_b32_e32 v1, v2, v1
	v_lshlrev_b32_e32 v0, 11, v0
	v_lshlrev_b32_e32 v1, 4, v1
	v_and_or_b32 v2, v1, s92, v0
	v_mov_b32_e32 v0, v161
	s_lshl_b64 s[0:1], s[0:1], 11
	v_ashrrev_i32_e32 v1, 1, v0
	v_and_b32_e32 v1, 0xffffffe0, v1
	v_bfe_u32 v0, v0, 3, 3
	v_or3_b32 v0, v0, v1, 8
	v_mov_b32_e32 v1, v161
	v_lshrrev_b32_e32 v3, 1, v0
	v_xor_b32_e32 v1, v3, v1
	v_lshlrev_b32_e32 v0, 11, v0
	v_lshlrev_b32_e32 v1, 4, v1
	v_and_or_b32 v4, v1, s92, v0
	v_mov_b32_e32 v0, v161
	s_add_u32 s10, s4, s0
	v_lshrrev_b32_e32 v1, 1, v0
	v_lshrrev_b32_e32 v3, 3, v0
	v_bfe_u32 v0, v0, 3, 3
	v_and_or_b32 v0, v1, s43, v0
	v_mov_b32_e32 v1, v161
	v_bfe_u32 v3, v3, 1, 2
	v_xor_b32_e32 v1, v3, v1
	v_lshlrev_b32_e32 v1, 4, v1
	v_lshlrev_b32_e32 v0, 11, v0
	v_and_b32_e32 v1, 0x70, v1
	v_or3_b32 v6, v0, v1, s9
	v_mov_b32_e32 v0, v161
	s_addc_u32 s11, s5, s1
	v_ashrrev_i32_e32 v1, 1, v0
	v_and_b32_e32 v1, 0xffffffe0, v1
	v_bfe_u32 v0, v0, 3, 3
	v_or3_b32 v0, v0, v1, 24
	v_mov_b32_e32 v1, v161
	v_lshrrev_b32_e32 v3, 1, v0
	v_xor_b32_e32 v1, v3, v1
	v_lshlrev_b32_e32 v0, 11, v0
	v_lshlrev_b32_e32 v1, 4, v1
	v_and_or_b32 v0, v1, s92, v0
	v_mov_b32_e32 v1, v161
	s_lshl_b32 s0, s15, 11
	v_and_b32_e32 v3, 31, v1
	v_lshrrev_b32_e32 v5, 5, v1
	v_bfe_u32 v7, v1, 5, 1
	v_lshrrev_b32_e32 v8, 1, v1
	v_bfe_u32 v9, v1, 1, 3
	v_lshlrev_b32_e32 v10, 7, v1
	v_lshlrev_b32_e32 v1, 6, v1
	v_and_b32_e32 v154, 0xfffff000, v1
	v_readlane_b32 s1, v255, 6
	v_add_u32_e32 v151, 0x4000, v154
	v_readfirstlane_b32 s17, v154
	s_add_u32 s0, s1, s0
	v_readlane_b32 s1, v255, 5
	s_mov_b32 m0, s17
	v_readfirstlane_b32 s16, v151
	v_or_b32_e32 v160, 0x400, v154
	s_addc_u32 s1, s1, 0
	global_load_lds_dwordx4 v2, s[10:11]
	s_mov_b32 m0, s16
	v_readfirstlane_b32 s18, v160
	v_add_u32_e32 v159, 0x4400, v154
	global_load_lds_dwordx4 v2, s[0:1]
	s_mov_b32 m0, s18
	v_readfirstlane_b32 s19, v159
	v_or_b32_e32 v164, 0x800, v154
	global_load_lds_dwordx4 v4, s[10:11]
	s_mov_b32 m0, s19
	v_readfirstlane_b32 s21, v164
	v_add_u32_e32 v162, 0x4800, v154
	s_mov_b32 s12, 0x1ffffc0
	v_bitop3_b32 v5, v5, v9, 1 bitop3:0x6c
	global_load_lds_dwordx4 v4, s[0:1]
	s_mov_b32 m0, s21
	v_readfirstlane_b32 s20, v162
	v_or_b32_e32 v166, 0xc00, v154
	v_and_or_b32 v3, v8, s12, v3
	v_lshlrev_b32_e32 v8, 4, v5
	v_bitop3_b32 v5, v7, v9, 2 bitop3:0x36
	global_load_lds_dwordx4 v6, s[10:11]
	s_mov_b32 m0, s20
	v_readfirstlane_b32 s23, v166
	v_add_u32_e32 v168, 0x4c00, v154
	v_lshlrev_b32_e32 v153, 4, v5
	v_bitop3_b32 v5, v7, v9, 4 bitop3:0x36
	v_lshlrev_b32_e32 v157, 7, v3
	v_mov_b32_e32 v3, v137
	global_load_lds_dwordx4 v6, s[0:1]
	s_mov_b32 m0, s23
	v_readfirstlane_b32 s22, v168
	v_add_u32_e32 v172, 0x8000, v154
	v_lshlrev_b32_e32 v156, 4, v5
	v_bitop3_b32 v5, v7, v9, 6 bitop3:0x36
	v_lshl_add_u64 v[66:67], s[10:11], 0, v[2:3]
	v_mov_b32_e32 v1, v137
	global_load_lds_dwordx4 v0, s[10:11]
	s_mov_b32 m0, s22
	v_add_u32_e32 v170, 0xc000, v154
	v_readfirstlane_b32 s29, v172
	v_lshlrev_b32_e32 v158, 4, v5
	v_lshl_add_u64 v[64:65], s[0:1], 0, v[2:3]
	v_mov_b32_e32 v5, v137
	v_lshl_add_u64 v[76:77], s[10:11], 0, v[0:1]
	v_lshl_add_u64 v[78:79], s[0:1], 0, v[0:1]
	global_load_lds_dwordx4 v0, s[0:1]
	v_lshl_add_u64 v[0:1], v[66:67], 0, s[94:95]
	s_mov_b32 m0, s29
	v_readfirstlane_b32 s28, v170
	v_add_u32_e32 v174, 0x8400, v154
	v_lshl_add_u64 v[68:69], s[10:11], 0, v[4:5]
	v_mov_b32_e32 v7, v137
	global_load_lds_dwordx4 v[0:1], off
	v_lshl_add_u64 v[0:1], v[64:65], 0, s[94:95]
	s_mov_b32 m0, s28
	v_readfirstlane_b32 s42, v174
	v_add_u32_e32 v2, 0xc400, v154
	v_lshl_add_u64 v[70:71], s[0:1], 0, v[4:5]
	v_lshl_add_u64 v[72:73], s[0:1], 0, v[6:7]
	global_load_lds_dwordx4 v[0:1], off
	v_lshl_add_u64 v[0:1], v[68:69], 0, s[94:95]
	s_mov_b32 m0, s42
	v_readfirstlane_b32 s0, v2
	v_add_u32_e32 v2, 0x8800, v154
	v_lshl_add_u64 v[74:75], s[10:11], 0, v[6:7]
	global_load_lds_dwordx4 v[0:1], off
	v_lshl_add_u64 v[0:1], v[70:71], 0, s[94:95]
	s_mov_b32 m0, s0
	v_readfirstlane_b32 s1, v2
	v_add_u32_e32 v2, 0xc800, v154
	global_load_lds_dwordx4 v[0:1], off
	v_lshl_add_u64 v[0:1], v[74:75], 0, s[94:95]
	s_mov_b32 m0, s1
	v_readfirstlane_b32 s10, v2
	v_add_u32_e32 v2, 0x8c00, v154
	global_load_lds_dwordx4 v[0:1], off
	v_lshl_add_u64 v[0:1], v[72:73], 0, s[94:95]
	s_mov_b32 m0, s10
	v_readfirstlane_b32 s11, v2
	v_add_u32_e32 v2, 0xcc00, v154
	global_load_lds_dwordx4 v[0:1], off
	v_lshl_add_u64 v[0:1], v[76:77], 0, s[94:95]
	s_mov_b32 m0, s11
	v_readfirstlane_b32 s15, v2
	v_and_b32_e32 v176, 0x2f80, v10
	global_load_lds_dwordx4 v[0:1], off
	v_lshl_add_u64 v[0:1], v[78:79], 0, s[94:95]
	s_mov_b32 m0, s15
	v_or_b32_e32 v149, v157, v8
	global_load_lds_dwordx4 v[0:1], off
	s_waitcnt vmcnt(8)
	s_waitcnt vmcnt(8) lgkmcnt(0)
	s_barrier
; #define WAIT_V0() asm volatile("s_waitcnt vmcnt(0)" ::: "memory")
; DI void gemm_core(char* smem, int nk, const char* Ab, const char* Bb, const unsigned (&aoff)[4], const unsigned (&boff)[4],
;                   f32x16 (&acc)[2][2]) {
;     ...
;   for (int kt = 0; kt < nk; ++kt) {
;     const int cur = kt & 1;
;     if (kt + 1 < nk) stage(cur ^ 1, kt + 1);
;     const char* sb = smem + cur * STAGE_B;
; #pragma unroll
;     for (int ks = 0; ks < 4; ++ks) {
;       bf16x8 af[2], bfr[2];
; #pragma unroll
;       for (int mb = 0; mb < 2; ++mb) af[mb] = *(const bf16x8*)(sb + a_base + mb * 4096 + xo[ks]);
; #pragma unroll
;       for (int nb = 0; nb < 2; ++nb) bfr[nb] = *(const bf16x8*)(sb + b_base + nb * 4096 + xo[ks]);
; #pragma unroll
;       for (int mb = 0; mb < 2; ++mb)
; #pragma unroll
;         for (int nb = 0; nb < 2; ++nb)
;           acc[mb][nb] = __builtin_amdgcn_mfma_f32_32x32x16_bf16(af[mb], bfr[nb], acc[mb][nb], 0, 0, 0);
;     }
;     WAIT_V0();
;     __syncthreads();
;   }
	v_or_b32_e32 v150, v176, v8
	ds_read_b128 v[0:3], v149
	ds_read_b128 v[4:7], v149 offset:4096
	ds_read_b128 v[8:11], v150 offset:16384
	ds_read_b128 v[12:15], v150 offset:20480
	s_waitcnt lgkmcnt(0)
	v_mfma_f32_32x32x16_bf16 v[48:63], v[0:3], v[8:11], 0
	v_or_b32_e32 v152, v157, v153
	v_or_b32_e32 v153, v176, v153
	ds_read_b128 v[208:211], v152
	ds_read_b128 v[212:215], v152 offset:4096
	ds_read_b128 v[216:219], v153 offset:16384
	ds_read_b128 v[220:223], v153 offset:20480
	v_or_b32_e32 v155, v157, v156
	v_or_b32_e32 v156, v176, v156
	v_or_b32_e32 v157, v157, v158
	v_mfma_f32_32x32x16_bf16 v[32:47], v[0:3], v[12:15], 0
	v_or_b32_e32 v158, v176, v158
	s_mov_b32 m0, s17
	s_add_i32 s14, s14, s70
	s_add_i32 s13, s13, s7
	s_cmpk_gt_i32 s14, 0x7ff
	v_mfma_f32_32x32x16_bf16 v[16:31], v[4:7], v[8:11], 0
	v_mfma_f32_32x32x16_bf16 v[0:15], v[4:7], v[12:15], 0
	s_waitcnt lgkmcnt(0)
	v_mfma_f32_32x32x16_bf16 v[48:63], v[208:211], v[216:219], v[48:63]
	v_mfma_f32_32x32x16_bf16 v[32:47], v[208:211], v[220:223], v[32:47]
	v_mfma_f32_32x32x16_bf16 v[16:31], v[212:215], v[216:219], v[16:31]
	v_mfma_f32_32x32x16_bf16 v[0:15], v[212:215], v[220:223], v[0:15]
	ds_read_b128 v[208:211], v155
	ds_read_b128 v[212:215], v155 offset:4096
	ds_read_b128 v[216:219], v156 offset:16384
	ds_read_b128 v[220:223], v156 offset:20480
	s_waitcnt lgkmcnt(0)
	v_mfma_f32_32x32x16_bf16 v[48:63], v[208:211], v[216:219], v[48:63]
	v_mfma_f32_32x32x16_bf16 v[32:47], v[208:211], v[220:223], v[32:47]
	v_mfma_f32_32x32x16_bf16 v[16:31], v[212:215], v[216:219], v[16:31]
	v_mfma_f32_32x32x16_bf16 v[0:15], v[212:215], v[220:223], v[0:15]
	ds_read_b128 v[208:211], v157
	ds_read_b128 v[212:215], v157 offset:4096
	ds_read_b128 v[216:219], v158 offset:16384
	ds_read_b128 v[220:223], v158 offset:20480
	s_waitcnt vmcnt(0)
	s_waitcnt vmcnt(0) lgkmcnt(0)
	s_barrier
	v_mfma_f32_32x32x16_bf16 v[48:63], v[208:211], v[216:219], v[48:63]
	v_mfma_f32_32x32x16_bf16 v[32:47], v[208:211], v[220:223], v[32:47]
	v_lshl_add_u64 v[208:209], v[66:67], 0, s[90:91]
	global_load_lds_dwordx4 v[208:209], off
	v_lshl_add_u64 v[208:209], v[64:65], 0, s[90:91]
	s_mov_b32 m0, s16
	s_nop 0
	global_load_lds_dwordx4 v[208:209], off
	v_lshl_add_u64 v[208:209], v[68:69], 0, s[90:91]
	s_mov_b32 m0, s18
	v_mfma_f32_32x32x16_bf16 v[16:31], v[212:215], v[216:219], v[16:31]
	global_load_lds_dwordx4 v[208:209], off
	v_lshl_add_u64 v[208:209], v[70:71], 0, s[90:91]
	s_mov_b32 m0, s19
	s_nop 0
	global_load_lds_dwordx4 v[208:209], off
	v_lshl_add_u64 v[208:209], v[74:75], 0, s[90:91]
	s_mov_b32 m0, s21
	v_mfma_f32_32x32x16_bf16 v[0:15], v[212:215], v[220:223], v[0:15]
	global_load_lds_dwordx4 v[208:209], off
	v_lshl_add_u64 v[208:209], v[72:73], 0, s[90:91]
	s_mov_b32 m0, s20
	s_nop 0
	global_load_lds_dwordx4 v[208:209], off
	v_lshl_add_u64 v[208:209], v[76:77], 0, s[90:91]
	s_mov_b32 m0, s23
	s_nop 0
	global_load_lds_dwordx4 v[208:209], off
	v_lshl_add_u64 v[208:209], v[78:79], 0, s[90:91]
	s_mov_b32 m0, s22
	s_nop 0
	global_load_lds_dwordx4 v[208:209], off
	ds_read_b128 v[208:211], v149 offset:32768
	ds_read_b128 v[212:215], v149 offset:36864
	ds_read_b128 v[216:219], v150 offset:49152
	ds_read_b128 v[220:223], v150 offset:53248
	s_waitcnt lgkmcnt(0)
	v_mfma_f32_32x32x16_bf16 v[48:63], v[208:211], v[216:219], v[48:63]
	s_mov_b32 m0, s29
	v_mfma_f32_32x32x16_bf16 v[32:47], v[208:211], v[220:223], v[32:47]
	v_mfma_f32_32x32x16_bf16 v[16:31], v[212:215], v[216:219], v[16:31]
	v_mfma_f32_32x32x16_bf16 v[0:15], v[212:215], v[220:223], v[0:15]
	ds_read_b128 v[208:211], v152 offset:32768
	ds_read_b128 v[212:215], v152 offset:36864
	ds_read_b128 v[216:219], v153 offset:49152
	ds_read_b128 v[220:223], v153 offset:53248
	s_waitcnt lgkmcnt(0)
	v_mfma_f32_32x32x16_bf16 v[48:63], v[208:211], v[216:219], v[48:63]
	v_mfma_f32_32x32x16_bf16 v[32:47], v[208:211], v[220:223], v[32:47]
	v_mfma_f32_32x32x16_bf16 v[16:31], v[212:215], v[216:219], v[16:31]
	v_mfma_f32_32x32x16_bf16 v[0:15], v[212:215], v[220:223], v[0:15]
	ds_read_b128 v[208:211], v155 offset:32768
	ds_read_b128 v[212:215], v155 offset:36864
	ds_read_b128 v[216:219], v156 offset:49152
	ds_read_b128 v[220:223], v156 offset:53248
	s_waitcnt lgkmcnt(0)
	v_mfma_f32_32x32x16_bf16 v[48:63], v[208:211], v[216:219], v[48:63]
	v_mfma_f32_32x32x16_bf16 v[32:47], v[208:211], v[220:223], v[32:47]
	v_mfma_f32_32x32x16_bf16 v[16:31], v[212:215], v[216:219], v[16:31]
	v_mfma_f32_32x32x16_bf16 v[0:15], v[212:215], v[220:223], v[0:15]
	ds_read_b128 v[208:211], v157 offset:32768
	ds_read_b128 v[212:215], v157 offset:36864
	ds_read_b128 v[216:219], v158 offset:49152
	ds_read_b128 v[220:223], v158 offset:53248
	s_waitcnt vmcnt(0)
	s_waitcnt vmcnt(0) lgkmcnt(0)
	s_barrier
; #define WAIT_V0() asm volatile("s_waitcnt vmcnt(0)" ::: "memory")
; DI void gemm_core(char* smem, int nk, const char* Ab, const char* Bb, const unsigned (&aoff)[4], const unsigned (&boff)[4],
;                   f32x16 (&acc)[2][2]) {
;     ...
;   for (int kt = 0; kt < nk; ++kt) {
;     const int cur = kt & 1;
;     if (kt + 1 < nk) stage(cur ^ 1, kt + 1);
;     const char* sb = smem + cur * STAGE_B;
; #pragma unroll
;     for (int ks = 0; ks < 4; ++ks) {
;       bf16x8 af[2], bfr[2];
; #pragma unroll
;       for (int mb = 0; mb < 2; ++mb) af[mb] = *(const bf16x8*)(sb + a_base + mb * 4096 + xo[ks]);
; #pragma unroll
;       for (int nb = 0; nb < 2; ++nb) bfr[nb] = *(const bf16x8*)(sb + b_base + nb * 4096 + xo[ks]);
; #pragma unroll
;       for (int mb = 0; mb < 2; ++mb)
; #pragma unroll
;         for (int nb = 0; nb < 2; ++nb)
;           acc[mb][nb] = __builtin_amdgcn_mfma_f32_32x32x16_bf16(af[mb], bfr[nb], acc[mb][nb], 0, 0, 0);
;     }
;     WAIT_V0();
;     __syncthreads();
;   }
	v_mfma_f32_32x32x16_bf16 v[48:63], v[208:211], v[216:219], v[48:63]
	v_mfma_f32_32x32x16_bf16 v[32:47], v[208:211], v[220:223], v[32:47]
	v_lshl_add_u64 v[208:209], v[66:67], 0, s[40:41]
	global_load_lds_dwordx4 v[208:209], off
	v_lshl_add_u64 v[208:209], v[64:65], 0, s[40:41]
	s_mov_b32 m0, s28
	s_nop 0
	global_load_lds_dwordx4 v[208:209], off
	v_lshl_add_u64 v[208:209], v[68:69], 0, s[40:41]
	s_mov_b32 m0, s42
	v_mfma_f32_32x32x16_bf16 v[16:31], v[212:215], v[216:219], v[16:31]
	global_load_lds_dwordx4 v[208:209], off
	v_lshl_add_u64 v[208:209], v[70:71], 0, s[40:41]
	s_mov_b32 m0, s0
	s_nop 0
	global_load_lds_dwordx4 v[208:209], off
	v_lshl_add_u64 v[208:209], v[74:75], 0, s[40:41]
	s_mov_b32 m0, s1
	v_mfma_f32_32x32x16_bf16 v[0:15], v[212:215], v[220:223], v[0:15]
	global_load_lds_dwordx4 v[208:209], off
	v_lshl_add_u64 v[208:209], v[72:73], 0, s[40:41]
	s_mov_b32 m0, s10
	s_nop 0
	global_load_lds_dwordx4 v[208:209], off
	v_lshl_add_u64 v[208:209], v[76:77], 0, s[40:41]
	s_mov_b32 m0, s11
	s_nop 0
	global_load_lds_dwordx4 v[208:209], off
	v_lshl_add_u64 v[208:209], v[78:79], 0, s[40:41]
	s_mov_b32 m0, s15
	s_nop 0
	global_load_lds_dwordx4 v[208:209], off
	ds_read_b128 v[208:211], v149
	ds_read_b128 v[212:215], v149 offset:4096
	ds_read_b128 v[216:219], v150 offset:16384
	ds_read_b128 v[220:223], v150 offset:20480
	s_waitcnt lgkmcnt(0)
	v_mfma_f32_32x32x16_bf16 v[48:63], v[208:211], v[216:219], v[48:63]
	s_mov_b32 m0, s17
	v_mfma_f32_32x32x16_bf16 v[32:47], v[208:211], v[220:223], v[32:47]
	v_mfma_f32_32x32x16_bf16 v[16:31], v[212:215], v[216:219], v[16:31]
	v_mfma_f32_32x32x16_bf16 v[0:15], v[212:215], v[220:223], v[0:15]
	ds_read_b128 v[208:211], v152
	ds_read_b128 v[212:215], v152 offset:4096
	ds_read_b128 v[216:219], v153 offset:16384
	ds_read_b128 v[220:223], v153 offset:20480
	s_waitcnt lgkmcnt(0)
	v_mfma_f32_32x32x16_bf16 v[48:63], v[208:211], v[216:219], v[48:63]
	v_mfma_f32_32x32x16_bf16 v[32:47], v[208:211], v[220:223], v[32:47]
	v_mfma_f32_32x32x16_bf16 v[16:31], v[212:215], v[216:219], v[16:31]
	v_mfma_f32_32x32x16_bf16 v[0:15], v[212:215], v[220:223], v[0:15]
	ds_read_b128 v[208:211], v155
	ds_read_b128 v[212:215], v155 offset:4096
	ds_read_b128 v[216:219], v156 offset:16384
	ds_read_b128 v[220:223], v156 offset:20480
	s_waitcnt lgkmcnt(0)
	v_mfma_f32_32x32x16_bf16 v[48:63], v[208:211], v[216:219], v[48:63]
	v_mfma_f32_32x32x16_bf16 v[32:47], v[208:211], v[220:223], v[32:47]
	v_mfma_f32_32x32x16_bf16 v[16:31], v[212:215], v[216:219], v[16:31]
	v_mfma_f32_32x32x16_bf16 v[0:15], v[212:215], v[220:223], v[0:15]
	ds_read_b128 v[208:211], v157
	ds_read_b128 v[212:215], v157 offset:4096
	ds_read_b128 v[216:219], v158 offset:16384
	ds_read_b128 v[220:223], v158 offset:20480
	s_waitcnt vmcnt(0)
	s_waitcnt vmcnt(0) lgkmcnt(0)
	s_barrier
	v_mfma_f32_32x32x16_bf16 v[48:63], v[208:211], v[216:219], v[48:63]
	v_mfma_f32_32x32x16_bf16 v[32:47], v[208:211], v[220:223], v[32:47]
	v_lshl_add_u64 v[208:209], v[66:67], 0, s[30:31]
	global_load_lds_dwordx4 v[208:209], off
	v_lshl_add_u64 v[208:209], v[64:65], 0, s[30:31]
	s_mov_b32 m0, s16
	s_nop 0
	global_load_lds_dwordx4 v[208:209], off
	v_lshl_add_u64 v[208:209], v[68:69], 0, s[30:31]
	s_mov_b32 m0, s18
	v_mfma_f32_32x32x16_bf16 v[16:31], v[212:215], v[216:219], v[16:31]
	global_load_lds_dwordx4 v[208:209], off
	v_lshl_add_u64 v[208:209], v[70:71], 0, s[30:31]
	s_mov_b32 m0, s19
	s_nop 0
	global_load_lds_dwordx4 v[208:209], off
	v_lshl_add_u64 v[208:209], v[74:75], 0, s[30:31]
	s_mov_b32 m0, s21
	v_mfma_f32_32x32x16_bf16 v[0:15], v[212:215], v[220:223], v[0:15]
	global_load_lds_dwordx4 v[208:209], off
	v_lshl_add_u64 v[208:209], v[72:73], 0, s[30:31]
	s_mov_b32 m0, s20
	s_nop 0
	global_load_lds_dwordx4 v[208:209], off
	v_lshl_add_u64 v[208:209], v[76:77], 0, s[30:31]
	s_mov_b32 m0, s23
	s_nop 0
	global_load_lds_dwordx4 v[208:209], off
	v_lshl_add_u64 v[208:209], v[78:79], 0, s[30:31]
	s_mov_b32 m0, s22
	s_nop 0
	global_load_lds_dwordx4 v[208:209], off
	ds_read_b128 v[208:211], v149 offset:32768
	ds_read_b128 v[212:215], v149 offset:36864
	ds_read_b128 v[216:219], v150 offset:49152
	ds_read_b128 v[220:223], v150 offset:53248
	s_waitcnt lgkmcnt(0)
	v_mfma_f32_32x32x16_bf16 v[48:63], v[208:211], v[216:219], v[48:63]
	s_mov_b32 m0, s29
	v_mfma_f32_32x32x16_bf16 v[32:47], v[208:211], v[220:223], v[32:47]
	v_mfma_f32_32x32x16_bf16 v[16:31], v[212:215], v[216:219], v[16:31]
	v_mfma_f32_32x32x16_bf16 v[0:15], v[212:215], v[220:223], v[0:15]
	ds_read_b128 v[208:211], v152 offset:32768
	ds_read_b128 v[212:215], v152 offset:36864
	ds_read_b128 v[216:219], v153 offset:49152
	ds_read_b128 v[220:223], v153 offset:53248
	s_waitcnt lgkmcnt(0)
	v_mfma_f32_32x32x16_bf16 v[48:63], v[208:211], v[216:219], v[48:63]
	v_mfma_f32_32x32x16_bf16 v[32:47], v[208:211], v[220:223], v[32:47]
	v_mfma_f32_32x32x16_bf16 v[16:31], v[212:215], v[216:219], v[16:31]
	v_mfma_f32_32x32x16_bf16 v[0:15], v[212:215], v[220:223], v[0:15]
	ds_read_b128 v[208:211], v155 offset:32768
	ds_read_b128 v[212:215], v155 offset:36864
	ds_read_b128 v[216:219], v156 offset:49152
	ds_read_b128 v[220:223], v156 offset:53248
	s_waitcnt lgkmcnt(0)
	v_mfma_f32_32x32x16_bf16 v[48:63], v[208:211], v[216:219], v[48:63]
	v_mfma_f32_32x32x16_bf16 v[32:47], v[208:211], v[220:223], v[32:47]
	v_mfma_f32_32x32x16_bf16 v[16:31], v[212:215], v[216:219], v[16:31]
	v_mfma_f32_32x32x16_bf16 v[0:15], v[212:215], v[220:223], v[0:15]
	ds_read_b128 v[208:211], v157 offset:32768
	ds_read_b128 v[212:215], v157 offset:36864
	ds_read_b128 v[216:219], v158 offset:49152
	ds_read_b128 v[220:223], v158 offset:53248
	s_waitcnt vmcnt(0)
	s_waitcnt vmcnt(0) lgkmcnt(0)
	s_barrier
; #define WAIT_V0() asm volatile("s_waitcnt vmcnt(0)" ::: "memory")
; DI void gemm_core(char* smem, int nk, const char* Ab, const char* Bb, const unsigned (&aoff)[4], const unsigned (&boff)[4],
;                   f32x16 (&acc)[2][2]) {
;     ...
;   for (int kt = 0; kt < nk; ++kt) {
;     const int cur = kt & 1;
;     if (kt + 1 < nk) stage(cur ^ 1, kt + 1);
;     const char* sb = smem + cur * STAGE_B;
; #pragma unroll
;     for (int ks = 0; ks < 4; ++ks) {
;       bf16x8 af[2], bfr[2];
; #pragma unroll
;       for (int mb = 0; mb < 2; ++mb) af[mb] = *(const bf16x8*)(sb + a_base + mb * 4096 + xo[ks]);
; #pragma unroll
;       for (int nb = 0; nb < 2; ++nb) bfr[nb] = *(const bf16x8*)(sb + b_base + nb * 4096 + xo[ks]);
; #pragma unroll
;       for (int mb = 0; mb < 2; ++mb)
; #pragma unroll
;         for (int nb = 0; nb < 2; ++nb)
;           acc[mb][nb] = __builtin_amdgcn_mfma_f32_32x32x16_bf16(af[mb], bfr[nb], acc[mb][nb], 0, 0, 0);
;     }
;     WAIT_V0();
;     __syncthreads();
;   }
	v_mfma_f32_32x32x16_bf16 v[48:63], v[208:211], v[216:219], v[48:63]
	v_mfma_f32_32x32x16_bf16 v[32:47], v[208:211], v[220:223], v[32:47]
	v_lshl_add_u64 v[208:209], v[66:67], 0, s[88:89]
	global_load_lds_dwordx4 v[208:209], off
	v_lshl_add_u64 v[208:209], v[64:65], 0, s[88:89]
	s_mov_b32 m0, s28
	s_nop 0
	global_load_lds_dwordx4 v[208:209], off
	v_lshl_add_u64 v[208:209], v[68:69], 0, s[88:89]
	s_mov_b32 m0, s42
	v_mfma_f32_32x32x16_bf16 v[16:31], v[212:215], v[216:219], v[16:31]
	global_load_lds_dwordx4 v[208:209], off
	v_lshl_add_u64 v[208:209], v[70:71], 0, s[88:89]
	s_mov_b32 m0, s0
	s_nop 0
	global_load_lds_dwordx4 v[208:209], off
	v_lshl_add_u64 v[208:209], v[74:75], 0, s[88:89]
	s_mov_b32 m0, s1
	v_mfma_f32_32x32x16_bf16 v[0:15], v[212:215], v[220:223], v[0:15]
	global_load_lds_dwordx4 v[208:209], off
	v_lshl_add_u64 v[208:209], v[72:73], 0, s[88:89]
	s_mov_b32 m0, s10
	s_nop 0
	global_load_lds_dwordx4 v[208:209], off
	v_lshl_add_u64 v[208:209], v[76:77], 0, s[88:89]
	s_mov_b32 m0, s11
	s_nop 0
	global_load_lds_dwordx4 v[208:209], off
	v_lshl_add_u64 v[208:209], v[78:79], 0, s[88:89]
	s_mov_b32 m0, s15
	s_nop 0
	global_load_lds_dwordx4 v[208:209], off
	ds_read_b128 v[208:211], v149
	ds_read_b128 v[212:215], v149 offset:4096
	ds_read_b128 v[216:219], v150 offset:16384
	ds_read_b128 v[220:223], v150 offset:20480
	s_waitcnt lgkmcnt(0)
	v_mfma_f32_32x32x16_bf16 v[48:63], v[208:211], v[216:219], v[48:63]
	s_mov_b32 m0, s17
	v_mfma_f32_32x32x16_bf16 v[32:47], v[208:211], v[220:223], v[32:47]
	v_mfma_f32_32x32x16_bf16 v[16:31], v[212:215], v[216:219], v[16:31]
	v_mfma_f32_32x32x16_bf16 v[0:15], v[212:215], v[220:223], v[0:15]
	ds_read_b128 v[208:211], v152
	ds_read_b128 v[212:215], v152 offset:4096
	ds_read_b128 v[216:219], v153 offset:16384
	ds_read_b128 v[220:223], v153 offset:20480
	s_waitcnt lgkmcnt(0)
	v_mfma_f32_32x32x16_bf16 v[48:63], v[208:211], v[216:219], v[48:63]
	v_mfma_f32_32x32x16_bf16 v[32:47], v[208:211], v[220:223], v[32:47]
	v_mfma_f32_32x32x16_bf16 v[16:31], v[212:215], v[216:219], v[16:31]
	v_mfma_f32_32x32x16_bf16 v[0:15], v[212:215], v[220:223], v[0:15]
	ds_read_b128 v[208:211], v155
	ds_read_b128 v[212:215], v155 offset:4096
	ds_read_b128 v[216:219], v156 offset:16384
	ds_read_b128 v[220:223], v156 offset:20480
	s_waitcnt lgkmcnt(0)
	v_mfma_f32_32x32x16_bf16 v[48:63], v[208:211], v[216:219], v[48:63]
	v_mfma_f32_32x32x16_bf16 v[32:47], v[208:211], v[220:223], v[32:47]
	v_mfma_f32_32x32x16_bf16 v[16:31], v[212:215], v[216:219], v[16:31]
	v_mfma_f32_32x32x16_bf16 v[0:15], v[212:215], v[220:223], v[0:15]
	ds_read_b128 v[208:211], v157
	ds_read_b128 v[212:215], v157 offset:4096
	ds_read_b128 v[216:219], v158 offset:16384
	ds_read_b128 v[220:223], v158 offset:20480
	s_waitcnt vmcnt(0)
	s_waitcnt vmcnt(0) lgkmcnt(0)
	s_barrier
	v_mfma_f32_32x32x16_bf16 v[48:63], v[208:211], v[216:219], v[48:63]
	v_mfma_f32_32x32x16_bf16 v[32:47], v[208:211], v[220:223], v[32:47]
	v_lshl_add_u64 v[208:209], v[66:67], 0, s[44:45]
	global_load_lds_dwordx4 v[208:209], off
	v_lshl_add_u64 v[208:209], v[64:65], 0, s[44:45]
	s_mov_b32 m0, s16
	s_nop 0
	global_load_lds_dwordx4 v[208:209], off
	v_lshl_add_u64 v[208:209], v[68:69], 0, s[44:45]
	s_mov_b32 m0, s18
	v_mfma_f32_32x32x16_bf16 v[16:31], v[212:215], v[216:219], v[16:31]
	global_load_lds_dwordx4 v[208:209], off
	v_lshl_add_u64 v[208:209], v[70:71], 0, s[44:45]
	s_mov_b32 m0, s19
	s_nop 0
	global_load_lds_dwordx4 v[208:209], off
	v_lshl_add_u64 v[208:209], v[74:75], 0, s[44:45]
	s_mov_b32 m0, s21
	v_mfma_f32_32x32x16_bf16 v[0:15], v[212:215], v[220:223], v[0:15]
	global_load_lds_dwordx4 v[208:209], off
	v_lshl_add_u64 v[208:209], v[72:73], 0, s[44:45]
	s_mov_b32 m0, s20
	s_nop 0
	global_load_lds_dwordx4 v[208:209], off
	v_lshl_add_u64 v[208:209], v[76:77], 0, s[44:45]
	s_mov_b32 m0, s23
	s_nop 0
	global_load_lds_dwordx4 v[208:209], off
	v_lshl_add_u64 v[208:209], v[78:79], 0, s[44:45]
	s_mov_b32 m0, s22
	s_nop 0
	global_load_lds_dwordx4 v[208:209], off
	ds_read_b128 v[208:211], v149 offset:32768
	ds_read_b128 v[212:215], v149 offset:36864
	ds_read_b128 v[216:219], v150 offset:49152
	ds_read_b128 v[220:223], v150 offset:53248
	s_waitcnt lgkmcnt(0)
	v_mfma_f32_32x32x16_bf16 v[48:63], v[208:211], v[216:219], v[48:63]
	s_mov_b32 m0, s29
	v_readfirstlane_b32 s29, v168
	v_mfma_f32_32x32x16_bf16 v[32:47], v[208:211], v[220:223], v[32:47]
	v_mfma_f32_32x32x16_bf16 v[16:31], v[212:215], v[216:219], v[16:31]
	v_mfma_f32_32x32x16_bf16 v[0:15], v[212:215], v[220:223], v[0:15]
	ds_read_b128 v[208:211], v152 offset:32768
	ds_read_b128 v[212:215], v152 offset:36864
	ds_read_b128 v[216:219], v153 offset:49152
	ds_read_b128 v[220:223], v153 offset:53248
	s_waitcnt lgkmcnt(0)
	v_mfma_f32_32x32x16_bf16 v[48:63], v[208:211], v[216:219], v[48:63]
	v_mfma_f32_32x32x16_bf16 v[32:47], v[208:211], v[220:223], v[32:47]
	v_mfma_f32_32x32x16_bf16 v[16:31], v[212:215], v[216:219], v[16:31]
	v_mfma_f32_32x32x16_bf16 v[0:15], v[212:215], v[220:223], v[0:15]
	ds_read_b128 v[208:211], v155 offset:32768
	ds_read_b128 v[212:215], v155 offset:36864
	ds_read_b128 v[216:219], v156 offset:49152
	ds_read_b128 v[220:223], v156 offset:53248
	s_waitcnt lgkmcnt(0)
	v_mfma_f32_32x32x16_bf16 v[48:63], v[208:211], v[216:219], v[48:63]
	v_mfma_f32_32x32x16_bf16 v[32:47], v[208:211], v[220:223], v[32:47]
	v_mfma_f32_32x32x16_bf16 v[16:31], v[212:215], v[216:219], v[16:31]
	v_mfma_f32_32x32x16_bf16 v[0:15], v[212:215], v[220:223], v[0:15]
	ds_read_b128 v[208:211], v157 offset:32768
	ds_read_b128 v[212:215], v157 offset:36864
	ds_read_b128 v[216:219], v158 offset:49152
	ds_read_b128 v[220:223], v158 offset:53248
	s_waitcnt vmcnt(0)
	s_waitcnt vmcnt(0) lgkmcnt(0)
	s_barrier
; #define WAIT_V0() asm volatile("s_waitcnt vmcnt(0)" ::: "memory")
; DI void gemm_core(char* smem, int nk, const char* Ab, const char* Bb, const unsigned (&aoff)[4], const unsigned (&boff)[4],
;                   f32x16 (&acc)[2][2]) {
;     ...
;   for (int kt = 0; kt < nk; ++kt) {
;     const int cur = kt & 1;
;     if (kt + 1 < nk) stage(cur ^ 1, kt + 1);
;     const char* sb = smem + cur * STAGE_B;
; #pragma unroll
;     for (int ks = 0; ks < 4; ++ks) {
;       bf16x8 af[2], bfr[2];
; #pragma unroll
;       for (int mb = 0; mb < 2; ++mb) af[mb] = *(const bf16x8*)(sb + a_base + mb * 4096 + xo[ks]);
; #pragma unroll
;       for (int nb = 0; nb < 2; ++nb) bfr[nb] = *(const bf16x8*)(sb + b_base + nb * 4096 + xo[ks]);
; #pragma unroll
;       for (int mb = 0; mb < 2; ++mb)
; #pragma unroll
;         for (int nb = 0; nb < 2; ++nb)
;           acc[mb][nb] = __builtin_amdgcn_mfma_f32_32x32x16_bf16(af[mb], bfr[nb], acc[mb][nb], 0, 0, 0);
;     }
;     WAIT_V0();
;     __syncthreads();
;   }
	v_mfma_f32_32x32x16_bf16 v[48:63], v[208:211], v[216:219], v[48:63]
	v_mfma_f32_32x32x16_bf16 v[32:47], v[208:211], v[220:223], v[32:47]
	v_lshl_add_u64 v[208:209], v[66:67], 0, s[46:47]
	global_load_lds_dwordx4 v[208:209], off
	v_lshl_add_u64 v[208:209], v[64:65], 0, s[46:47]
	s_mov_b32 m0, s28
	v_readfirstlane_b32 s28, v162
	global_load_lds_dwordx4 v[208:209], off
	v_lshl_add_u64 v[208:209], v[68:69], 0, s[46:47]
	s_mov_b32 m0, s42
	v_mfma_f32_32x32x16_bf16 v[16:31], v[212:215], v[216:219], v[16:31]
	global_load_lds_dwordx4 v[208:209], off
	v_lshl_add_u64 v[208:209], v[70:71], 0, s[46:47]
	s_mov_b32 m0, s0
	v_readfirstlane_b32 s42, v166
	global_load_lds_dwordx4 v[208:209], off
	v_lshl_add_u64 v[208:209], v[74:75], 0, s[46:47]
	s_mov_b32 m0, s1
	v_mfma_f32_32x32x16_bf16 v[0:15], v[212:215], v[220:223], v[0:15]
	global_load_lds_dwordx4 v[208:209], off
	v_lshl_add_u64 v[208:209], v[72:73], 0, s[46:47]
	s_mov_b32 m0, s10
	s_nop 0
	global_load_lds_dwordx4 v[208:209], off
	v_lshl_add_u64 v[208:209], v[76:77], 0, s[46:47]
	s_mov_b32 m0, s11
	s_nop 0
	global_load_lds_dwordx4 v[208:209], off
	v_lshl_add_u64 v[208:209], v[78:79], 0, s[46:47]
	s_mov_b32 m0, s15
	s_nop 0
	global_load_lds_dwordx4 v[208:209], off
	ds_read_b128 v[208:211], v149
	ds_read_b128 v[212:215], v149 offset:4096
	ds_read_b128 v[216:219], v150 offset:16384
	ds_read_b128 v[220:223], v150 offset:20480
	s_waitcnt lgkmcnt(0)
	v_mfma_f32_32x32x16_bf16 v[48:63], v[208:211], v[216:219], v[48:63]
	s_mov_b32 m0, s17
	v_readfirstlane_b32 s17, v170
	v_mfma_f32_32x32x16_bf16 v[32:47], v[208:211], v[220:223], v[32:47]
	v_mfma_f32_32x32x16_bf16 v[16:31], v[212:215], v[216:219], v[16:31]
	v_mfma_f32_32x32x16_bf16 v[0:15], v[212:215], v[220:223], v[0:15]
	ds_read_b128 v[208:211], v152
	ds_read_b128 v[212:215], v152 offset:4096
	ds_read_b128 v[216:219], v153 offset:16384
	ds_read_b128 v[220:223], v153 offset:20480
	s_waitcnt lgkmcnt(0)
	v_mfma_f32_32x32x16_bf16 v[48:63], v[208:211], v[216:219], v[48:63]
	v_mfma_f32_32x32x16_bf16 v[32:47], v[208:211], v[220:223], v[32:47]
	v_mfma_f32_32x32x16_bf16 v[16:31], v[212:215], v[216:219], v[16:31]
	v_mfma_f32_32x32x16_bf16 v[0:15], v[212:215], v[220:223], v[0:15]
	ds_read_b128 v[208:211], v155
	ds_read_b128 v[212:215], v155 offset:4096
	ds_read_b128 v[216:219], v156 offset:16384
	ds_read_b128 v[220:223], v156 offset:20480
	s_waitcnt lgkmcnt(0)
	v_mfma_f32_32x32x16_bf16 v[48:63], v[208:211], v[216:219], v[48:63]
	v_mfma_f32_32x32x16_bf16 v[32:47], v[208:211], v[220:223], v[32:47]
	v_mfma_f32_32x32x16_bf16 v[16:31], v[212:215], v[216:219], v[16:31]
	v_mfma_f32_32x32x16_bf16 v[0:15], v[212:215], v[220:223], v[0:15]
	ds_read_b128 v[208:211], v157
	ds_read_b128 v[212:215], v157 offset:4096
	ds_read_b128 v[216:219], v158 offset:16384
	ds_read_b128 v[220:223], v158 offset:20480
	s_waitcnt vmcnt(0)
	s_waitcnt vmcnt(0) lgkmcnt(0)
	s_barrier
	v_mfma_f32_32x32x16_bf16 v[48:63], v[208:211], v[216:219], v[48:63]
	v_mfma_f32_32x32x16_bf16 v[32:47], v[208:211], v[220:223], v[32:47]
	v_lshl_add_u64 v[208:209], v[66:67], 0, s[48:49]
	global_load_lds_dwordx4 v[208:209], off
	v_lshl_add_u64 v[208:209], v[64:65], 0, s[48:49]
	s_mov_b32 m0, s16
	v_readfirstlane_b32 s16, v172
	global_load_lds_dwordx4 v[208:209], off
	v_lshl_add_u64 v[208:209], v[68:69], 0, s[48:49]
	s_mov_b32 m0, s18
	v_mfma_f32_32x32x16_bf16 v[16:31], v[212:215], v[216:219], v[16:31]
	global_load_lds_dwordx4 v[208:209], off
	v_lshl_add_u64 v[208:209], v[70:71], 0, s[48:49]
	s_mov_b32 m0, s19
	v_readfirstlane_b32 s18, v174
	global_load_lds_dwordx4 v[208:209], off
	v_lshl_add_u64 v[208:209], v[74:75], 0, s[48:49]
	s_mov_b32 m0, s21
	v_mfma_f32_32x32x16_bf16 v[0:15], v[212:215], v[220:223], v[0:15]
	global_load_lds_dwordx4 v[208:209], off
	v_lshl_add_u64 v[208:209], v[72:73], 0, s[48:49]
	s_mov_b32 m0, s20
	v_readfirstlane_b32 s19, v154
	global_load_lds_dwordx4 v[208:209], off
	v_lshl_add_u64 v[208:209], v[76:77], 0, s[48:49]
	s_mov_b32 m0, s23
	v_readfirstlane_b32 s20, v151
	global_load_lds_dwordx4 v[208:209], off
	v_lshl_add_u64 v[208:209], v[78:79], 0, s[48:49]
	s_mov_b32 m0, s22
	v_readfirstlane_b32 s21, v160
	global_load_lds_dwordx4 v[208:209], off
	ds_read_b128 v[208:211], v149 offset:32768
	ds_read_b128 v[212:215], v149 offset:36864
	ds_read_b128 v[216:219], v150 offset:49152
	ds_read_b128 v[220:223], v150 offset:53248
	s_waitcnt lgkmcnt(0)
	v_mfma_f32_32x32x16_bf16 v[48:63], v[208:211], v[216:219], v[48:63]
	s_mov_b32 m0, s16
	v_readfirstlane_b32 s22, v159
	v_readfirstlane_b32 s23, v164
	v_mfma_f32_32x32x16_bf16 v[32:47], v[208:211], v[220:223], v[32:47]
	v_mfma_f32_32x32x16_bf16 v[16:31], v[212:215], v[216:219], v[16:31]
	v_mfma_f32_32x32x16_bf16 v[0:15], v[212:215], v[220:223], v[0:15]
	ds_read_b128 v[208:211], v152 offset:32768
	ds_read_b128 v[212:215], v152 offset:36864
	ds_read_b128 v[216:219], v153 offset:49152
	ds_read_b128 v[220:223], v153 offset:53248
	s_waitcnt lgkmcnt(0)
	v_mfma_f32_32x32x16_bf16 v[48:63], v[208:211], v[216:219], v[48:63]
	v_mfma_f32_32x32x16_bf16 v[32:47], v[208:211], v[220:223], v[32:47]
	v_mfma_f32_32x32x16_bf16 v[16:31], v[212:215], v[216:219], v[16:31]
	v_mfma_f32_32x32x16_bf16 v[0:15], v[212:215], v[220:223], v[0:15]
	ds_read_b128 v[208:211], v155 offset:32768
	ds_read_b128 v[212:215], v155 offset:36864
	ds_read_b128 v[216:219], v156 offset:49152
	ds_read_b128 v[220:223], v156 offset:53248
	s_waitcnt lgkmcnt(0)
	v_mfma_f32_32x32x16_bf16 v[48:63], v[208:211], v[216:219], v[48:63]
	v_mfma_f32_32x32x16_bf16 v[32:47], v[208:211], v[220:223], v[32:47]
	v_mfma_f32_32x32x16_bf16 v[16:31], v[212:215], v[216:219], v[16:31]
	v_mfma_f32_32x32x16_bf16 v[0:15], v[212:215], v[220:223], v[0:15]
	ds_read_b128 v[208:211], v157 offset:32768
	ds_read_b128 v[212:215], v157 offset:36864
	ds_read_b128 v[216:219], v158 offset:49152
	ds_read_b128 v[220:223], v158 offset:53248
	s_waitcnt vmcnt(0)
	s_waitcnt vmcnt(0) lgkmcnt(0)
	s_barrier
; #define WAIT_V0() asm volatile("s_waitcnt vmcnt(0)" ::: "memory")
; DI void gemm_core(char* smem, int nk, const char* Ab, const char* Bb, const unsigned (&aoff)[4], const unsigned (&boff)[4],
;                   f32x16 (&acc)[2][2]) {
;     ...
;   for (int kt = 0; kt < nk; ++kt) {
;     const int cur = kt & 1;
;     if (kt + 1 < nk) stage(cur ^ 1, kt + 1);
;     const char* sb = smem + cur * STAGE_B;
; #pragma unroll
;     for (int ks = 0; ks < 4; ++ks) {
;       bf16x8 af[2], bfr[2];
; #pragma unroll
;       for (int mb = 0; mb < 2; ++mb) af[mb] = *(const bf16x8*)(sb + a_base + mb * 4096 + xo[ks]);
; #pragma unroll
;       for (int nb = 0; nb < 2; ++nb) bfr[nb] = *(const bf16x8*)(sb + b_base + nb * 4096 + xo[ks]);
; #pragma unroll
;       for (int mb = 0; mb < 2; ++mb)
; #pragma unroll
;         for (int nb = 0; nb < 2; ++nb)
;           acc[mb][nb] = __builtin_amdgcn_mfma_f32_32x32x16_bf16(af[mb], bfr[nb], acc[mb][nb], 0, 0, 0);
;     }
;     WAIT_V0();
;     __syncthreads();
;   }
	v_mfma_f32_32x32x16_bf16 v[48:63], v[208:211], v[216:219], v[48:63]
	v_mfma_f32_32x32x16_bf16 v[32:47], v[208:211], v[220:223], v[32:47]
	v_lshl_add_u64 v[208:209], v[66:67], 0, s[50:51]
	global_load_lds_dwordx4 v[208:209], off
	v_lshl_add_u64 v[208:209], v[64:65], 0, s[50:51]
	s_mov_b32 m0, s17
	s_nop 0
	global_load_lds_dwordx4 v[208:209], off
	v_lshl_add_u64 v[208:209], v[68:69], 0, s[50:51]
	s_mov_b32 m0, s18
	v_mfma_f32_32x32x16_bf16 v[16:31], v[212:215], v[216:219], v[16:31]
	global_load_lds_dwordx4 v[208:209], off
	v_lshl_add_u64 v[208:209], v[70:71], 0, s[50:51]
	s_mov_b32 m0, s0
	s_nop 0
	global_load_lds_dwordx4 v[208:209], off
	v_lshl_add_u64 v[208:209], v[74:75], 0, s[50:51]
	s_mov_b32 m0, s1
	v_mfma_f32_32x32x16_bf16 v[0:15], v[212:215], v[220:223], v[0:15]
	global_load_lds_dwordx4 v[208:209], off
	v_lshl_add_u64 v[208:209], v[72:73], 0, s[50:51]
	s_mov_b32 m0, s10
	s_nop 0
	global_load_lds_dwordx4 v[208:209], off
	v_lshl_add_u64 v[208:209], v[76:77], 0, s[50:51]
	s_mov_b32 m0, s11
	s_nop 0
	global_load_lds_dwordx4 v[208:209], off
	v_lshl_add_u64 v[208:209], v[78:79], 0, s[50:51]
	s_mov_b32 m0, s15
	s_nop 0
	global_load_lds_dwordx4 v[208:209], off
	ds_read_b128 v[208:211], v149
	ds_read_b128 v[212:215], v149 offset:4096
	ds_read_b128 v[216:219], v150 offset:16384
	ds_read_b128 v[220:223], v150 offset:20480
	s_waitcnt lgkmcnt(0)
	v_mfma_f32_32x32x16_bf16 v[48:63], v[208:211], v[216:219], v[48:63]
	s_mov_b32 m0, s19
	v_mfma_f32_32x32x16_bf16 v[32:47], v[208:211], v[220:223], v[32:47]
	v_mfma_f32_32x32x16_bf16 v[16:31], v[212:215], v[216:219], v[16:31]
	v_mfma_f32_32x32x16_bf16 v[0:15], v[212:215], v[220:223], v[0:15]
	ds_read_b128 v[208:211], v152
	ds_read_b128 v[212:215], v152 offset:4096
	ds_read_b128 v[216:219], v153 offset:16384
	ds_read_b128 v[220:223], v153 offset:20480
	s_waitcnt lgkmcnt(0)
	v_mfma_f32_32x32x16_bf16 v[48:63], v[208:211], v[216:219], v[48:63]
	v_mfma_f32_32x32x16_bf16 v[32:47], v[208:211], v[220:223], v[32:47]
	v_mfma_f32_32x32x16_bf16 v[16:31], v[212:215], v[216:219], v[16:31]
	v_mfma_f32_32x32x16_bf16 v[0:15], v[212:215], v[220:223], v[0:15]
	ds_read_b128 v[208:211], v155
	ds_read_b128 v[212:215], v155 offset:4096
	ds_read_b128 v[216:219], v156 offset:16384
	ds_read_b128 v[220:223], v156 offset:20480
	s_waitcnt lgkmcnt(0)
	v_mfma_f32_32x32x16_bf16 v[48:63], v[208:211], v[216:219], v[48:63]
	v_mfma_f32_32x32x16_bf16 v[32:47], v[208:211], v[220:223], v[32:47]
	v_mfma_f32_32x32x16_bf16 v[16:31], v[212:215], v[216:219], v[16:31]
	v_mfma_f32_32x32x16_bf16 v[0:15], v[212:215], v[220:223], v[0:15]
	ds_read_b128 v[208:211], v157
	ds_read_b128 v[212:215], v157 offset:4096
	ds_read_b128 v[216:219], v158 offset:16384
	ds_read_b128 v[220:223], v158 offset:20480
	s_waitcnt vmcnt(0)
	s_waitcnt vmcnt(0) lgkmcnt(0)
	s_barrier
	v_mfma_f32_32x32x16_bf16 v[48:63], v[208:211], v[216:219], v[48:63]
	v_mfma_f32_32x32x16_bf16 v[32:47], v[208:211], v[220:223], v[32:47]
	v_lshl_add_u64 v[208:209], v[66:67], 0, s[52:53]
	global_load_lds_dwordx4 v[208:209], off
	v_lshl_add_u64 v[208:209], v[64:65], 0, s[52:53]
	s_mov_b32 m0, s20
	s_nop 0
	global_load_lds_dwordx4 v[208:209], off
	v_lshl_add_u64 v[208:209], v[68:69], 0, s[52:53]
	s_mov_b32 m0, s21
	v_mfma_f32_32x32x16_bf16 v[16:31], v[212:215], v[216:219], v[16:31]
	global_load_lds_dwordx4 v[208:209], off
	v_lshl_add_u64 v[208:209], v[70:71], 0, s[52:53]
	s_mov_b32 m0, s22
	s_nop 0
	global_load_lds_dwordx4 v[208:209], off
	v_lshl_add_u64 v[208:209], v[74:75], 0, s[52:53]
	s_mov_b32 m0, s23
	v_mfma_f32_32x32x16_bf16 v[0:15], v[212:215], v[220:223], v[0:15]
	global_load_lds_dwordx4 v[208:209], off
	v_lshl_add_u64 v[208:209], v[72:73], 0, s[52:53]
	s_mov_b32 m0, s28
	s_nop 0
	global_load_lds_dwordx4 v[208:209], off
	v_lshl_add_u64 v[208:209], v[76:77], 0, s[52:53]
	s_mov_b32 m0, s42
	s_nop 0
	global_load_lds_dwordx4 v[208:209], off
	v_lshl_add_u64 v[208:209], v[78:79], 0, s[52:53]
	s_mov_b32 m0, s29
	s_nop 0
	global_load_lds_dwordx4 v[208:209], off
	ds_read_b128 v[208:211], v149 offset:32768
	ds_read_b128 v[212:215], v149 offset:36864
	ds_read_b128 v[216:219], v150 offset:49152
	ds_read_b128 v[220:223], v150 offset:53248
	s_waitcnt lgkmcnt(0)
	v_mfma_f32_32x32x16_bf16 v[48:63], v[208:211], v[216:219], v[48:63]
	s_mov_b32 m0, s16
	v_mfma_f32_32x32x16_bf16 v[32:47], v[208:211], v[220:223], v[32:47]
	v_mfma_f32_32x32x16_bf16 v[16:31], v[212:215], v[216:219], v[16:31]
	v_mfma_f32_32x32x16_bf16 v[0:15], v[212:215], v[220:223], v[0:15]
	ds_read_b128 v[208:211], v152 offset:32768
	ds_read_b128 v[212:215], v152 offset:36864
	ds_read_b128 v[216:219], v153 offset:49152
	ds_read_b128 v[220:223], v153 offset:53248
	s_waitcnt lgkmcnt(0)
	v_mfma_f32_32x32x16_bf16 v[48:63], v[208:211], v[216:219], v[48:63]
	v_mfma_f32_32x32x16_bf16 v[32:47], v[208:211], v[220:223], v[32:47]
	v_mfma_f32_32x32x16_bf16 v[16:31], v[212:215], v[216:219], v[16:31]
	v_mfma_f32_32x32x16_bf16 v[0:15], v[212:215], v[220:223], v[0:15]
	ds_read_b128 v[208:211], v155 offset:32768
	ds_read_b128 v[212:215], v155 offset:36864
	ds_read_b128 v[216:219], v156 offset:49152
	ds_read_b128 v[220:223], v156 offset:53248
	s_waitcnt lgkmcnt(0)
	v_mfma_f32_32x32x16_bf16 v[48:63], v[208:211], v[216:219], v[48:63]
	v_mfma_f32_32x32x16_bf16 v[32:47], v[208:211], v[220:223], v[32:47]
	v_mfma_f32_32x32x16_bf16 v[16:31], v[212:215], v[216:219], v[16:31]
	v_mfma_f32_32x32x16_bf16 v[0:15], v[212:215], v[220:223], v[0:15]
	ds_read_b128 v[208:211], v157 offset:32768
	ds_read_b128 v[212:215], v157 offset:36864
	ds_read_b128 v[216:219], v158 offset:49152
	ds_read_b128 v[220:223], v158 offset:53248
	s_waitcnt vmcnt(0)
	s_waitcnt vmcnt(0) lgkmcnt(0)
	s_barrier
; #define WAIT_V0() asm volatile("s_waitcnt vmcnt(0)" ::: "memory")
; DI void gemm_core(char* smem, int nk, const char* Ab, const char* Bb, const unsigned (&aoff)[4], const unsigned (&boff)[4],
;                   f32x16 (&acc)[2][2]) {
;     ...
;   for (int kt = 0; kt < nk; ++kt) {
;     const int cur = kt & 1;
;     if (kt + 1 < nk) stage(cur ^ 1, kt + 1);
;     const char* sb = smem + cur * STAGE_B;
; #pragma unroll
;     for (int ks = 0; ks < 4; ++ks) {
;       bf16x8 af[2], bfr[2];
; #pragma unroll
;       for (int mb = 0; mb < 2; ++mb) af[mb] = *(const bf16x8*)(sb + a_base + mb * 4096 + xo[ks]);
; #pragma unroll
;       for (int nb = 0; nb < 2; ++nb) bfr[nb] = *(const bf16x8*)(sb + b_base + nb * 4096 + xo[ks]);
; #pragma unroll
;       for (int mb = 0; mb < 2; ++mb)
; #pragma unroll
;         for (int nb = 0; nb < 2; ++nb)
;           acc[mb][nb] = __builtin_amdgcn_mfma_f32_32x32x16_bf16(af[mb], bfr[nb], acc[mb][nb], 0, 0, 0);
;     }
;     WAIT_V0();
;     __syncthreads();
;   }
	v_mfma_f32_32x32x16_bf16 v[48:63], v[208:211], v[216:219], v[48:63]
	v_mfma_f32_32x32x16_bf16 v[32:47], v[208:211], v[220:223], v[32:47]
	v_lshl_add_u64 v[208:209], v[66:67], 0, s[54:55]
	global_load_lds_dwordx4 v[208:209], off
	v_lshl_add_u64 v[208:209], v[64:65], 0, s[54:55]
	s_mov_b32 m0, s17
	s_nop 0
	global_load_lds_dwordx4 v[208:209], off
	v_lshl_add_u64 v[208:209], v[68:69], 0, s[54:55]
	s_mov_b32 m0, s18
	v_mfma_f32_32x32x16_bf16 v[16:31], v[212:215], v[216:219], v[16:31]
	global_load_lds_dwordx4 v[208:209], off
	v_lshl_add_u64 v[208:209], v[70:71], 0, s[54:55]
	s_mov_b32 m0, s0
	s_nop 0
	global_load_lds_dwordx4 v[208:209], off
	v_lshl_add_u64 v[208:209], v[74:75], 0, s[54:55]
	s_mov_b32 m0, s1
	v_mfma_f32_32x32x16_bf16 v[0:15], v[212:215], v[220:223], v[0:15]
	global_load_lds_dwordx4 v[208:209], off
	v_lshl_add_u64 v[208:209], v[72:73], 0, s[54:55]
	s_mov_b32 m0, s10
	s_nop 0
	global_load_lds_dwordx4 v[208:209], off
	v_lshl_add_u64 v[208:209], v[76:77], 0, s[54:55]
	s_mov_b32 m0, s11
	s_nop 0
	global_load_lds_dwordx4 v[208:209], off
	v_lshl_add_u64 v[208:209], v[78:79], 0, s[54:55]
	s_mov_b32 m0, s15
	s_nop 0
	global_load_lds_dwordx4 v[208:209], off
	ds_read_b128 v[208:211], v149
	ds_read_b128 v[212:215], v149 offset:4096
	ds_read_b128 v[216:219], v150 offset:16384
	ds_read_b128 v[220:223], v150 offset:20480
	s_waitcnt lgkmcnt(0)
	v_mfma_f32_32x32x16_bf16 v[48:63], v[208:211], v[216:219], v[48:63]
	s_mov_b32 m0, s19
	v_mfma_f32_32x32x16_bf16 v[32:47], v[208:211], v[220:223], v[32:47]
	v_mfma_f32_32x32x16_bf16 v[16:31], v[212:215], v[216:219], v[16:31]
	v_mfma_f32_32x32x16_bf16 v[0:15], v[212:215], v[220:223], v[0:15]
	ds_read_b128 v[208:211], v152
	ds_read_b128 v[212:215], v152 offset:4096
	ds_read_b128 v[216:219], v153 offset:16384
	ds_read_b128 v[220:223], v153 offset:20480
	s_waitcnt lgkmcnt(0)
	v_mfma_f32_32x32x16_bf16 v[48:63], v[208:211], v[216:219], v[48:63]
	v_mfma_f32_32x32x16_bf16 v[32:47], v[208:211], v[220:223], v[32:47]
	v_mfma_f32_32x32x16_bf16 v[16:31], v[212:215], v[216:219], v[16:31]
	v_mfma_f32_32x32x16_bf16 v[0:15], v[212:215], v[220:223], v[0:15]
	ds_read_b128 v[208:211], v155
	ds_read_b128 v[212:215], v155 offset:4096
	ds_read_b128 v[216:219], v156 offset:16384
	ds_read_b128 v[220:223], v156 offset:20480
	s_waitcnt lgkmcnt(0)
	v_mfma_f32_32x32x16_bf16 v[48:63], v[208:211], v[216:219], v[48:63]
	v_mfma_f32_32x32x16_bf16 v[32:47], v[208:211], v[220:223], v[32:47]
	v_mfma_f32_32x32x16_bf16 v[16:31], v[212:215], v[216:219], v[16:31]
	v_mfma_f32_32x32x16_bf16 v[0:15], v[212:215], v[220:223], v[0:15]
	ds_read_b128 v[208:211], v157
	ds_read_b128 v[212:215], v157 offset:4096
	ds_read_b128 v[216:219], v158 offset:16384
	ds_read_b128 v[220:223], v158 offset:20480
	s_waitcnt vmcnt(0)
	s_waitcnt vmcnt(0) lgkmcnt(0)
	s_barrier
	v_mfma_f32_32x32x16_bf16 v[48:63], v[208:211], v[216:219], v[48:63]
	v_mfma_f32_32x32x16_bf16 v[32:47], v[208:211], v[220:223], v[32:47]
	v_lshl_add_u64 v[208:209], v[66:67], 0, s[56:57]
	global_load_lds_dwordx4 v[208:209], off
	v_lshl_add_u64 v[208:209], v[64:65], 0, s[56:57]
	s_mov_b32 m0, s20
	s_nop 0
	global_load_lds_dwordx4 v[208:209], off
	v_lshl_add_u64 v[208:209], v[68:69], 0, s[56:57]
	s_mov_b32 m0, s21
	v_mfma_f32_32x32x16_bf16 v[16:31], v[212:215], v[216:219], v[16:31]
	global_load_lds_dwordx4 v[208:209], off
	v_lshl_add_u64 v[208:209], v[70:71], 0, s[56:57]
	s_mov_b32 m0, s22
	s_nop 0
	global_load_lds_dwordx4 v[208:209], off
	v_lshl_add_u64 v[208:209], v[74:75], 0, s[56:57]
	s_mov_b32 m0, s23
	v_mfma_f32_32x32x16_bf16 v[0:15], v[212:215], v[220:223], v[0:15]
	global_load_lds_dwordx4 v[208:209], off
	v_lshl_add_u64 v[208:209], v[72:73], 0, s[56:57]
	s_mov_b32 m0, s28
	s_nop 0
	global_load_lds_dwordx4 v[208:209], off
	v_lshl_add_u64 v[208:209], v[76:77], 0, s[56:57]
	s_mov_b32 m0, s42
	s_nop 0
	global_load_lds_dwordx4 v[208:209], off
	v_lshl_add_u64 v[208:209], v[78:79], 0, s[56:57]
	s_mov_b32 m0, s29
	s_nop 0
	global_load_lds_dwordx4 v[208:209], off
	ds_read_b128 v[208:211], v149 offset:32768
	ds_read_b128 v[212:215], v149 offset:36864
	ds_read_b128 v[216:219], v150 offset:49152
	ds_read_b128 v[220:223], v150 offset:53248
	s_waitcnt lgkmcnt(0)
	v_mfma_f32_32x32x16_bf16 v[48:63], v[208:211], v[216:219], v[48:63]
	s_mov_b32 m0, s16
	v_mfma_f32_32x32x16_bf16 v[32:47], v[208:211], v[220:223], v[32:47]
	v_mfma_f32_32x32x16_bf16 v[16:31], v[212:215], v[216:219], v[16:31]
	v_mfma_f32_32x32x16_bf16 v[0:15], v[212:215], v[220:223], v[0:15]
	ds_read_b128 v[208:211], v152 offset:32768
	ds_read_b128 v[212:215], v152 offset:36864
	ds_read_b128 v[216:219], v153 offset:49152
	ds_read_b128 v[220:223], v153 offset:53248
	s_waitcnt lgkmcnt(0)
	v_mfma_f32_32x32x16_bf16 v[48:63], v[208:211], v[216:219], v[48:63]
	v_mfma_f32_32x32x16_bf16 v[32:47], v[208:211], v[220:223], v[32:47]
	v_mfma_f32_32x32x16_bf16 v[16:31], v[212:215], v[216:219], v[16:31]
	v_mfma_f32_32x32x16_bf16 v[0:15], v[212:215], v[220:223], v[0:15]
	ds_read_b128 v[208:211], v155 offset:32768
	ds_read_b128 v[212:215], v155 offset:36864
	ds_read_b128 v[216:219], v156 offset:49152
	ds_read_b128 v[220:223], v156 offset:53248
	s_waitcnt lgkmcnt(0)
	v_mfma_f32_32x32x16_bf16 v[48:63], v[208:211], v[216:219], v[48:63]
	v_mfma_f32_32x32x16_bf16 v[32:47], v[208:211], v[220:223], v[32:47]
	v_mfma_f32_32x32x16_bf16 v[16:31], v[212:215], v[216:219], v[16:31]
	v_mfma_f32_32x32x16_bf16 v[0:15], v[212:215], v[220:223], v[0:15]
	ds_read_b128 v[208:211], v157 offset:32768
	ds_read_b128 v[212:215], v157 offset:36864
	ds_read_b128 v[216:219], v158 offset:49152
	ds_read_b128 v[220:223], v158 offset:53248
	s_waitcnt vmcnt(0)
	s_waitcnt vmcnt(0) lgkmcnt(0)
	s_barrier
; #define WAIT_V0() asm volatile("s_waitcnt vmcnt(0)" ::: "memory")
; DI void gemm_core(char* smem, int nk, const char* Ab, const char* Bb, const unsigned (&aoff)[4], const unsigned (&boff)[4],
;                   f32x16 (&acc)[2][2]) {
;     ...
;   for (int kt = 0; kt < nk; ++kt) {
;     const int cur = kt & 1;
;     if (kt + 1 < nk) stage(cur ^ 1, kt + 1);
;     const char* sb = smem + cur * STAGE_B;
; #pragma unroll
;     for (int ks = 0; ks < 4; ++ks) {
;       bf16x8 af[2], bfr[2];
; #pragma unroll
;       for (int mb = 0; mb < 2; ++mb) af[mb] = *(const bf16x8*)(sb + a_base + mb * 4096 + xo[ks]);
; #pragma unroll
;       for (int nb = 0; nb < 2; ++nb) bfr[nb] = *(const bf16x8*)(sb + b_base + nb * 4096 + xo[ks]);
; #pragma unroll
;       for (int mb = 0; mb < 2; ++mb)
; #pragma unroll
;         for (int nb = 0; nb < 2; ++nb)
;           acc[mb][nb] = __builtin_amdgcn_mfma_f32_32x32x16_bf16(af[mb], bfr[nb], acc[mb][nb], 0, 0, 0);
;     }
;     WAIT_V0();
;     __syncthreads();
;   }
	v_mfma_f32_32x32x16_bf16 v[48:63], v[208:211], v[216:219], v[48:63]
	v_mfma_f32_32x32x16_bf16 v[32:47], v[208:211], v[220:223], v[32:47]
	v_lshl_add_u64 v[208:209], v[66:67], 0, s[58:59]
	global_load_lds_dwordx4 v[208:209], off
	v_lshl_add_u64 v[208:209], v[64:65], 0, s[58:59]
	s_mov_b32 m0, s17
	s_nop 0
	global_load_lds_dwordx4 v[208:209], off
	v_lshl_add_u64 v[208:209], v[68:69], 0, s[58:59]
	s_mov_b32 m0, s18
	v_mfma_f32_32x32x16_bf16 v[16:31], v[212:215], v[216:219], v[16:31]
	global_load_lds_dwordx4 v[208:209], off
	v_lshl_add_u64 v[208:209], v[70:71], 0, s[58:59]
	s_mov_b32 m0, s0
	s_nop 0
	global_load_lds_dwordx4 v[208:209], off
	v_lshl_add_u64 v[208:209], v[74:75], 0, s[58:59]
	s_mov_b32 m0, s1
	v_mfma_f32_32x32x16_bf16 v[0:15], v[212:215], v[220:223], v[0:15]
	global_load_lds_dwordx4 v[208:209], off
	v_lshl_add_u64 v[208:209], v[72:73], 0, s[58:59]
	s_mov_b32 m0, s10
	s_nop 0
	global_load_lds_dwordx4 v[208:209], off
	v_lshl_add_u64 v[208:209], v[76:77], 0, s[58:59]
	s_mov_b32 m0, s11
	s_nop 0
	global_load_lds_dwordx4 v[208:209], off
	v_lshl_add_u64 v[208:209], v[78:79], 0, s[58:59]
	s_mov_b32 m0, s15
	s_nop 0
	global_load_lds_dwordx4 v[208:209], off
	ds_read_b128 v[208:211], v149
	ds_read_b128 v[212:215], v149 offset:4096
	ds_read_b128 v[216:219], v150 offset:16384
	ds_read_b128 v[220:223], v150 offset:20480
	s_waitcnt lgkmcnt(0)
	v_mfma_f32_32x32x16_bf16 v[48:63], v[208:211], v[216:219], v[48:63]
	s_mov_b32 m0, s19
	v_mfma_f32_32x32x16_bf16 v[32:47], v[208:211], v[220:223], v[32:47]
	v_mfma_f32_32x32x16_bf16 v[16:31], v[212:215], v[216:219], v[16:31]
	v_mfma_f32_32x32x16_bf16 v[0:15], v[212:215], v[220:223], v[0:15]
	ds_read_b128 v[208:211], v152
	ds_read_b128 v[212:215], v152 offset:4096
	ds_read_b128 v[216:219], v153 offset:16384
	ds_read_b128 v[220:223], v153 offset:20480
	s_waitcnt lgkmcnt(0)
	v_mfma_f32_32x32x16_bf16 v[48:63], v[208:211], v[216:219], v[48:63]
	v_mfma_f32_32x32x16_bf16 v[32:47], v[208:211], v[220:223], v[32:47]
	v_mfma_f32_32x32x16_bf16 v[16:31], v[212:215], v[216:219], v[16:31]
	v_mfma_f32_32x32x16_bf16 v[0:15], v[212:215], v[220:223], v[0:15]
	ds_read_b128 v[208:211], v155
	ds_read_b128 v[212:215], v155 offset:4096
	ds_read_b128 v[216:219], v156 offset:16384
	ds_read_b128 v[220:223], v156 offset:20480
	s_waitcnt lgkmcnt(0)
	v_mfma_f32_32x32x16_bf16 v[48:63], v[208:211], v[216:219], v[48:63]
	v_mfma_f32_32x32x16_bf16 v[32:47], v[208:211], v[220:223], v[32:47]
	v_mfma_f32_32x32x16_bf16 v[16:31], v[212:215], v[216:219], v[16:31]
	v_mfma_f32_32x32x16_bf16 v[0:15], v[212:215], v[220:223], v[0:15]
	ds_read_b128 v[208:211], v157
	ds_read_b128 v[212:215], v157 offset:4096
	ds_read_b128 v[216:219], v158 offset:16384
	ds_read_b128 v[220:223], v158 offset:20480
	s_waitcnt vmcnt(0)
	s_waitcnt vmcnt(0) lgkmcnt(0)
	s_barrier
	v_mfma_f32_32x32x16_bf16 v[48:63], v[208:211], v[216:219], v[48:63]
	v_mfma_f32_32x32x16_bf16 v[32:47], v[208:211], v[220:223], v[32:47]
	v_lshl_add_u64 v[208:209], v[66:67], 0, s[60:61]
	global_load_lds_dwordx4 v[208:209], off
	v_lshl_add_u64 v[208:209], v[64:65], 0, s[60:61]
	s_mov_b32 m0, s20
	v_lshl_add_u64 v[66:67], v[66:67], 0, s[62:63]
	global_load_lds_dwordx4 v[208:209], off
	v_lshl_add_u64 v[208:209], v[68:69], 0, s[60:61]
	s_mov_b32 m0, s21
	v_mfma_f32_32x32x16_bf16 v[16:31], v[212:215], v[216:219], v[16:31]
	global_load_lds_dwordx4 v[208:209], off
	v_lshl_add_u64 v[208:209], v[70:71], 0, s[60:61]
	s_mov_b32 m0, s22
	v_lshl_add_u64 v[64:65], v[64:65], 0, s[62:63]
	global_load_lds_dwordx4 v[208:209], off
	v_lshl_add_u64 v[208:209], v[74:75], 0, s[60:61]
	s_mov_b32 m0, s23
	v_mfma_f32_32x32x16_bf16 v[0:15], v[212:215], v[220:223], v[0:15]
	global_load_lds_dwordx4 v[208:209], off
	v_lshl_add_u64 v[208:209], v[72:73], 0, s[60:61]
	s_mov_b32 m0, s28
	s_movk_i32 s20, 0x3000
	global_load_lds_dwordx4 v[208:209], off
	v_lshl_add_u64 v[208:209], v[76:77], 0, s[60:61]
	s_mov_b32 m0, s42
	s_mov_b32 s21, 0x9000
	global_load_lds_dwordx4 v[208:209], off
	v_lshl_add_u64 v[208:209], v[78:79], 0, s[60:61]
	s_mov_b32 m0, s29
	s_mov_b32 s22, 0xa000
	global_load_lds_dwordx4 v[208:209], off
	ds_read_b128 v[208:211], v149 offset:32768
	ds_read_b128 v[212:215], v149 offset:36864
	ds_read_b128 v[216:219], v150 offset:49152
	ds_read_b128 v[220:223], v150 offset:53248
	s_waitcnt lgkmcnt(0)
	v_mfma_f32_32x32x16_bf16 v[48:63], v[208:211], v[216:219], v[48:63]
	s_mov_b32 m0, s16
	s_movk_i32 s16, 0x2000
	s_mov_b32 s23, 0xb000
	s_mov_b32 s28, 0x10000
	s_mov_b32 s29, 0x11000
	s_mov_b32 s42, 0x12000
	v_mfma_f32_32x32x16_bf16 v[32:47], v[208:211], v[220:223], v[32:47]
	v_mfma_f32_32x32x16_bf16 v[16:31], v[212:215], v[216:219], v[16:31]
	v_mfma_f32_32x32x16_bf16 v[0:15], v[212:215], v[220:223], v[0:15]
	ds_read_b128 v[208:211], v152 offset:32768
	ds_read_b128 v[212:215], v152 offset:36864
	ds_read_b128 v[216:219], v153 offset:49152
	ds_read_b128 v[220:223], v153 offset:53248
	s_waitcnt lgkmcnt(0)
	v_mfma_f32_32x32x16_bf16 v[48:63], v[208:211], v[216:219], v[48:63]
	v_mfma_f32_32x32x16_bf16 v[32:47], v[208:211], v[220:223], v[32:47]
	v_mfma_f32_32x32x16_bf16 v[16:31], v[212:215], v[216:219], v[16:31]
	v_mfma_f32_32x32x16_bf16 v[0:15], v[212:215], v[220:223], v[0:15]
	ds_read_b128 v[208:211], v155 offset:32768
	ds_read_b128 v[212:215], v155 offset:36864
	ds_read_b128 v[216:219], v156 offset:49152
	ds_read_b128 v[220:223], v156 offset:53248
	s_waitcnt lgkmcnt(0)
	v_mfma_f32_32x32x16_bf16 v[48:63], v[208:211], v[216:219], v[48:63]
	v_mfma_f32_32x32x16_bf16 v[32:47], v[208:211], v[220:223], v[32:47]
	v_mfma_f32_32x32x16_bf16 v[16:31], v[212:215], v[216:219], v[16:31]
	v_mfma_f32_32x32x16_bf16 v[0:15], v[212:215], v[220:223], v[0:15]
	ds_read_b128 v[208:211], v157 offset:32768
	ds_read_b128 v[212:215], v157 offset:36864
	ds_read_b128 v[216:219], v158 offset:49152
	ds_read_b128 v[220:223], v158 offset:53248
	s_waitcnt vmcnt(0)
	s_waitcnt vmcnt(0) lgkmcnt(0)
	s_barrier
; #define WAIT_V0() asm volatile("s_waitcnt vmcnt(0)" ::: "memory")
; DI void gemm_core(char* smem, int nk, const char* Ab, const char* Bb, const unsigned (&aoff)[4], const unsigned (&boff)[4],
;                   f32x16 (&acc)[2][2]) {
;     ...
;   for (int kt = 0; kt < nk; ++kt) {
;     const int cur = kt & 1;
;     if (kt + 1 < nk) stage(cur ^ 1, kt + 1);
;     const char* sb = smem + cur * STAGE_B;
; #pragma unroll
;     for (int ks = 0; ks < 4; ++ks) {
;       bf16x8 af[2], bfr[2];
; #pragma unroll
;       for (int mb = 0; mb < 2; ++mb) af[mb] = *(const bf16x8*)(sb + a_base + mb * 4096 + xo[ks]);
; #pragma unroll
;       for (int nb = 0; nb < 2; ++nb) bfr[nb] = *(const bf16x8*)(sb + b_base + nb * 4096 + xo[ks]);
; #pragma unroll
;       for (int mb = 0; mb < 2; ++mb)
; #pragma unroll
;         for (int nb = 0; nb < 2; ++nb)
;           acc[mb][nb] = __builtin_amdgcn_mfma_f32_32x32x16_bf16(af[mb], bfr[nb], acc[mb][nb], 0, 0, 0);
;     }
;     WAIT_V0();
;     __syncthreads();
;   }
	global_load_lds_dwordx4 v[66:67], off
	s_mov_b32 m0, s17
	v_mfma_f32_32x32x16_bf16 v[48:63], v[208:211], v[216:219], v[48:63]
	global_load_lds_dwordx4 v[64:65], off
	v_lshl_add_u64 v[64:65], v[68:69], 0, s[62:63]
	s_mov_b32 m0, s18
	s_movk_i32 s17, 0x1000
	global_load_lds_dwordx4 v[64:65], off
	v_lshl_add_u64 v[64:65], v[70:71], 0, s[62:63]
	s_mov_b32 m0, s0
	v_mfma_f32_32x32x16_bf16 v[32:47], v[208:211], v[220:223], v[32:47]
	global_load_lds_dwordx4 v[64:65], off
	v_lshl_add_u64 v[64:65], v[74:75], 0, s[62:63]
	s_mov_b32 m0, s1
	s_mov_b32 s0, 0x13000
	global_load_lds_dwordx4 v[64:65], off
	v_lshl_add_u64 v[64:65], v[72:73], 0, s[62:63]
	s_mov_b32 m0, s10
	v_mfma_f32_32x32x16_bf16 v[16:31], v[212:215], v[216:219], v[16:31]
	global_load_lds_dwordx4 v[64:65], off
	v_lshl_add_u64 v[64:65], v[76:77], 0, s[62:63]
	s_mov_b32 m0, s11
	s_mov_b32 s1, 0x18000
	global_load_lds_dwordx4 v[64:65], off
	v_lshl_add_u64 v[64:65], v[78:79], 0, s[62:63]
	s_mov_b32 m0, s15
	v_mfma_f32_32x32x16_bf16 v[0:15], v[212:215], v[220:223], v[0:15]
	global_load_lds_dwordx4 v[64:65], off
	ds_read_b128 v[64:67], v149
	ds_read_b128 v[68:71], v149 offset:4096
	ds_read_b128 v[72:75], v150 offset:16384
	ds_read_b128 v[76:79], v150 offset:20480
	s_mov_b32 s10, 0x1b000
	v_readlane_b32 s18, v255, 3
	v_readlane_b32 s19, v255, 4
	s_waitcnt lgkmcnt(0)
	v_mfma_f32_32x32x16_bf16 v[48:63], v[64:67], v[72:75], v[48:63]
	v_mfma_f32_32x32x16_bf16 v[32:47], v[64:67], v[76:79], v[32:47]
	v_mfma_f32_32x32x16_bf16 v[16:31], v[68:71], v[72:75], v[16:31]
	v_mfma_f32_32x32x16_bf16 v[0:15], v[68:71], v[76:79], v[0:15]
	ds_read_b128 v[64:67], v152
	ds_read_b128 v[68:71], v152 offset:4096
	ds_read_b128 v[72:75], v153 offset:16384
	ds_read_b128 v[76:79], v153 offset:20480
	s_waitcnt lgkmcnt(0)
	v_mfma_f32_32x32x16_bf16 v[48:63], v[64:67], v[72:75], v[48:63]
	v_mfma_f32_32x32x16_bf16 v[32:47], v[64:67], v[76:79], v[32:47]
	v_mfma_f32_32x32x16_bf16 v[16:31], v[68:71], v[72:75], v[16:31]
	v_mfma_f32_32x32x16_bf16 v[0:15], v[68:71], v[76:79], v[0:15]
	ds_read_b128 v[64:67], v155
	ds_read_b128 v[68:71], v155 offset:4096
	ds_read_b128 v[72:75], v156 offset:16384
	ds_read_b128 v[76:79], v156 offset:20480
	s_waitcnt lgkmcnt(0)
	v_mfma_f32_32x32x16_bf16 v[48:63], v[64:67], v[72:75], v[48:63]
	v_mfma_f32_32x32x16_bf16 v[32:47], v[64:67], v[76:79], v[32:47]
	v_mfma_f32_32x32x16_bf16 v[16:31], v[68:71], v[72:75], v[16:31]
	v_mfma_f32_32x32x16_bf16 v[0:15], v[68:71], v[76:79], v[0:15]
	ds_read_b128 v[64:67], v157
	ds_read_b128 v[68:71], v157 offset:4096
	ds_read_b128 v[72:75], v158 offset:16384
	ds_read_b128 v[76:79], v158 offset:20480
	s_waitcnt vmcnt(0)
	s_waitcnt vmcnt(0) lgkmcnt(0)
	s_barrier
	v_mfma_f32_32x32x16_bf16 v[48:63], v[64:67], v[72:75], v[48:63]
	v_mfma_f32_32x32x16_bf16 v[32:47], v[64:67], v[76:79], v[32:47]
	v_mfma_f32_32x32x16_bf16 v[16:31], v[68:71], v[72:75], v[16:31]
	v_mfma_f32_32x32x16_bf16 v[0:15], v[68:71], v[76:79], v[0:15]
	ds_read_b128 v[64:67], v149 offset:32768
	ds_read_b128 v[68:71], v149 offset:36864
	ds_read_b128 v[72:75], v150 offset:49152
	ds_read_b128 v[76:79], v150 offset:53248
	s_waitcnt lgkmcnt(1)
	v_mfma_f32_32x32x16_bf16 v[48:63], v[64:67], v[72:75], v[48:63]
	s_waitcnt lgkmcnt(0)
	v_mfma_f32_32x32x16_bf16 v[32:47], v[64:67], v[76:79], v[32:47]
	v_mfma_f32_32x32x16_bf16 v[16:31], v[68:71], v[72:75], v[16:31]
	v_mfma_f32_32x32x16_bf16 v[0:15], v[68:71], v[76:79], v[0:15]
	ds_read_b128 v[64:67], v152 offset:32768
	ds_read_b128 v[68:71], v152 offset:36864
	ds_read_b128 v[72:75], v153 offset:49152
	ds_read_b128 v[76:79], v153 offset:53248
	s_waitcnt lgkmcnt(1)
	v_mfma_f32_32x32x16_bf16 v[48:63], v[64:67], v[72:75], v[48:63]
	s_waitcnt lgkmcnt(0)
	v_mfma_f32_32x32x16_bf16 v[32:47], v[64:67], v[76:79], v[32:47]
	v_mfma_f32_32x32x16_bf16 v[16:31], v[68:71], v[72:75], v[16:31]
	v_mfma_f32_32x32x16_bf16 v[0:15], v[68:71], v[76:79], v[0:15]
	ds_read_b128 v[64:67], v155 offset:32768
	ds_read_b128 v[68:71], v155 offset:36864
	ds_read_b128 v[72:75], v156 offset:49152
	ds_read_b128 v[76:79], v156 offset:53248
	s_waitcnt lgkmcnt(1)
	v_mfma_f32_32x32x16_bf16 v[48:63], v[64:67], v[72:75], v[48:63]
	s_waitcnt lgkmcnt(0)
	v_mfma_f32_32x32x16_bf16 v[32:47], v[64:67], v[76:79], v[32:47]
	v_mfma_f32_32x32x16_bf16 v[16:31], v[68:71], v[72:75], v[16:31]
	v_mfma_f32_32x32x16_bf16 v[0:15], v[68:71], v[76:79], v[0:15]
	ds_read_b128 v[64:67], v157 offset:32768
	ds_read_b128 v[68:71], v157 offset:36864
	ds_read_b128 v[72:75], v158 offset:49152
	ds_read_b128 v[76:79], v158 offset:53248
	s_waitcnt vmcnt(0)
	s_waitcnt lgkmcnt(0)
	s_barrier
; template <class T> DI T* uoff(T* base, unsigned byteoff) { return (T*)((char*)base + byteoff); }
; template <class T> DI const T* uoff(const T* base, unsigned byteoff) { return (const T*)((const char*)base + byteoff); }
; DI void phase_out(const Params& P, int layer, const float* xin, char* smem) {
;     ...
; #pragma unroll
;     for (int mb = 0; mb < 2; ++mb)
; #pragma unroll
;       for (int nb = 0; nb < 2; ++nb)
; #pragma unroll
;         for (int r = 0; r < 16; ++r)
;           (*uoff(P.out + ((mb * 32 + (r & 3) + 8 * (r >> 2)) * 1024 + nb * 32), obase_b)) = xr[mb][nb][r] + acc[mb][nb][r];
	v_mfma_f32_32x32x16_bf16 v[48:63], v[64:67], v[72:75], v[48:63]
	v_mfma_f32_32x32x16_bf16 v[32:47], v[64:67], v[76:79], v[32:47]
	v_lshl_add_u64 v[64:65], s[82:83], 0, v[136:137]
	s_nop 9
	v_add_f32_e32 v48, v147, v48
	global_store_dword v136, v48, s[82:83]
	v_add_co_u32_e32 v48, vcc, s17, v64
	v_add_f32_e32 v50, v145, v50
	v_add_f32_e32 v52, v144, v52
	v_mfma_f32_32x32x16_bf16 v[16:31], v[68:71], v[72:75], v[16:31]
	v_add_f32_e32 v54, v143, v54
	v_add_f32_e32 v56, v141, v56
	v_add_f32_e32 v32, v129, v32
	global_store_dword v136, v32, s[82:83] offset:128
	v_add_f32_e32 v32, v128, v33
	v_add_f32_e32 v58, v139, v58
	v_add_f32_e32 v60, v134, v60
	v_mfma_f32_32x32x16_bf16 v[0:15], v[68:71], v[76:79], v[0:15]
	v_add_f32_e32 v68, v148, v49
	v_addc_co_u32_e32 v49, vcc, 0, v65, vcc
	v_add_co_u32_e32 v66, vcc, s16, v64
	global_store_dword v[48:49], v32, off offset:128
	s_nop 0
	v_addc_co_u32_e32 v67, vcc, 0, v65, vcc
	global_store_dword v[66:67], v50, off
	v_add_co_u32_e32 v50, vcc, s20, v64
	global_store_dword v[66:67], v68, off offset:-4096
	v_add_f32_e32 v68, v146, v51
	v_addc_co_u32_e32 v51, vcc, 0, v65, vcc
	global_store_dword v[50:51], v68, off
	v_add_co_u32_e32 v68, vcc, s9, v64
	v_add_f32_e32 v32, v127, v34
	s_nop 0
	v_addc_co_u32_e32 v69, vcc, 0, v65, vcc
	v_add_co_u32_e32 v70, vcc, s21, v64
	global_store_dword v[66:67], v32, off offset:128
	s_nop 0
	v_addc_co_u32_e32 v71, vcc, 0, v65, vcc
	global_store_dword v[70:71], v52, off offset:-4096
	v_add_f32_e32 v52, v142, v53
	global_store_dword v[70:71], v52, off
	v_add_co_u32_e32 v52, vcc, s22, v64
	v_add_f32_e32 v32, v126, v35
	s_nop 0
	v_addc_co_u32_e32 v53, vcc, 0, v65, vcc
	v_add_co_u32_e32 v72, vcc, s23, v64
	global_store_dword v[50:51], v32, off offset:128
	s_nop 0
	v_addc_co_u32_e32 v73, vcc, 0, v65, vcc
	global_store_dword v[72:73], v54, off offset:-4096
	v_add_f32_e32 v54, v140, v55
	global_store_dword v[72:73], v54, off
	v_add_co_u32_e32 v54, vcc, s28, v64
	v_add_f32_e32 v32, v125, v36
	s_nop 0
	v_addc_co_u32_e32 v55, vcc, 0, v65, vcc
	v_add_co_u32_e32 v74, vcc, s29, v64
	global_store_dword v[68:69], v32, off offset:128
	s_nop 0
	v_addc_co_u32_e32 v75, vcc, 0, v65, vcc
	global_store_dword v[74:75], v56, off offset:-4096
	v_add_f32_e32 v56, v135, v57
	global_store_dword v[74:75], v56, off
	v_add_co_u32_e32 v56, vcc, s42, v64
	v_add_f32_e32 v32, v124, v37
	s_nop 0
	v_addc_co_u32_e32 v57, vcc, 0, v65, vcc
	v_add_co_u32_e32 v76, vcc, s0, v64
	global_store_dword v[70:71], v32, off offset:128
	s_nop 0
	v_addc_co_u32_e32 v77, vcc, 0, v65, vcc
	global_store_dword v[76:77], v58, off offset:-4096
	v_add_f32_e32 v58, v133, v59
	v_add_f32_e32 v32, v123, v38
	global_store_dword v[76:77], v58, off
	v_add_co_u32_e32 v58, vcc, s1, v64
	global_store_dword v[52:53], v32, off offset:128
	v_add_f32_e32 v32, v122, v39
	v_addc_co_u32_e32 v59, vcc, 0, v65, vcc
	global_store_dword v[72:73], v32, off offset:128
	v_add_f32_e32 v32, v121, v40
	v_add_co_u32_e32 v78, vcc, s2, v64
	global_store_dword v[54:55], v32, off offset:128
	v_add_f32_e32 v32, v120, v41
	v_addc_co_u32_e32 v79, vcc, 0, v65, vcc
	global_store_dword v[74:75], v32, off offset:128
	v_add_f32_e32 v32, v119, v42
	global_store_dword v[78:79], v60, off offset:-4096
	v_add_f32_e32 v60, v131, v61
	global_store_dword v[56:57], v32, off offset:128
	v_add_f32_e32 v32, v117, v43
	global_store_dword v[78:79], v60, off
	v_add_co_u32_e32 v60, vcc, s68, v64
	global_store_dword v[76:77], v32, off offset:128
	v_add_f32_e32 v32, v116, v44
	v_addc_co_u32_e32 v61, vcc, 0, v65, vcc
	global_store_dword v[58:59], v32, off offset:128
	v_add_f32_e32 v32, v115, v45
	v_add_f32_e32 v62, v132, v62
	v_add_co_u32_e32 v132, vcc, s10, v64
	global_store_dword v[78:79], v32, off offset:128
	v_add_f32_e32 v32, v114, v46
	v_addc_co_u32_e32 v133, vcc, 0, v65, vcc
	global_store_dword v[60:61], v32, off offset:128
	v_add_f32_e32 v32, v113, v47
	global_store_dword v[132:133], v32, off offset:128
	v_add_co_u32_e32 v32, vcc, s3, v64
	s_mov_b32 s0, 0x21000
	s_nop 0
; template <class T> DI T* uoff(T* base, unsigned byteoff) { return (T*)((char*)base + byteoff); }
; template <class T> DI const T* uoff(const T* base, unsigned byteoff) { return (const T*)((const char*)base + byteoff); }
; DI void phase_out(const Params& P, int layer, const float* xin, char* smem) {
;     ...
; #pragma unroll
;     for (int mb = 0; mb < 2; ++mb)
; #pragma unroll
;       for (int nb = 0; nb < 2; ++nb)
; #pragma unroll
;         for (int r = 0; r < 16; ++r)
;           (*uoff(P.out + ((mb * 32 + (r & 3) + 8 * (r >> 2)) * 1024 + nb * 32), obase_b)) = xr[mb][nb][r] + acc[mb][nb][r];
;   }
	v_addc_co_u32_e32 v33, vcc, 0, v65, vcc
	v_add_co_u32_e32 v34, vcc, s0, v64
	v_add_f32_e32 v16, v118, v16
	s_nop 0
	v_addc_co_u32_e32 v35, vcc, 0, v65, vcc
	global_store_dword v[34:35], v16, off offset:-4096
	v_add_f32_e32 v16, v111, v17
	global_store_dword v[34:35], v16, off
	v_add_co_u32_e32 v16, vcc, s6, v64
	s_mov_b32 s1, 0x23000
	s_nop 0
	v_addc_co_u32_e32 v17, vcc, 0, v65, vcc
	v_add_co_u32_e32 v36, vcc, s1, v64
	v_add_f32_e32 v18, v112, v18
	s_nop 0
	v_addc_co_u32_e32 v37, vcc, 0, v65, vcc
	s_mov_b32 s2, 0x28000
	global_store_dword v[36:37], v18, off offset:-4096
	v_add_f32_e32 v18, v109, v19
	global_store_dword v[36:37], v18, off
	v_add_co_u32_e32 v18, vcc, s2, v64
	v_add_f32_e32 v20, v110, v20
	s_nop 0
	v_addc_co_u32_e32 v19, vcc, 0, v65, vcc
	v_add_co_u32_e32 v38, vcc, s8, v64
	s_mov_b32 s3, 0x2a000
	s_nop 0
	v_addc_co_u32_e32 v39, vcc, 0, v65, vcc
	global_store_dword v[38:39], v20, off offset:-4096
	v_add_f32_e32 v20, v107, v21
	global_store_dword v[38:39], v20, off
	v_add_co_u32_e32 v20, vcc, s3, v64
	v_add_f32_e32 v22, v108, v22
	s_nop 0
	v_addc_co_u32_e32 v21, vcc, 0, v65, vcc
	v_add_co_u32_e32 v40, vcc, s64, v64
	s_mov_b32 s0, 0x30000
	s_nop 0
	v_addc_co_u32_e32 v41, vcc, 0, v65, vcc
	global_store_dword v[40:41], v22, off offset:-4096
	v_add_f32_e32 v22, v105, v23
	global_store_dword v[40:41], v22, off
	v_add_co_u32_e32 v22, vcc, s0, v64
	v_add_f32_e32 v24, v106, v24
	s_nop 0
	v_addc_co_u32_e32 v23, vcc, 0, v65, vcc
	v_add_co_u32_e32 v42, vcc, s65, v64
	s_mov_b32 s1, 0x32000
	s_nop 0
	v_addc_co_u32_e32 v43, vcc, 0, v65, vcc
	global_store_dword v[42:43], v24, off offset:-4096
	v_add_f32_e32 v24, v103, v25
	v_add_f32_e32 v0, v97, v0
	global_store_dword v[42:43], v24, off
	v_add_co_u32_e32 v24, vcc, s1, v64
	global_store_dword v[32:33], v0, off offset:128
	v_add_f32_e32 v0, v96, v1
	v_addc_co_u32_e32 v25, vcc, 0, v65, vcc
	global_store_dword v[34:35], v0, off offset:128
	v_add_f32_e32 v0, v95, v2
	v_add_co_u32_e32 v44, vcc, s66, v64
	global_store_dword v[16:17], v0, off offset:128
	v_add_f32_e32 v0, v94, v3
	v_add_f32_e32 v26, v104, v26
	v_addc_co_u32_e32 v45, vcc, 0, v65, vcc
	global_store_dword v[36:37], v0, off offset:128
	v_add_f32_e32 v0, v93, v4
	s_mov_b32 s2, 0x38000
	global_store_dword v[44:45], v26, off offset:-4096
	v_add_f32_e32 v26, v101, v27
	global_store_dword v[18:19], v0, off offset:128
	v_add_f32_e32 v0, v92, v5
	global_store_dword v[44:45], v26, off
	v_add_co_u32_e32 v26, vcc, s2, v64
	global_store_dword v[38:39], v0, off offset:128
	v_add_f32_e32 v0, v91, v6
	v_addc_co_u32_e32 v27, vcc, 0, v65, vcc
	global_store_dword v[20:21], v0, off offset:128
	v_add_f32_e32 v0, v90, v7
	v_add_co_u32_e32 v46, vcc, s67, v64
	global_store_dword v[40:41], v0, off offset:128
	v_add_f32_e32 v0, v89, v8
	v_add_f32_e32 v28, v102, v28
	v_addc_co_u32_e32 v47, vcc, 0, v65, vcc
	global_store_dword v[22:23], v0, off offset:128
	v_add_f32_e32 v0, v88, v9
	global_store_dword v[46:47], v28, off offset:-4096
	v_add_f32_e32 v28, v99, v29
	global_store_dword v[42:43], v0, off offset:128
	v_add_f32_e32 v0, v87, v10
	global_store_dword v[46:47], v28, off
	v_add_co_u32_e32 v28, vcc, s69, v64
	global_store_dword v[24:25], v0, off offset:128
	v_add_f32_e32 v0, v86, v11
	v_addc_co_u32_e32 v29, vcc, 0, v65, vcc
	global_store_dword v[44:45], v0, off offset:128
	v_add_f32_e32 v0, v85, v12
	v_add_co_u32_e32 v48, vcc, s71, v64
	global_store_dword v[26:27], v0, off offset:128
	v_add_f32_e32 v0, v84, v13
	v_add_f32_e32 v30, v100, v30
	v_addc_co_u32_e32 v49, vcc, 0, v65, vcc
	global_store_dword v[46:47], v0, off offset:128
	v_add_f32_e32 v0, v83, v14
	global_store_dword v[132:133], v62, off offset:-4096
	v_add_f32_e32 v62, v130, v63
	global_store_dword v[48:49], v30, off offset:-4096
	v_add_f32_e32 v30, v98, v31
	global_store_dword v[28:29], v0, off offset:128
	v_add_f32_e32 v0, v82, v15
	global_store_dword v[132:133], v62, off
	global_store_dword v[48:49], v30, off
	global_store_dword v[48:49], v0, off offset:128
	s_cbranch_scc0 .LBB0_43

; DI float bflo(unsigned u) { return __uint_as_float(u << 16); }
; DI float bfhi(unsigned u) { return __uint_as_float(u & 0xffff0000u); }
; DI void phase_token_c(const Params& P, int layer, char* smem) {
;     ...
;     unsigned short* qr = QB + (size_t)t * 768;
; #pragma unroll
;     for (int i = 0; i < 3; ++i) {
;       const u32x2 u = *(const u32x2*)(qr + (lane + 64 * i) * 4);
;       float4 f = {bflo(u.x), bfhi(u.x), bflo(u.y), bfhi(u.y)};
;       *(float4*)(rowbuf + (lane + 64 * i) * 4) = f;
;     }
;     if (lane < 16) {
;       const float inv = powf(10000.f, -(float)lane / 16.f);
;       const float ang = (float)(t % S_) * inv;
;       float sn, cs;
;       sincosf(ang, &sn, &cs);
;       rowbuf[768 + lane] = cs; rowbuf[784 + lane] = sn;
.LBB0_190:
	v_readlane_b32 s0, v252, 51
	v_readlane_b32 s1, v252, 52
	v_ashrrev_i32_e32 v17, 31, v16
	s_nop 0
	v_mov_b64_e32 v[0:1], s[0:1]
	s_movk_i32 s0, 0x600
	v_mad_i64_i32 v[0:1], s[0:1], v16, s0, v[0:1]
	v_lshl_add_u64 v[2:3], v[0:1], 0, v[136:137]
	global_load_dwordx2 v[20:21], v[2:3], off
	global_load_dwordx2 v[22:23], v[2:3], off offset:512
	global_load_dwordx2 v[2:3], v[2:3], off offset:1024
	s_waitcnt vmcnt(2)
	v_lshlrev_b32_e32 v60, 16, v20
	v_and_b32_e32 v61, 0xffff0000, v20
	v_lshlrev_b32_e32 v62, 16, v21
	v_and_b32_e32 v63, 0xffff0000, v21
	ds_write_b128 v46, v[60:63]
	s_waitcnt vmcnt(1)
	v_lshlrev_b32_e32 v64, 16, v22
	v_and_b32_e32 v65, 0xffff0000, v22
	v_lshlrev_b32_e32 v66, 16, v23
	v_and_b32_e32 v67, 0xffff0000, v23
	ds_write_b128 v46, v[64:67] offset:1024
	s_waitcnt vmcnt(0)
	v_lshlrev_b32_e32 v18, 16, v2
	v_and_b32_e32 v19, 0xffff0000, v2
	v_lshlrev_b32_e32 v20, 16, v3
	v_and_b32_e32 v21, 0xffff0000, v3
	ds_write_b128 v46, v[18:21] offset:2048
	s_and_saveexec_b64 s[10:11], vcc
	s_cbranch_execz .LBB0_196
	v_lshrrev_b32_e32 v2, 18, v17
	v_add_u32_e32 v2, v16, v2
	v_and_b32_e32 v2, 0xffffc000, v2
	v_sub_u32_e32 v2, v16, v2
	v_cvt_f32_i32_e32 v2, v2
	s_brev_b32 s0, 18
	v_mul_f32_e32 v2, v5, v2
	v_and_b32_e32 v3, 0x7fffffff, v2
	v_cmp_nlt_f32_e64 s[0:1], |v2|, s0
	s_and_saveexec_b64 s[12:13], s[0:1]
	s_xor_b64 s[12:13], exec, s[12:13]
	s_cbranch_execz .LBB0_193
	v_lshrrev_b32_e32 v18, 23, v3
	v_add_u32_e32 v18, 0xffffff88, v18
	v_cmp_lt_u32_e64 s[0:1], 63, v18
	s_mov_b32 s3, 0xfe5163ab
	v_mov_b32_e32 v21, v137
	v_cndmask_b32_e64 v19, 0, v167, s[0:1]
	v_add_u32_e32 v18, v19, v18
	v_cmp_lt_u32_e64 s[54:55], 31, v18
	v_mov_b32_e32 v23, v137
	v_mov_b32_e32 v25, v137
	v_cndmask_b32_e64 v19, 0, v197, s[54:55]
	v_add_u32_e32 v18, v19, v18
	v_cmp_lt_u32_e64 s[56:57], 31, v18
	v_mov_b32_e32 v27, v137
	v_mov_b32_e32 v61, v137
	v_cndmask_b32_e64 v19, 0, v197, s[56:57]
	v_add_u32_e32 v59, v19, v18
	v_and_b32_e32 v18, 0x7fffff, v3
	v_or_b32_e32 v64, 0x800000, v18
	v_mad_u64_u32 v[18:19], s[14:15], v64, s3, 0
	v_mov_b32_e32 v20, v19
	s_mov_b32 s3, 0x3c439041
	v_mad_u64_u32 v[20:21], s[14:15], v64, s3, v[20:21]
	v_mov_b32_e32 v22, v21
	s_mov_b32 s3, 0xdb629599
	v_mad_u64_u32 v[22:23], s[14:15], v64, s3, v[22:23]
	v_mov_b32_e32 v24, v23
	s_mov_b32 s3, 0xf534ddc0
	v_mad_u64_u32 v[24:25], s[14:15], v64, s3, v[24:25]
	v_mov_b32_e32 v26, v25
	s_mov_b32 s3, 0xfc2757d1
	v_mad_u64_u32 v[26:27], s[14:15], v64, s3, v[26:27]
	v_mov_b32_e32 v60, v27
	s_mov_b32 s3, 0x4e441529
	v_mad_u64_u32 v[60:61], s[14:15], v64, s3, v[60:61]
	v_mov_b32_e32 v62, v61
	v_mov_b32_e32 v63, v137
	s_mov_b32 s3, 0xa2f9836e
	v_mad_u64_u32 v[62:63], s[14:15], v64, s3, v[62:63]
	v_cndmask_b32_e64 v19, v60, v24, s[0:1]
	v_cndmask_b32_e64 v21, v62, v26, s[0:1]
	v_cndmask_b32_e64 v25, v63, v60, s[0:1]
	v_cndmask_b32_e64 v23, v21, v19, s[54:55]
	v_cndmask_b32_e64 v21, v25, v21, s[54:55]
	v_cndmask_b32_e64 v25, v26, v22, s[0:1]
	v_cndmask_b32_e64 v19, v19, v25, s[54:55]
	v_cndmask_b32_e64 v20, v24, v20, s[0:1]
	v_cndmask_b32_e64 v21, v21, v23, s[56:57]
	v_cndmask_b32_e64 v23, v23, v19, s[56:57]
	v_sub_u32_e32 v26, 32, v59
	v_cndmask_b32_e64 v24, v25, v20, s[54:55]
	v_alignbit_b32 v27, v21, v23, v26
	v_cmp_eq_u32_e64 s[58:59], 0, v59
	v_cndmask_b32_e64 v19, v19, v24, s[56:57]
	v_alignbit_b32 v25, v23, v19, v26
	v_cndmask_b32_e64 v21, v27, v21, s[58:59]
	v_cndmask_b32_e64 v18, v22, v18, s[0:1]
	v_cndmask_b32_e64 v23, v25, v23, s[58:59]
	v_bfe_u32 v59, v21, 29, 1
	v_cndmask_b32_e64 v18, v20, v18, s[54:55]
	v_alignbit_b32 v25, v21, v23, 30
	v_sub_u32_e32 v60, 0, v59
	v_cndmask_b32_e64 v18, v24, v18, s[56:57]
	v_xor_b32_e32 v25, v25, v60
	v_alignbit_b32 v20, v19, v18, v26
	v_cndmask_b32_e64 v19, v20, v19, s[58:59]
	v_ffbh_u32_e32 v22, v25
	v_alignbit_b32 v20, v23, v19, 30
	v_min_u32_e32 v22, 32, v22
	v_alignbit_b32 v18, v19, v18, 30
	v_xor_b32_e32 v20, v20, v60
	v_sub_u32_e32 v23, 31, v22
	v_xor_b32_e32 v18, v18, v60
	v_alignbit_b32 v24, v25, v20, v23
	v_alignbit_b32 v18, v20, v18, v23
	v_alignbit_b32 v19, v24, v18, 9
	v_ffbh_u32_e32 v20, v19
	v_min_u32_e32 v20, 32, v20
	v_lshrrev_b32_e32 v27, 29, v21
	v_not_b32_e32 v23, v20
	v_alignbit_b32 v18, v19, v18, v23
	v_lshlrev_b32_e32 v19, 31, v27
	v_or_b32_e32 v23, 0x33000000, v19
	v_add_lshl_u32 v20, v20, v22, 23
	v_lshrrev_b32_e32 v18, 9, v18
	v_sub_u32_e32 v20, v23, v20
	v_or_b32_e32 v19, 0.5, v19
	v_lshlrev_b32_e32 v22, 23, v22
	v_or_b32_e32 v18, v20, v18
	v_lshrrev_b32_e32 v20, 9, v24
	v_sub_u32_e32 v19, v19, v22
	v_or_b32_e32 v19, v20, v19
	v_mul_f32_e32 v20, 0x3fc90fda, v19
	s_mov_b32 s0, 0x3fc90fda
	v_fma_f32 v22, v19, s0, -v20
	v_fmac_f32_e32 v22, 0x33a22168, v19
	v_fmac_f32_e32 v22, 0x3fc90fda, v18
	v_lshrrev_b32_e32 v19, 30, v21
	v_add_f32_e32 v18, v20, v22
	v_add_u32_e32 v19, v59, v19

; DI int glds_row(int i) { const int tid = ltid(); return ((tid >> 6) * 4 + i) * 8 + ((tid & 63) >> 3); }
; DI int glds_chunk(int row) { return (ltid() & 7) ^ ((row >> 1) & 7); }
; DI void gemm_tile(char* smem, int nk, const bf16* A, int lda, int m0, const bf16* Bt, int ldb, int n0, f32x16 (&acc)[2][2]) {
;   unsigned aoff[4], boff[4];
; #pragma unroll
;   for (int i = 0; i < 4; ++i) {
;     const int row = glds_row(i), ch = glds_chunk(row);
;     aoff[i] = (unsigned)((row * lda + ch * 8) * 2);
;     boff[i] = (unsigned)((row * ldb + ch * 8) * 2);
;   }
;   gemm_core(smem, nk, (const char*)(A + (size_t)m0 * lda), (const char*)(Bt + (size_t)n0 * ldb), aoff, boff, acc);
; DI void phase_gemm_in(const Params& P, int layer, char* smem) {
;     ...
;   for (int t0 = blockIdx.x; t0 < NT * MT; t0 += gridDim.x) {
;     const int tl = xcd_tile(t0, NT * MT) - (t0 & 7) * ((NT * MT) >> 3);
;     const int m0 = ((t0 & 3) * 64 + tl / 11) * 128, n0 = (((t0 & 7) >> 2) * 11 + tl % 11) * 128;
;     f32x16 acc[2][2];
;     gemm_tile(smem, 16, hn, 1024, m0, wt, 1024, n0, acc);
.LBB0_436:
	v_mov_b32_e32 v0, v161
	s_ashr_i32 s0, s14, 3
	v_lshrrev_b32_e32 v1, 1, v0
	v_lshrrev_b32_e32 v2, 3, v0
	v_bfe_u32 v0, v0, 3, 3
	v_and_or_b32 v0, v1, s9, v0
	v_mov_b32_e32 v1, v161
	v_bfe_u32 v2, v2, 1, 2
	v_xor_b32_e32 v1, v2, v1
	v_lshlrev_b32_e32 v0, 11, v0
	v_lshlrev_b32_e32 v1, 4, v1
	v_and_or_b32 v136, v1, s92, v0
	v_mov_b32_e32 v0, v161
	s_and_b32 s1, s0, 0xffffffc0
	v_ashrrev_i32_e32 v1, 1, v0
	v_and_b32_e32 v1, 0xffffffe0, v1
	v_bfe_u32 v0, v0, 3, 3
	v_or3_b32 v0, v0, v1, 8
	v_mov_b32_e32 v1, v161
	v_lshrrev_b32_e32 v2, 1, v0
	v_xor_b32_e32 v1, v2, v1
	v_lshlrev_b32_e32 v0, 11, v0
	v_lshlrev_b32_e32 v1, 4, v1
	v_and_or_b32 v0, v1, s92, v0
	v_mov_b32_e32 v1, v161
	s_lshl_b32 s10, s0, 1
	v_lshrrev_b32_e32 v2, 1, v1
	v_lshrrev_b32_e32 v3, 3, v1
	v_bfe_u32 v1, v1, 3, 3
	v_and_or_b32 v1, v2, s9, v1
	v_mov_b32_e32 v2, v161
	s_bfe_u32 s11, s0, 0x10005
	v_bfe_u32 v3, v3, 1, 2
	s_and_b32 s10, s10, 62
	s_or_b32 s1, s11, s1
	v_xor_b32_e32 v2, v3, v2
	s_or_b32 s1, s1, s10
	s_or_b32 s10, s0, 63
	v_lshlrev_b32_e32 v2, 4, v2
	s_cmpk_lt_i32 s10, 0x2c0
	v_lshlrev_b32_e32 v1, 11, v1
	v_and_b32_e32 v2, 0x70, v2
	s_cselect_b32 s1, s1, s0
	v_or3_b32 v2, v1, v2, s8
	v_mov_b32_e32 v1, v161
	s_mul_hi_i32 s10, s1, 0x2e8ba2e9
	s_lshr_b32 s11, s10, 31
	v_ashrrev_i32_e32 v3, 1, v1
	s_ashr_i32 s10, s10, 1
	v_and_b32_e32 v3, 0xffffffe0, v3
	v_bfe_u32 v1, v1, 3, 3
	s_and_b32 s0, s13, 0xc0
	s_add_i32 s10, s10, s11
	v_or3_b32 v1, v1, v3, 24
	v_mov_b32_e32 v3, v161
	s_add_i32 s15, s10, s0
	s_bfe_i32 s11, s14, 0x10002
	s_mul_i32 s10, s10, 11
	v_lshrrev_b32_e32 v4, 1, v1
	s_and_b32 s11, s11, 11
	s_sub_i32 s1, s1, s10
	v_xor_b32_e32 v3, v4, v3
	s_lshl_b32 s0, s15, 7
	s_add_i32 s1, s1, s11
	v_lshlrev_b32_e32 v1, 11, v1
	v_lshlrev_b32_e32 v3, 4, v3
	v_mov_b32_e32 v12, v161
	s_lshl_b32 s10, s1, 7
	v_and_or_b32 v4, v3, s92, v1
	s_ashr_i32 s1, s0, 31
	s_lshl_b64 s[16:17], s[0:1], 11
	v_and_b32_e32 v1, 31, v12
	v_lshrrev_b32_e32 v5, 1, v12
	v_and_or_b32 v1, v5, s6, v1
	s_add_u32 s16, s84, s16
	v_lshlrev_b32_e32 v112, 7, v1
	v_lshlrev_b32_e32 v1, 6, v12
	s_addc_u32 s17, s85, s17
	s_ashr_i32 s11, s10, 31
	v_and_b32_e32 v89, 0xfffff000, v1
	s_lshl_b64 s[18:19], s[10:11], 11
	v_add_u32_e32 v88, 0x4000, v89
	v_readfirstlane_b32 s20, v89
	s_add_u32 s18, s2, s18
	s_mov_b32 m0, s20
	v_readfirstlane_b32 s21, v88
	v_or_b32_e32 v90, 0x400, v89
	s_addc_u32 s19, s12, s19
	global_load_lds_dwordx4 v136, s[16:17]
	s_mov_b32 m0, s21
	v_readfirstlane_b32 s22, v90
	v_add_u32_e32 v91, 0x4400, v89
	global_load_lds_dwordx4 v136, s[18:19]
	s_mov_b32 m0, s22
	v_readfirstlane_b32 s23, v91
	v_or_b32_e32 v92, 0x800, v89
	global_load_lds_dwordx4 v0, s[16:17]
	s_mov_b32 m0, s23
	v_readfirstlane_b32 s28, v92
	v_add_u32_e32 v93, 0x4800, v89
	global_load_lds_dwordx4 v0, s[18:19]
	s_mov_b32 m0, s28
	v_readfirstlane_b32 s29, v93
	v_or_b32_e32 v94, 0xc00, v89
	global_load_lds_dwordx4 v2, s[16:17]
	s_mov_b32 m0, s29
	v_readfirstlane_b32 s40, v94
	v_add_u32_e32 v95, 0x4c00, v89
	v_lshrrev_b32_e32 v3, 5, v12
	v_bfe_u32 v99, v12, 1, 3
	global_load_lds_dwordx4 v2, s[18:19]
	s_mov_b32 m0, s40
	v_readfirstlane_b32 s41, v95
	v_add_u32_e32 v97, 0x8000, v89
	v_bitop3_b32 v3, v3, v99, 1 bitop3:0x6c
	v_lshl_add_u64 v[64:65], s[16:17], 0, v[136:137]
	v_mov_b32_e32 v1, v137
	global_load_lds_dwordx4 v4, s[16:17]
	s_mov_b32 m0, s41
	v_add_u32_e32 v96, 0xc000, v89
	v_readfirstlane_b32 s42, v97
	v_lshlrev_b32_e32 v6, 4, v3
	v_lshl_add_u64 v[66:67], s[18:19], 0, v[136:137]
	v_lshl_add_u64 v[68:69], s[16:17], 0, v[0:1]
	v_lshl_add_u64 v[70:71], s[18:19], 0, v[0:1]
	v_mov_b32_e32 v3, v137
	global_load_lds_dwordx4 v4, s[18:19]
	v_lshl_add_u64 v[0:1], v[64:65], 0, s[94:95]
	s_mov_b32 m0, s42
	v_readfirstlane_b32 s43, v96
	v_add_u32_e32 v98, 0x8400, v89
	v_lshl_add_u64 v[72:73], s[16:17], 0, v[2:3]
	v_lshl_add_u64 v[74:75], s[18:19], 0, v[2:3]
	global_load_lds_dwordx4 v[0:1], off
	v_lshl_add_u64 v[0:1], v[66:67], 0, s[94:95]
	s_mov_b32 m0, s43
	v_readfirstlane_b32 s44, v98
	v_add_u32_e32 v2, 0xc400, v89
	v_mov_b32_e32 v5, v137
	global_load_lds_dwordx4 v[0:1], off
	v_lshl_add_u64 v[0:1], v[68:69], 0, s[94:95]
	s_mov_b32 m0, s44
	v_readfirstlane_b32 s1, v2
	v_add_u32_e32 v2, 0x8800, v89
	v_lshl_add_u64 v[76:77], s[16:17], 0, v[4:5]
	global_load_lds_dwordx4 v[0:1], off
	v_lshl_add_u64 v[0:1], v[70:71], 0, s[94:95]
	s_mov_b32 m0, s1
	v_readfirstlane_b32 s16, v2
	v_add_u32_e32 v2, 0xc800, v89
	global_load_lds_dwordx4 v[0:1], off
	v_lshl_add_u64 v[0:1], v[72:73], 0, s[94:95]
	s_mov_b32 m0, s16
	v_readfirstlane_b32 s17, v2
	v_add_u32_e32 v2, 0x8c00, v89
	v_lshl_add_u64 v[78:79], s[18:19], 0, v[4:5]
	global_load_lds_dwordx4 v[0:1], off
	v_lshl_add_u64 v[0:1], v[74:75], 0, s[94:95]
	s_mov_b32 m0, s17
	v_readfirstlane_b32 s18, v2
	v_add_u32_e32 v2, 0xcc00, v89
	global_load_lds_dwordx4 v[0:1], off
	v_lshl_add_u64 v[0:1], v[76:77], 0, s[94:95]
	s_mov_b32 m0, s18
	v_readfirstlane_b32 s19, v2
	global_load_lds_dwordx4 v[0:1], off
	v_lshl_add_u64 v[0:1], v[78:79], 0, s[94:95]
	s_mov_b32 m0, s19
	v_or_b32_e32 v80, v112, v6
	global_load_lds_dwordx4 v[0:1], off
	s_waitcnt vmcnt(8)
	s_waitcnt vmcnt(8) lgkmcnt(0)
	s_barrier
; #define WAIT_V0() asm volatile("s_waitcnt vmcnt(0)" ::: "memory")
; DI void gemm_core(char* smem, int nk, const char* Ab, const char* Bb, const unsigned (&aoff)[4], const unsigned (&boff)[4],
;                   f32x16 (&acc)[2][2]) {
;     ...
;   for (int kt = 0; kt < nk; ++kt) {
;     const int cur = kt & 1;
;     if (kt + 1 < nk) stage(cur ^ 1, kt + 1);
;     const char* sb = smem + cur * STAGE_B;
; #pragma unroll
;     for (int ks = 0; ks < 4; ++ks) {
;       bf16x8 af[2], bfr[2];
; #pragma unroll
;       for (int mb = 0; mb < 2; ++mb) af[mb] = *(const bf16x8*)(sb + a_base + mb * 4096 + xo[ks]);
; #pragma unroll
;       for (int nb = 0; nb < 2; ++nb) bfr[nb] = *(const bf16x8*)(sb + b_base + nb * 4096 + xo[ks]);
; #pragma unroll
;       for (int mb = 0; mb < 2; ++mb)
; #pragma unroll
;         for (int nb = 0; nb < 2; ++nb)
;           acc[mb][nb] = __builtin_amdgcn_mfma_f32_32x32x16_bf16(af[mb], bfr[nb], acc[mb][nb], 0, 0, 0);
;     }
;     WAIT_V0();
;     __syncthreads();
;   }
	ds_read_b128 v[0:3], v80
	v_lshlrev_b32_e32 v4, 7, v12
	v_and_b32_e32 v113, 0x2f80, v4
	v_or_b32_e32 v82, v113, v6
	ds_read_b128 v[4:7], v82 offset:16384
	ds_read_b128 v[8:11], v82 offset:20480
	s_waitcnt lgkmcnt(0)
	v_mfma_f32_32x32x16_bf16 v[48:63], v[0:3], v[4:7], 0
	v_bfe_u32 v114, v12, 5, 1
	s_mov_b32 m0, s20
	v_mfma_f32_32x32x16_bf16 v[32:47], v[0:3], v[8:11], 0
	ds_read_b128 v[0:3], v80 offset:4096
	s_waitcnt lgkmcnt(0)
	v_mfma_f32_32x32x16_bf16 v[16:31], v[0:3], v[4:7], 0
	v_bitop3_b32 v4, v114, v99, 2 bitop3:0x36
	v_lshlrev_b32_e32 v83, 4, v4
	v_or_b32_e32 v81, v112, v83
	ds_read_b128 v[84:87], v81
	v_or_b32_e32 v83, v113, v83
	ds_read_b128 v[100:103], v83 offset:16384
	ds_read_b128 v[104:107], v83 offset:20480
	s_waitcnt lgkmcnt(0)
	v_mfma_f32_32x32x16_bf16 v[48:63], v[84:87], v[100:103], v[48:63]
	v_mfma_f32_32x32x16_bf16 v[32:47], v[84:87], v[104:107], v[32:47]
	ds_read_b128 v[84:87], v81 offset:4096
	v_mfma_f32_32x32x16_bf16 v[0:15], v[0:3], v[8:11], 0
	s_waitcnt lgkmcnt(0)
	v_mfma_f32_32x32x16_bf16 v[16:31], v[84:87], v[100:103], v[16:31]
	v_bitop3_b32 v100, v114, v99, 4 bitop3:0x36
	v_lshlrev_b32_e32 v108, 4, v100
	v_mfma_f32_32x32x16_bf16 v[0:15], v[84:87], v[104:107], v[0:15]
	v_or_b32_e32 v84, v112, v108
	ds_read_b128 v[100:103], v84
	v_or_b32_e32 v85, v113, v108
	ds_read_b128 v[104:107], v85 offset:16384
	ds_read_b128 v[108:111], v85 offset:20480
	v_bitop3_b32 v86, v114, v99, 6 bitop3:0x36
	v_lshlrev_b32_e32 v87, 4, v86
	s_waitcnt lgkmcnt(0)
	v_mfma_f32_32x32x16_bf16 v[48:63], v[100:103], v[104:107], v[48:63]
	v_or_b32_e32 v86, v112, v87
	v_or_b32_e32 v87, v113, v87
	v_mfma_f32_32x32x16_bf16 v[32:47], v[100:103], v[108:111], v[32:47]
	ds_read_b128 v[100:103], v84 offset:4096
	s_waitcnt lgkmcnt(0)
	v_mfma_f32_32x32x16_bf16 v[16:31], v[100:103], v[104:107], v[16:31]
	ds_read_b128 v[104:107], v87 offset:16384
	v_mfma_f32_32x32x16_bf16 v[0:15], v[100:103], v[108:111], v[0:15]
	ds_read_b128 v[100:103], v86
	ds_read_b128 v[108:111], v87 offset:20480
	s_waitcnt lgkmcnt(0)
	v_mfma_f32_32x32x16_bf16 v[48:63], v[100:103], v[104:107], v[48:63]
	v_mfma_f32_32x32x16_bf16 v[32:47], v[100:103], v[108:111], v[32:47]
	ds_read_b128 v[100:103], v86 offset:4096
	s_waitcnt vmcnt(0)
	s_waitcnt vmcnt(0) lgkmcnt(0)
	s_barrier
	v_mfma_f32_32x32x16_bf16 v[16:31], v[100:103], v[104:107], v[16:31]
	v_mfma_f32_32x32x16_bf16 v[0:15], v[100:103], v[108:111], v[0:15]
	v_lshl_add_u64 v[100:101], v[64:65], 0, s[36:37]
	global_load_lds_dwordx4 v[100:101], off
	v_lshl_add_u64 v[100:101], v[66:67], 0, s[36:37]
	s_mov_b32 m0, s21
	s_nop 0
	global_load_lds_dwordx4 v[100:101], off
	v_lshl_add_u64 v[100:101], v[68:69], 0, s[36:37]
	s_mov_b32 m0, s22
	s_nop 0
	global_load_lds_dwordx4 v[100:101], off
	v_lshl_add_u64 v[100:101], v[70:71], 0, s[36:37]
	s_mov_b32 m0, s23
	s_nop 0
	global_load_lds_dwordx4 v[100:101], off
	v_lshl_add_u64 v[100:101], v[72:73], 0, s[36:37]
	s_mov_b32 m0, s28
	s_nop 0
	global_load_lds_dwordx4 v[100:101], off
	v_lshl_add_u64 v[100:101], v[74:75], 0, s[36:37]
	s_mov_b32 m0, s29
	s_nop 0
	global_load_lds_dwordx4 v[100:101], off
	v_lshl_add_u64 v[100:101], v[76:77], 0, s[36:37]
	s_mov_b32 m0, s40
	s_nop 0
	global_load_lds_dwordx4 v[100:101], off
	v_lshl_add_u64 v[100:101], v[78:79], 0, s[36:37]
	s_mov_b32 m0, s41
	s_nop 0
	global_load_lds_dwordx4 v[100:101], off
	ds_read_b128 v[100:103], v80 offset:32768
	ds_read_b128 v[104:107], v82 offset:49152
	ds_read_b128 v[108:111], v82 offset:53248
	s_waitcnt lgkmcnt(0)
	v_mfma_f32_32x32x16_bf16 v[48:63], v[100:103], v[104:107], v[48:63]
	s_mov_b32 m0, s42
	v_mfma_f32_32x32x16_bf16 v[32:47], v[100:103], v[108:111], v[32:47]
	ds_read_b128 v[100:103], v80 offset:36864
	s_waitcnt lgkmcnt(0)
	v_mfma_f32_32x32x16_bf16 v[16:31], v[100:103], v[104:107], v[16:31]
	v_mfma_f32_32x32x16_bf16 v[0:15], v[100:103], v[108:111], v[0:15]
	ds_read_b128 v[100:103], v81 offset:32768
	ds_read_b128 v[104:107], v83 offset:49152
	ds_read_b128 v[108:111], v83 offset:53248
	s_waitcnt lgkmcnt(0)
	v_mfma_f32_32x32x16_bf16 v[48:63], v[100:103], v[104:107], v[48:63]
	v_mfma_f32_32x32x16_bf16 v[32:47], v[100:103], v[108:111], v[32:47]
	ds_read_b128 v[100:103], v81 offset:36864
	s_waitcnt lgkmcnt(0)
	v_mfma_f32_32x32x16_bf16 v[16:31], v[100:103], v[104:107], v[16:31]
	v_mfma_f32_32x32x16_bf16 v[0:15], v[100:103], v[108:111], v[0:15]
	ds_read_b128 v[100:103], v84 offset:32768
	ds_read_b128 v[104:107], v85 offset:49152
	ds_read_b128 v[108:111], v85 offset:53248
	s_waitcnt lgkmcnt(0)
	v_mfma_f32_32x32x16_bf16 v[48:63], v[100:103], v[104:107], v[48:63]
	v_mfma_f32_32x32x16_bf16 v[32:47], v[100:103], v[108:111], v[32:47]
	ds_read_b128 v[100:103], v84 offset:36864
	s_waitcnt lgkmcnt(0)
	v_mfma_f32_32x32x16_bf16 v[16:31], v[100:103], v[104:107], v[16:31]
	v_mfma_f32_32x32x16_bf16 v[0:15], v[100:103], v[108:111], v[0:15]
	ds_read_b128 v[100:103], v86 offset:32768
	ds_read_b128 v[104:107], v87 offset:49152
	ds_read_b128 v[108:111], v87 offset:53248
	s_waitcnt lgkmcnt(0)
	v_mfma_f32_32x32x16_bf16 v[48:63], v[100:103], v[104:107], v[48:63]
	v_mfma_f32_32x32x16_bf16 v[32:47], v[100:103], v[108:111], v[32:47]
	ds_read_b128 v[100:103], v86 offset:36864
	s_waitcnt vmcnt(0)
	s_waitcnt vmcnt(0) lgkmcnt(0)
	s_barrier
; #define WAIT_V0() asm volatile("s_waitcnt vmcnt(0)" ::: "memory")
; DI void gemm_core(char* smem, int nk, const char* Ab, const char* Bb, const unsigned (&aoff)[4], const unsigned (&boff)[4],
;                   f32x16 (&acc)[2][2]) {
;     ...
;   for (int kt = 0; kt < nk; ++kt) {
;     const int cur = kt & 1;
;     if (kt + 1 < nk) stage(cur ^ 1, kt + 1);
;     const char* sb = smem + cur * STAGE_B;
; #pragma unroll
;     for (int ks = 0; ks < 4; ++ks) {
;       bf16x8 af[2], bfr[2];
; #pragma unroll
;       for (int mb = 0; mb < 2; ++mb) af[mb] = *(const bf16x8*)(sb + a_base + mb * 4096 + xo[ks]);
; #pragma unroll
;       for (int nb = 0; nb < 2; ++nb) bfr[nb] = *(const bf16x8*)(sb + b_base + nb * 4096 + xo[ks]);
; #pragma unroll
;       for (int mb = 0; mb < 2; ++mb)
; #pragma unroll
;         for (int nb = 0; nb < 2; ++nb)
;           acc[mb][nb] = __builtin_amdgcn_mfma_f32_32x32x16_bf16(af[mb], bfr[nb], acc[mb][nb], 0, 0, 0);
;     }
;     WAIT_V0();
;     __syncthreads();
;   }
	v_mfma_f32_32x32x16_bf16 v[16:31], v[100:103], v[104:107], v[16:31]
	v_mfma_f32_32x32x16_bf16 v[0:15], v[100:103], v[108:111], v[0:15]
	v_lshl_add_u64 v[100:101], v[64:65], 0, s[38:39]
	global_load_lds_dwordx4 v[100:101], off
	v_lshl_add_u64 v[100:101], v[66:67], 0, s[38:39]
	s_mov_b32 m0, s43
	s_nop 0
	global_load_lds_dwordx4 v[100:101], off
	v_lshl_add_u64 v[100:101], v[68:69], 0, s[38:39]
	s_mov_b32 m0, s44
	s_nop 0
	global_load_lds_dwordx4 v[100:101], off
	v_lshl_add_u64 v[100:101], v[70:71], 0, s[38:39]
	s_mov_b32 m0, s1
	s_nop 0
	global_load_lds_dwordx4 v[100:101], off
	v_lshl_add_u64 v[100:101], v[72:73], 0, s[38:39]
	s_mov_b32 m0, s16
	s_nop 0
	global_load_lds_dwordx4 v[100:101], off
	v_lshl_add_u64 v[100:101], v[74:75], 0, s[38:39]
	s_mov_b32 m0, s17
	s_nop 0
	global_load_lds_dwordx4 v[100:101], off
	v_lshl_add_u64 v[100:101], v[76:77], 0, s[38:39]
	s_mov_b32 m0, s18
	s_nop 0
	global_load_lds_dwordx4 v[100:101], off
	v_lshl_add_u64 v[100:101], v[78:79], 0, s[38:39]
	s_mov_b32 m0, s19
	s_nop 0
	global_load_lds_dwordx4 v[100:101], off
	ds_read_b128 v[100:103], v80
	ds_read_b128 v[104:107], v82 offset:16384
	ds_read_b128 v[108:111], v82 offset:20480
	s_waitcnt lgkmcnt(0)
	v_mfma_f32_32x32x16_bf16 v[48:63], v[100:103], v[104:107], v[48:63]
	s_mov_b32 m0, s20
	v_mfma_f32_32x32x16_bf16 v[32:47], v[100:103], v[108:111], v[32:47]
	ds_read_b128 v[100:103], v80 offset:4096
	s_waitcnt lgkmcnt(0)
	v_mfma_f32_32x32x16_bf16 v[16:31], v[100:103], v[104:107], v[16:31]
	v_mfma_f32_32x32x16_bf16 v[0:15], v[100:103], v[108:111], v[0:15]
	ds_read_b128 v[100:103], v81
	ds_read_b128 v[104:107], v83 offset:16384
	ds_read_b128 v[108:111], v83 offset:20480
	s_waitcnt lgkmcnt(0)
	v_mfma_f32_32x32x16_bf16 v[48:63], v[100:103], v[104:107], v[48:63]
	v_mfma_f32_32x32x16_bf16 v[32:47], v[100:103], v[108:111], v[32:47]
	ds_read_b128 v[100:103], v81 offset:4096
	s_waitcnt lgkmcnt(0)
	v_mfma_f32_32x32x16_bf16 v[16:31], v[100:103], v[104:107], v[16:31]
	v_mfma_f32_32x32x16_bf16 v[0:15], v[100:103], v[108:111], v[0:15]
	ds_read_b128 v[100:103], v84
	ds_read_b128 v[104:107], v85 offset:16384
	ds_read_b128 v[108:111], v85 offset:20480
	s_waitcnt lgkmcnt(0)
	v_mfma_f32_32x32x16_bf16 v[48:63], v[100:103], v[104:107], v[48:63]
	v_mfma_f32_32x32x16_bf16 v[32:47], v[100:103], v[108:111], v[32:47]
	ds_read_b128 v[100:103], v84 offset:4096
	s_waitcnt lgkmcnt(0)
	v_mfma_f32_32x32x16_bf16 v[16:31], v[100:103], v[104:107], v[16:31]
	v_mfma_f32_32x32x16_bf16 v[0:15], v[100:103], v[108:111], v[0:15]
	ds_read_b128 v[100:103], v86
	ds_read_b128 v[104:107], v87 offset:16384
	ds_read_b128 v[108:111], v87 offset:20480
	s_waitcnt lgkmcnt(0)
	v_mfma_f32_32x32x16_bf16 v[48:63], v[100:103], v[104:107], v[48:63]
	v_mfma_f32_32x32x16_bf16 v[32:47], v[100:103], v[108:111], v[32:47]
	ds_read_b128 v[100:103], v86 offset:4096
	s_waitcnt vmcnt(0)
	s_waitcnt vmcnt(0) lgkmcnt(0)
	s_barrier
	v_mfma_f32_32x32x16_bf16 v[16:31], v[100:103], v[104:107], v[16:31]
	v_mfma_f32_32x32x16_bf16 v[0:15], v[100:103], v[108:111], v[0:15]
	v_lshl_add_u64 v[100:101], v[64:65], 0, s[30:31]
	global_load_lds_dwordx4 v[100:101], off
	v_lshl_add_u64 v[100:101], v[66:67], 0, s[30:31]
	s_mov_b32 m0, s21
	s_nop 0
	global_load_lds_dwordx4 v[100:101], off
	v_lshl_add_u64 v[100:101], v[68:69], 0, s[30:31]
	s_mov_b32 m0, s22
	s_nop 0
	global_load_lds_dwordx4 v[100:101], off
	v_lshl_add_u64 v[100:101], v[70:71], 0, s[30:31]
	s_mov_b32 m0, s23
	s_nop 0
	global_load_lds_dwordx4 v[100:101], off
	v_lshl_add_u64 v[100:101], v[72:73], 0, s[30:31]
	s_mov_b32 m0, s28
	s_nop 0
	global_load_lds_dwordx4 v[100:101], off
	v_lshl_add_u64 v[100:101], v[74:75], 0, s[30:31]
	s_mov_b32 m0, s29
	s_nop 0
	global_load_lds_dwordx4 v[100:101], off
	v_lshl_add_u64 v[100:101], v[76:77], 0, s[30:31]
	s_mov_b32 m0, s40
	s_nop 0
	global_load_lds_dwordx4 v[100:101], off
	v_lshl_add_u64 v[100:101], v[78:79], 0, s[30:31]
	s_mov_b32 m0, s41
	s_nop 0
	global_load_lds_dwordx4 v[100:101], off
	ds_read_b128 v[100:103], v80 offset:32768
	ds_read_b128 v[104:107], v82 offset:49152
	ds_read_b128 v[108:111], v82 offset:53248
	s_waitcnt lgkmcnt(0)
	v_mfma_f32_32x32x16_bf16 v[48:63], v[100:103], v[104:107], v[48:63]
	s_mov_b32 m0, s42
	v_mfma_f32_32x32x16_bf16 v[32:47], v[100:103], v[108:111], v[32:47]
	ds_read_b128 v[100:103], v80 offset:36864
	s_waitcnt lgkmcnt(0)
	v_mfma_f32_32x32x16_bf16 v[16:31], v[100:103], v[104:107], v[16:31]
	v_mfma_f32_32x32x16_bf16 v[0:15], v[100:103], v[108:111], v[0:15]
	ds_read_b128 v[100:103], v81 offset:32768
	ds_read_b128 v[104:107], v83 offset:49152
	ds_read_b128 v[108:111], v83 offset:53248
	s_waitcnt lgkmcnt(0)
	v_mfma_f32_32x32x16_bf16 v[48:63], v[100:103], v[104:107], v[48:63]
	v_mfma_f32_32x32x16_bf16 v[32:47], v[100:103], v[108:111], v[32:47]
	ds_read_b128 v[100:103], v81 offset:36864
	s_waitcnt lgkmcnt(0)
	v_mfma_f32_32x32x16_bf16 v[16:31], v[100:103], v[104:107], v[16:31]
	v_mfma_f32_32x32x16_bf16 v[0:15], v[100:103], v[108:111], v[0:15]
	ds_read_b128 v[100:103], v84 offset:32768
	ds_read_b128 v[104:107], v85 offset:49152
	ds_read_b128 v[108:111], v85 offset:53248
	s_waitcnt lgkmcnt(0)
	v_mfma_f32_32x32x16_bf16 v[48:63], v[100:103], v[104:107], v[48:63]
	v_mfma_f32_32x32x16_bf16 v[32:47], v[100:103], v[108:111], v[32:47]
	ds_read_b128 v[100:103], v84 offset:36864
	s_waitcnt lgkmcnt(0)
	v_mfma_f32_32x32x16_bf16 v[16:31], v[100:103], v[104:107], v[16:31]
	v_mfma_f32_32x32x16_bf16 v[0:15], v[100:103], v[108:111], v[0:15]
	ds_read_b128 v[100:103], v86 offset:32768
	ds_read_b128 v[104:107], v87 offset:49152
	ds_read_b128 v[108:111], v87 offset:53248
	s_waitcnt lgkmcnt(0)
	v_mfma_f32_32x32x16_bf16 v[48:63], v[100:103], v[104:107], v[48:63]
	v_mfma_f32_32x32x16_bf16 v[32:47], v[100:103], v[108:111], v[32:47]
	ds_read_b128 v[100:103], v86 offset:36864
	s_waitcnt vmcnt(0)
	s_waitcnt vmcnt(0) lgkmcnt(0)
	s_barrier
; #define WAIT_V0() asm volatile("s_waitcnt vmcnt(0)" ::: "memory")
; DI void gemm_core(char* smem, int nk, const char* Ab, const char* Bb, const unsigned (&aoff)[4], const unsigned (&boff)[4],
;                   f32x16 (&acc)[2][2]) {
;     ...
;   for (int kt = 0; kt < nk; ++kt) {
;     const int cur = kt & 1;
;     if (kt + 1 < nk) stage(cur ^ 1, kt + 1);
;     const char* sb = smem + cur * STAGE_B;
; #pragma unroll
;     for (int ks = 0; ks < 4; ++ks) {
;       bf16x8 af[2], bfr[2];
; #pragma unroll
;       for (int mb = 0; mb < 2; ++mb) af[mb] = *(const bf16x8*)(sb + a_base + mb * 4096 + xo[ks]);
; #pragma unroll
;       for (int nb = 0; nb < 2; ++nb) bfr[nb] = *(const bf16x8*)(sb + b_base + nb * 4096 + xo[ks]);
; #pragma unroll
;       for (int mb = 0; mb < 2; ++mb)
; #pragma unroll
;         for (int nb = 0; nb < 2; ++nb)
;           acc[mb][nb] = __builtin_amdgcn_mfma_f32_32x32x16_bf16(af[mb], bfr[nb], acc[mb][nb], 0, 0, 0);
;     }
;     WAIT_V0();
;     __syncthreads();
;   }
	v_mfma_f32_32x32x16_bf16 v[16:31], v[100:103], v[104:107], v[16:31]
	v_mfma_f32_32x32x16_bf16 v[0:15], v[100:103], v[108:111], v[0:15]
	v_lshl_add_u64 v[100:101], v[64:65], 0, s[46:47]
	global_load_lds_dwordx4 v[100:101], off
	v_lshl_add_u64 v[100:101], v[66:67], 0, s[46:47]
	s_mov_b32 m0, s43
	s_nop 0
	global_load_lds_dwordx4 v[100:101], off
	v_lshl_add_u64 v[100:101], v[68:69], 0, s[46:47]
	s_mov_b32 m0, s44
	s_nop 0
	global_load_lds_dwordx4 v[100:101], off
	v_lshl_add_u64 v[100:101], v[70:71], 0, s[46:47]
	s_mov_b32 m0, s1
	s_nop 0
	global_load_lds_dwordx4 v[100:101], off
	v_lshl_add_u64 v[100:101], v[72:73], 0, s[46:47]
	s_mov_b32 m0, s16
	s_nop 0
	global_load_lds_dwordx4 v[100:101], off
	v_lshl_add_u64 v[100:101], v[74:75], 0, s[46:47]
	s_mov_b32 m0, s17
	s_nop 0
	global_load_lds_dwordx4 v[100:101], off
	v_lshl_add_u64 v[100:101], v[76:77], 0, s[46:47]
	s_mov_b32 m0, s18
	s_nop 0
	global_load_lds_dwordx4 v[100:101], off
	v_lshl_add_u64 v[100:101], v[78:79], 0, s[46:47]
	s_mov_b32 m0, s19
	s_nop 0
	global_load_lds_dwordx4 v[100:101], off
	ds_read_b128 v[100:103], v80
	ds_read_b128 v[104:107], v82 offset:16384
	ds_read_b128 v[108:111], v82 offset:20480
	s_waitcnt lgkmcnt(0)
	v_mfma_f32_32x32x16_bf16 v[48:63], v[100:103], v[104:107], v[48:63]
	s_mov_b32 m0, s20
	v_mfma_f32_32x32x16_bf16 v[32:47], v[100:103], v[108:111], v[32:47]
	ds_read_b128 v[100:103], v80 offset:4096
	s_waitcnt lgkmcnt(0)
	v_mfma_f32_32x32x16_bf16 v[16:31], v[100:103], v[104:107], v[16:31]
	v_mfma_f32_32x32x16_bf16 v[0:15], v[100:103], v[108:111], v[0:15]
	ds_read_b128 v[100:103], v81
	ds_read_b128 v[104:107], v83 offset:16384
	ds_read_b128 v[108:111], v83 offset:20480
	s_waitcnt lgkmcnt(0)
	v_mfma_f32_32x32x16_bf16 v[48:63], v[100:103], v[104:107], v[48:63]
	v_mfma_f32_32x32x16_bf16 v[32:47], v[100:103], v[108:111], v[32:47]
	ds_read_b128 v[100:103], v81 offset:4096
	s_waitcnt lgkmcnt(0)
	v_mfma_f32_32x32x16_bf16 v[16:31], v[100:103], v[104:107], v[16:31]
	v_mfma_f32_32x32x16_bf16 v[0:15], v[100:103], v[108:111], v[0:15]
	ds_read_b128 v[100:103], v84
	ds_read_b128 v[104:107], v85 offset:16384
	ds_read_b128 v[108:111], v85 offset:20480
	s_waitcnt lgkmcnt(0)
	v_mfma_f32_32x32x16_bf16 v[48:63], v[100:103], v[104:107], v[48:63]
	v_mfma_f32_32x32x16_bf16 v[32:47], v[100:103], v[108:111], v[32:47]
	ds_read_b128 v[100:103], v84 offset:4096
	s_waitcnt lgkmcnt(0)
	v_mfma_f32_32x32x16_bf16 v[16:31], v[100:103], v[104:107], v[16:31]
	v_mfma_f32_32x32x16_bf16 v[0:15], v[100:103], v[108:111], v[0:15]
	ds_read_b128 v[100:103], v86
	ds_read_b128 v[104:107], v87 offset:16384
	ds_read_b128 v[108:111], v87 offset:20480
	s_waitcnt lgkmcnt(0)
	v_mfma_f32_32x32x16_bf16 v[48:63], v[100:103], v[104:107], v[48:63]
	v_mfma_f32_32x32x16_bf16 v[32:47], v[100:103], v[108:111], v[32:47]
	ds_read_b128 v[100:103], v86 offset:4096
	s_waitcnt vmcnt(0)
	s_waitcnt vmcnt(0) lgkmcnt(0)
	s_barrier
	v_mfma_f32_32x32x16_bf16 v[16:31], v[100:103], v[104:107], v[16:31]
	v_mfma_f32_32x32x16_bf16 v[0:15], v[100:103], v[108:111], v[0:15]
	v_lshl_add_u64 v[100:101], v[64:65], 0, s[48:49]
	global_load_lds_dwordx4 v[100:101], off
	v_lshl_add_u64 v[100:101], v[66:67], 0, s[48:49]
	s_mov_b32 m0, s21
	s_nop 0
	global_load_lds_dwordx4 v[100:101], off
	v_lshl_add_u64 v[100:101], v[68:69], 0, s[48:49]
	s_mov_b32 m0, s22
	s_nop 0
	global_load_lds_dwordx4 v[100:101], off
	v_lshl_add_u64 v[100:101], v[70:71], 0, s[48:49]
	s_mov_b32 m0, s23
	s_nop 0
	global_load_lds_dwordx4 v[100:101], off
	v_lshl_add_u64 v[100:101], v[72:73], 0, s[48:49]
	s_mov_b32 m0, s28
	s_nop 0
	global_load_lds_dwordx4 v[100:101], off
	v_lshl_add_u64 v[100:101], v[74:75], 0, s[48:49]
	s_mov_b32 m0, s29
	s_nop 0
	global_load_lds_dwordx4 v[100:101], off
	v_lshl_add_u64 v[100:101], v[76:77], 0, s[48:49]
	s_mov_b32 m0, s40
	s_nop 0
	global_load_lds_dwordx4 v[100:101], off
	v_lshl_add_u64 v[100:101], v[78:79], 0, s[48:49]
	s_mov_b32 m0, s41
	s_nop 0
	global_load_lds_dwordx4 v[100:101], off
	ds_read_b128 v[100:103], v80 offset:32768
	ds_read_b128 v[104:107], v82 offset:49152
	ds_read_b128 v[108:111], v82 offset:53248
	s_waitcnt lgkmcnt(0)
	v_mfma_f32_32x32x16_bf16 v[48:63], v[100:103], v[104:107], v[48:63]
	s_mov_b32 m0, s42
	v_readfirstlane_b32 s42, v93
	v_mfma_f32_32x32x16_bf16 v[32:47], v[100:103], v[108:111], v[32:47]
	ds_read_b128 v[100:103], v80 offset:36864
	s_waitcnt lgkmcnt(0)
	v_mfma_f32_32x32x16_bf16 v[16:31], v[100:103], v[104:107], v[16:31]
	v_mfma_f32_32x32x16_bf16 v[0:15], v[100:103], v[108:111], v[0:15]
	ds_read_b128 v[100:103], v81 offset:32768
	ds_read_b128 v[104:107], v83 offset:49152
	ds_read_b128 v[108:111], v83 offset:53248
	s_waitcnt lgkmcnt(0)
	v_mfma_f32_32x32x16_bf16 v[48:63], v[100:103], v[104:107], v[48:63]
	v_mfma_f32_32x32x16_bf16 v[32:47], v[100:103], v[108:111], v[32:47]
	ds_read_b128 v[100:103], v81 offset:36864
	s_waitcnt lgkmcnt(0)
	v_mfma_f32_32x32x16_bf16 v[16:31], v[100:103], v[104:107], v[16:31]
	v_mfma_f32_32x32x16_bf16 v[0:15], v[100:103], v[108:111], v[0:15]
	ds_read_b128 v[100:103], v84 offset:32768
	ds_read_b128 v[104:107], v85 offset:49152
	ds_read_b128 v[108:111], v85 offset:53248
	s_waitcnt lgkmcnt(0)
	v_mfma_f32_32x32x16_bf16 v[48:63], v[100:103], v[104:107], v[48:63]
	v_mfma_f32_32x32x16_bf16 v[32:47], v[100:103], v[108:111], v[32:47]
	ds_read_b128 v[100:103], v84 offset:36864
	s_waitcnt lgkmcnt(0)
	v_mfma_f32_32x32x16_bf16 v[16:31], v[100:103], v[104:107], v[16:31]
	v_mfma_f32_32x32x16_bf16 v[0:15], v[100:103], v[108:111], v[0:15]
	ds_read_b128 v[100:103], v86 offset:32768
	ds_read_b128 v[104:107], v87 offset:49152
	ds_read_b128 v[108:111], v87 offset:53248
	s_waitcnt lgkmcnt(0)
	v_mfma_f32_32x32x16_bf16 v[48:63], v[100:103], v[104:107], v[48:63]
	v_mfma_f32_32x32x16_bf16 v[32:47], v[100:103], v[108:111], v[32:47]
	ds_read_b128 v[100:103], v86 offset:36864
	s_waitcnt vmcnt(0)
	s_waitcnt vmcnt(0) lgkmcnt(0)
	s_barrier
; #define WAIT_V0() asm volatile("s_waitcnt vmcnt(0)" ::: "memory")
; DI void gemm_core(char* smem, int nk, const char* Ab, const char* Bb, const unsigned (&aoff)[4], const unsigned (&boff)[4],
;                   f32x16 (&acc)[2][2]) {
;     ...
;   for (int kt = 0; kt < nk; ++kt) {
;     const int cur = kt & 1;
;     if (kt + 1 < nk) stage(cur ^ 1, kt + 1);
;     const char* sb = smem + cur * STAGE_B;
; #pragma unroll
;     for (int ks = 0; ks < 4; ++ks) {
;       bf16x8 af[2], bfr[2];
; #pragma unroll
;       for (int mb = 0; mb < 2; ++mb) af[mb] = *(const bf16x8*)(sb + a_base + mb * 4096 + xo[ks]);
; #pragma unroll
;       for (int nb = 0; nb < 2; ++nb) bfr[nb] = *(const bf16x8*)(sb + b_base + nb * 4096 + xo[ks]);
; #pragma unroll
;       for (int mb = 0; mb < 2; ++mb)
; #pragma unroll
;         for (int nb = 0; nb < 2; ++nb)
;           acc[mb][nb] = __builtin_amdgcn_mfma_f32_32x32x16_bf16(af[mb], bfr[nb], acc[mb][nb], 0, 0, 0);
;     }
;     WAIT_V0();
;     __syncthreads();
;   }
	v_mfma_f32_32x32x16_bf16 v[16:31], v[100:103], v[104:107], v[16:31]
	v_mfma_f32_32x32x16_bf16 v[0:15], v[100:103], v[108:111], v[0:15]
	v_lshl_add_u64 v[100:101], v[64:65], 0, s[50:51]
	global_load_lds_dwordx4 v[100:101], off
	v_lshl_add_u64 v[100:101], v[66:67], 0, s[50:51]
	s_mov_b32 m0, s43
	v_readfirstlane_b32 s43, v94
	global_load_lds_dwordx4 v[100:101], off
	v_lshl_add_u64 v[100:101], v[68:69], 0, s[50:51]
	s_mov_b32 m0, s44
	v_readfirstlane_b32 s44, v95
	global_load_lds_dwordx4 v[100:101], off
	v_lshl_add_u64 v[100:101], v[70:71], 0, s[50:51]
	s_mov_b32 m0, s1
	s_nop 0
	global_load_lds_dwordx4 v[100:101], off
	v_lshl_add_u64 v[100:101], v[72:73], 0, s[50:51]
	s_mov_b32 m0, s16
	s_nop 0
	global_load_lds_dwordx4 v[100:101], off
	v_lshl_add_u64 v[100:101], v[74:75], 0, s[50:51]
	s_mov_b32 m0, s17
	s_nop 0
	global_load_lds_dwordx4 v[100:101], off
	v_lshl_add_u64 v[100:101], v[76:77], 0, s[50:51]
	s_mov_b32 m0, s18
	s_nop 0
	global_load_lds_dwordx4 v[100:101], off
	v_lshl_add_u64 v[100:101], v[78:79], 0, s[50:51]
	s_mov_b32 m0, s19
	s_nop 0
	global_load_lds_dwordx4 v[100:101], off
	ds_read_b128 v[100:103], v80
	ds_read_b128 v[104:107], v82 offset:16384
	ds_read_b128 v[108:111], v82 offset:20480
	s_waitcnt lgkmcnt(0)
	v_mfma_f32_32x32x16_bf16 v[48:63], v[100:103], v[104:107], v[48:63]
	s_mov_b32 m0, s20
	v_readfirstlane_b32 s20, v97
	v_mfma_f32_32x32x16_bf16 v[32:47], v[100:103], v[108:111], v[32:47]
	ds_read_b128 v[100:103], v80 offset:4096
	s_waitcnt lgkmcnt(0)
	v_mfma_f32_32x32x16_bf16 v[16:31], v[100:103], v[104:107], v[16:31]
	v_mfma_f32_32x32x16_bf16 v[0:15], v[100:103], v[108:111], v[0:15]
	ds_read_b128 v[100:103], v81
	ds_read_b128 v[104:107], v83 offset:16384
	ds_read_b128 v[108:111], v83 offset:20480
	s_waitcnt lgkmcnt(0)
	v_mfma_f32_32x32x16_bf16 v[48:63], v[100:103], v[104:107], v[48:63]
	v_mfma_f32_32x32x16_bf16 v[32:47], v[100:103], v[108:111], v[32:47]
	ds_read_b128 v[100:103], v81 offset:4096
	s_waitcnt lgkmcnt(0)
	v_mfma_f32_32x32x16_bf16 v[16:31], v[100:103], v[104:107], v[16:31]
	v_mfma_f32_32x32x16_bf16 v[0:15], v[100:103], v[108:111], v[0:15]
	ds_read_b128 v[100:103], v84
	ds_read_b128 v[104:107], v85 offset:16384
	ds_read_b128 v[108:111], v85 offset:20480
	s_waitcnt lgkmcnt(0)
	v_mfma_f32_32x32x16_bf16 v[48:63], v[100:103], v[104:107], v[48:63]
	v_mfma_f32_32x32x16_bf16 v[32:47], v[100:103], v[108:111], v[32:47]
	ds_read_b128 v[100:103], v84 offset:4096
	s_waitcnt lgkmcnt(0)
	v_mfma_f32_32x32x16_bf16 v[16:31], v[100:103], v[104:107], v[16:31]
	v_mfma_f32_32x32x16_bf16 v[0:15], v[100:103], v[108:111], v[0:15]
	ds_read_b128 v[100:103], v86
	ds_read_b128 v[104:107], v87 offset:16384
	ds_read_b128 v[108:111], v87 offset:20480
	s_waitcnt lgkmcnt(0)
	v_mfma_f32_32x32x16_bf16 v[48:63], v[100:103], v[104:107], v[48:63]
	v_mfma_f32_32x32x16_bf16 v[32:47], v[100:103], v[108:111], v[32:47]
	ds_read_b128 v[100:103], v86 offset:4096
	s_waitcnt vmcnt(0)
	s_waitcnt vmcnt(0) lgkmcnt(0)
	s_barrier
	v_mfma_f32_32x32x16_bf16 v[16:31], v[100:103], v[104:107], v[16:31]
	v_mfma_f32_32x32x16_bf16 v[0:15], v[100:103], v[108:111], v[0:15]
	v_lshl_add_u64 v[100:101], v[64:65], 0, s[52:53]
	global_load_lds_dwordx4 v[100:101], off
	v_lshl_add_u64 v[100:101], v[66:67], 0, s[52:53]
	s_mov_b32 m0, s21
	v_readfirstlane_b32 s21, v96
	global_load_lds_dwordx4 v[100:101], off
	v_lshl_add_u64 v[100:101], v[68:69], 0, s[52:53]
	s_mov_b32 m0, s22
	v_readfirstlane_b32 s22, v98
	global_load_lds_dwordx4 v[100:101], off
	v_lshl_add_u64 v[100:101], v[70:71], 0, s[52:53]
	s_mov_b32 m0, s23
	v_lshl_add_u64 v[96:97], v[68:69], 0, s[54:55]
	global_load_lds_dwordx4 v[100:101], off
	v_lshl_add_u64 v[100:101], v[72:73], 0, s[52:53]
	s_mov_b32 m0, s28
	v_readfirstlane_b32 s23, v89
	global_load_lds_dwordx4 v[100:101], off
	v_lshl_add_u64 v[100:101], v[74:75], 0, s[52:53]
	s_mov_b32 m0, s29
	v_readfirstlane_b32 s28, v88
	global_load_lds_dwordx4 v[100:101], off
	v_lshl_add_u64 v[100:101], v[76:77], 0, s[52:53]
	s_mov_b32 m0, s40
	v_readfirstlane_b32 s29, v90
	global_load_lds_dwordx4 v[100:101], off
	v_lshl_add_u64 v[100:101], v[78:79], 0, s[52:53]
	s_mov_b32 m0, s41
	v_lshl_add_u64 v[88:89], v[68:69], 0, s[56:57]
	global_load_lds_dwordx4 v[100:101], off
	ds_read_b128 v[100:103], v80 offset:32768
	ds_read_b128 v[104:107], v82 offset:49152
	ds_read_b128 v[108:111], v82 offset:53248
	s_waitcnt lgkmcnt(0)
	v_mfma_f32_32x32x16_bf16 v[48:63], v[100:103], v[104:107], v[48:63]
	s_mov_b32 m0, s20
	v_readfirstlane_b32 s40, v91
	v_readfirstlane_b32 s41, v92
	v_mfma_f32_32x32x16_bf16 v[32:47], v[100:103], v[108:111], v[32:47]
	ds_read_b128 v[100:103], v80 offset:36864
	s_waitcnt lgkmcnt(0)
	v_mfma_f32_32x32x16_bf16 v[16:31], v[100:103], v[104:107], v[16:31]
	v_mfma_f32_32x32x16_bf16 v[0:15], v[100:103], v[108:111], v[0:15]
	ds_read_b128 v[100:103], v81 offset:32768
	ds_read_b128 v[104:107], v83 offset:49152
	ds_read_b128 v[108:111], v83 offset:53248
	s_waitcnt lgkmcnt(0)
	v_mfma_f32_32x32x16_bf16 v[48:63], v[100:103], v[104:107], v[48:63]
	v_mfma_f32_32x32x16_bf16 v[32:47], v[100:103], v[108:111], v[32:47]
	ds_read_b128 v[100:103], v81 offset:36864
	s_waitcnt lgkmcnt(0)
	v_mfma_f32_32x32x16_bf16 v[16:31], v[100:103], v[104:107], v[16:31]
	v_mfma_f32_32x32x16_bf16 v[0:15], v[100:103], v[108:111], v[0:15]
	ds_read_b128 v[100:103], v84 offset:32768
	ds_read_b128 v[104:107], v85 offset:49152
	ds_read_b128 v[108:111], v85 offset:53248
	s_waitcnt lgkmcnt(0)
	v_mfma_f32_32x32x16_bf16 v[48:63], v[100:103], v[104:107], v[48:63]
	v_mfma_f32_32x32x16_bf16 v[32:47], v[100:103], v[108:111], v[32:47]
	ds_read_b128 v[100:103], v84 offset:36864
	s_waitcnt lgkmcnt(0)
	v_mfma_f32_32x32x16_bf16 v[16:31], v[100:103], v[104:107], v[16:31]
	v_mfma_f32_32x32x16_bf16 v[0:15], v[100:103], v[108:111], v[0:15]
	ds_read_b128 v[100:103], v86 offset:32768
	ds_read_b128 v[104:107], v87 offset:49152
	ds_read_b128 v[108:111], v87 offset:53248
	s_waitcnt lgkmcnt(0)
	v_mfma_f32_32x32x16_bf16 v[48:63], v[100:103], v[104:107], v[48:63]
	v_mfma_f32_32x32x16_bf16 v[32:47], v[100:103], v[108:111], v[32:47]
	ds_read_b128 v[100:103], v86 offset:36864
	s_waitcnt vmcnt(0)
	s_waitcnt vmcnt(0) lgkmcnt(0)
	s_barrier
; #define WAIT_V0() asm volatile("s_waitcnt vmcnt(0)" ::: "memory")
; DI void gemm_core(char* smem, int nk, const char* Ab, const char* Bb, const unsigned (&aoff)[4], const unsigned (&boff)[4],
;                   f32x16 (&acc)[2][2]) {
;     ...
;   for (int kt = 0; kt < nk; ++kt) {
;     const int cur = kt & 1;
;     if (kt + 1 < nk) stage(cur ^ 1, kt + 1);
;     const char* sb = smem + cur * STAGE_B;
; #pragma unroll
;     for (int ks = 0; ks < 4; ++ks) {
;       bf16x8 af[2], bfr[2];
; #pragma unroll
;       for (int mb = 0; mb < 2; ++mb) af[mb] = *(const bf16x8*)(sb + a_base + mb * 4096 + xo[ks]);
; #pragma unroll
;       for (int nb = 0; nb < 2; ++nb) bfr[nb] = *(const bf16x8*)(sb + b_base + nb * 4096 + xo[ks]);
; #pragma unroll
;       for (int mb = 0; mb < 2; ++mb)
; #pragma unroll
;         for (int nb = 0; nb < 2; ++nb)
;           acc[mb][nb] = __builtin_amdgcn_mfma_f32_32x32x16_bf16(af[mb], bfr[nb], acc[mb][nb], 0, 0, 0);
;     }
;     WAIT_V0();
;     __syncthreads();
;   }
	v_mfma_f32_32x32x16_bf16 v[16:31], v[100:103], v[104:107], v[16:31]
	v_mfma_f32_32x32x16_bf16 v[0:15], v[100:103], v[108:111], v[0:15]
	v_lshl_add_u64 v[100:101], v[64:65], 0, s[54:55]
	global_load_lds_dwordx4 v[100:101], off
	v_lshl_add_u64 v[100:101], v[66:67], 0, s[54:55]
	s_mov_b32 m0, s21
	s_nop 0
	global_load_lds_dwordx4 v[100:101], off
	s_mov_b32 m0, s22
	s_nop 0
	global_load_lds_dwordx4 v[96:97], off
	v_lshl_add_u64 v[96:97], v[70:71], 0, s[54:55]
	s_mov_b32 m0, s1
	s_nop 0
	global_load_lds_dwordx4 v[96:97], off
	v_lshl_add_u64 v[96:97], v[72:73], 0, s[54:55]
	s_mov_b32 m0, s16
	s_nop 0
	global_load_lds_dwordx4 v[96:97], off
	v_lshl_add_u64 v[96:97], v[74:75], 0, s[54:55]
	s_mov_b32 m0, s17
	s_nop 0
	global_load_lds_dwordx4 v[96:97], off
	v_lshl_add_u64 v[96:97], v[76:77], 0, s[54:55]
	s_mov_b32 m0, s18
	s_nop 0
	global_load_lds_dwordx4 v[96:97], off
	v_lshl_add_u64 v[96:97], v[78:79], 0, s[54:55]
	s_mov_b32 m0, s19
	s_nop 0
	global_load_lds_dwordx4 v[96:97], off
	ds_read_b128 v[96:99], v80
	ds_read_b128 v[100:103], v82 offset:16384
	ds_read_b128 v[104:107], v82 offset:20480
	s_waitcnt lgkmcnt(0)
	v_mfma_f32_32x32x16_bf16 v[48:63], v[96:99], v[100:103], v[48:63]
	s_mov_b32 m0, s23
	v_mfma_f32_32x32x16_bf16 v[32:47], v[96:99], v[104:107], v[32:47]
	ds_read_b128 v[96:99], v80 offset:4096
	s_waitcnt lgkmcnt(0)
	v_mfma_f32_32x32x16_bf16 v[16:31], v[96:99], v[100:103], v[16:31]
	v_mfma_f32_32x32x16_bf16 v[0:15], v[96:99], v[104:107], v[0:15]
	ds_read_b128 v[96:99], v81
	ds_read_b128 v[100:103], v83 offset:16384
	ds_read_b128 v[104:107], v83 offset:20480
	s_waitcnt lgkmcnt(0)
	v_mfma_f32_32x32x16_bf16 v[48:63], v[96:99], v[100:103], v[48:63]
	v_mfma_f32_32x32x16_bf16 v[32:47], v[96:99], v[104:107], v[32:47]
	ds_read_b128 v[96:99], v81 offset:4096
	s_waitcnt lgkmcnt(0)
	v_mfma_f32_32x32x16_bf16 v[16:31], v[96:99], v[100:103], v[16:31]
	v_mfma_f32_32x32x16_bf16 v[0:15], v[96:99], v[104:107], v[0:15]
	ds_read_b128 v[96:99], v84
	ds_read_b128 v[100:103], v85 offset:16384
	ds_read_b128 v[104:107], v85 offset:20480
	s_waitcnt lgkmcnt(0)
	v_mfma_f32_32x32x16_bf16 v[48:63], v[96:99], v[100:103], v[48:63]
	v_mfma_f32_32x32x16_bf16 v[32:47], v[96:99], v[104:107], v[32:47]
	ds_read_b128 v[96:99], v84 offset:4096
	s_waitcnt lgkmcnt(0)
	v_mfma_f32_32x32x16_bf16 v[16:31], v[96:99], v[100:103], v[16:31]
	v_mfma_f32_32x32x16_bf16 v[0:15], v[96:99], v[104:107], v[0:15]
	ds_read_b128 v[96:99], v86
	ds_read_b128 v[100:103], v87 offset:16384
	ds_read_b128 v[104:107], v87 offset:20480
	s_waitcnt lgkmcnt(0)
	v_mfma_f32_32x32x16_bf16 v[48:63], v[96:99], v[100:103], v[48:63]
	v_mfma_f32_32x32x16_bf16 v[32:47], v[96:99], v[104:107], v[32:47]
	ds_read_b128 v[96:99], v86 offset:4096
	s_waitcnt vmcnt(0)
	s_waitcnt vmcnt(0) lgkmcnt(0)
	s_barrier
	v_mfma_f32_32x32x16_bf16 v[16:31], v[96:99], v[100:103], v[16:31]
	v_mfma_f32_32x32x16_bf16 v[0:15], v[96:99], v[104:107], v[0:15]
	v_lshl_add_u64 v[96:97], v[64:65], 0, s[56:57]
	global_load_lds_dwordx4 v[96:97], off
	v_lshl_add_u64 v[96:97], v[66:67], 0, s[56:57]
	s_mov_b32 m0, s28
	s_nop 0
	global_load_lds_dwordx4 v[96:97], off
	s_mov_b32 m0, s29
	s_nop 0
	global_load_lds_dwordx4 v[88:89], off
	v_lshl_add_u64 v[88:89], v[70:71], 0, s[56:57]
	s_mov_b32 m0, s40
	s_nop 0
	global_load_lds_dwordx4 v[88:89], off
	v_lshl_add_u64 v[88:89], v[72:73], 0, s[56:57]
	s_mov_b32 m0, s41
	s_nop 0
	global_load_lds_dwordx4 v[88:89], off
	v_lshl_add_u64 v[88:89], v[74:75], 0, s[56:57]
	s_mov_b32 m0, s42
	s_nop 0
	global_load_lds_dwordx4 v[88:89], off
	v_lshl_add_u64 v[88:89], v[76:77], 0, s[56:57]
	s_mov_b32 m0, s43
	s_nop 0
	global_load_lds_dwordx4 v[88:89], off
	v_lshl_add_u64 v[88:89], v[78:79], 0, s[56:57]
	s_mov_b32 m0, s44
	s_nop 0
	global_load_lds_dwordx4 v[88:89], off
	ds_read_b128 v[88:91], v80 offset:32768
	ds_read_b128 v[92:95], v82 offset:49152
	ds_read_b128 v[96:99], v82 offset:53248
	s_waitcnt lgkmcnt(0)
	v_mfma_f32_32x32x16_bf16 v[48:63], v[88:91], v[92:95], v[48:63]
	s_mov_b32 m0, s20
	v_mfma_f32_32x32x16_bf16 v[32:47], v[88:91], v[96:99], v[32:47]
	ds_read_b128 v[88:91], v80 offset:36864
	s_waitcnt lgkmcnt(0)
	v_mfma_f32_32x32x16_bf16 v[16:31], v[88:91], v[92:95], v[16:31]
	v_mfma_f32_32x32x16_bf16 v[0:15], v[88:91], v[96:99], v[0:15]
	ds_read_b128 v[88:91], v81 offset:32768
	ds_read_b128 v[92:95], v83 offset:49152
	ds_read_b128 v[96:99], v83 offset:53248
	s_waitcnt lgkmcnt(0)
	v_mfma_f32_32x32x16_bf16 v[48:63], v[88:91], v[92:95], v[48:63]
	v_mfma_f32_32x32x16_bf16 v[32:47], v[88:91], v[96:99], v[32:47]
	ds_read_b128 v[88:91], v81 offset:36864
	s_waitcnt lgkmcnt(0)
	v_mfma_f32_32x32x16_bf16 v[16:31], v[88:91], v[92:95], v[16:31]
	v_mfma_f32_32x32x16_bf16 v[0:15], v[88:91], v[96:99], v[0:15]
	ds_read_b128 v[88:91], v84 offset:32768
	ds_read_b128 v[92:95], v85 offset:49152
	ds_read_b128 v[96:99], v85 offset:53248
	s_waitcnt lgkmcnt(0)
	v_mfma_f32_32x32x16_bf16 v[48:63], v[88:91], v[92:95], v[48:63]
	v_mfma_f32_32x32x16_bf16 v[32:47], v[88:91], v[96:99], v[32:47]
	ds_read_b128 v[88:91], v84 offset:36864
	s_waitcnt lgkmcnt(0)
	v_mfma_f32_32x32x16_bf16 v[16:31], v[88:91], v[92:95], v[16:31]
	v_mfma_f32_32x32x16_bf16 v[0:15], v[88:91], v[96:99], v[0:15]
	ds_read_b128 v[88:91], v86 offset:32768
	ds_read_b128 v[92:95], v87 offset:49152
	ds_read_b128 v[96:99], v87 offset:53248
	s_waitcnt lgkmcnt(0)
	v_mfma_f32_32x32x16_bf16 v[48:63], v[88:91], v[92:95], v[48:63]
	v_mfma_f32_32x32x16_bf16 v[32:47], v[88:91], v[96:99], v[32:47]
	ds_read_b128 v[88:91], v86 offset:36864
	s_waitcnt vmcnt(0)
	s_waitcnt vmcnt(0) lgkmcnt(0)
	s_barrier
; #define WAIT_V0() asm volatile("s_waitcnt vmcnt(0)" ::: "memory")
; DI void gemm_core(char* smem, int nk, const char* Ab, const char* Bb, const unsigned (&aoff)[4], const unsigned (&boff)[4],
;                   f32x16 (&acc)[2][2]) {
;     ...
;   for (int kt = 0; kt < nk; ++kt) {
;     const int cur = kt & 1;
;     if (kt + 1 < nk) stage(cur ^ 1, kt + 1);
;     const char* sb = smem + cur * STAGE_B;
; #pragma unroll
;     for (int ks = 0; ks < 4; ++ks) {
;       bf16x8 af[2], bfr[2];
; #pragma unroll
;       for (int mb = 0; mb < 2; ++mb) af[mb] = *(const bf16x8*)(sb + a_base + mb * 4096 + xo[ks]);
; #pragma unroll
;       for (int nb = 0; nb < 2; ++nb) bfr[nb] = *(const bf16x8*)(sb + b_base + nb * 4096 + xo[ks]);
; #pragma unroll
;       for (int mb = 0; mb < 2; ++mb)
; #pragma unroll
;         for (int nb = 0; nb < 2; ++nb)
;           acc[mb][nb] = __builtin_amdgcn_mfma_f32_32x32x16_bf16(af[mb], bfr[nb], acc[mb][nb], 0, 0, 0);
;     }
;     WAIT_V0();
;     __syncthreads();
;   }
	v_mfma_f32_32x32x16_bf16 v[16:31], v[88:91], v[92:95], v[16:31]
	v_mfma_f32_32x32x16_bf16 v[0:15], v[88:91], v[96:99], v[0:15]
	v_lshl_add_u64 v[88:89], v[64:65], 0, s[58:59]
	global_load_lds_dwordx4 v[88:89], off
	v_lshl_add_u64 v[88:89], v[66:67], 0, s[58:59]
	s_mov_b32 m0, s21
	s_nop 0
	global_load_lds_dwordx4 v[88:89], off
	v_lshl_add_u64 v[88:89], v[68:69], 0, s[58:59]
	s_mov_b32 m0, s22
	s_nop 0
	global_load_lds_dwordx4 v[88:89], off
	v_lshl_add_u64 v[88:89], v[70:71], 0, s[58:59]
	s_mov_b32 m0, s1
	s_nop 0
	global_load_lds_dwordx4 v[88:89], off
	v_lshl_add_u64 v[88:89], v[72:73], 0, s[58:59]
	s_mov_b32 m0, s16
	s_nop 0
	global_load_lds_dwordx4 v[88:89], off
	v_lshl_add_u64 v[88:89], v[74:75], 0, s[58:59]
	s_mov_b32 m0, s17
	s_nop 0
	global_load_lds_dwordx4 v[88:89], off
	v_lshl_add_u64 v[88:89], v[76:77], 0, s[58:59]
	s_mov_b32 m0, s18
	s_nop 0
	global_load_lds_dwordx4 v[88:89], off
	v_lshl_add_u64 v[88:89], v[78:79], 0, s[58:59]
	s_mov_b32 m0, s19
	s_nop 0
	global_load_lds_dwordx4 v[88:89], off
	ds_read_b128 v[88:91], v80
	ds_read_b128 v[92:95], v82 offset:16384
	ds_read_b128 v[96:99], v82 offset:20480
	s_waitcnt lgkmcnt(0)
	v_mfma_f32_32x32x16_bf16 v[48:63], v[88:91], v[92:95], v[48:63]
	s_mov_b32 m0, s23
	v_mfma_f32_32x32x16_bf16 v[32:47], v[88:91], v[96:99], v[32:47]
	ds_read_b128 v[88:91], v80 offset:4096
	s_waitcnt lgkmcnt(0)
	v_mfma_f32_32x32x16_bf16 v[16:31], v[88:91], v[92:95], v[16:31]
	v_mfma_f32_32x32x16_bf16 v[0:15], v[88:91], v[96:99], v[0:15]
	ds_read_b128 v[88:91], v81
	ds_read_b128 v[92:95], v83 offset:16384
	ds_read_b128 v[96:99], v83 offset:20480
	s_waitcnt lgkmcnt(0)
	v_mfma_f32_32x32x16_bf16 v[48:63], v[88:91], v[92:95], v[48:63]
	v_mfma_f32_32x32x16_bf16 v[32:47], v[88:91], v[96:99], v[32:47]
	ds_read_b128 v[88:91], v81 offset:4096
	s_waitcnt lgkmcnt(0)
	v_mfma_f32_32x32x16_bf16 v[16:31], v[88:91], v[92:95], v[16:31]
	v_mfma_f32_32x32x16_bf16 v[0:15], v[88:91], v[96:99], v[0:15]
	ds_read_b128 v[88:91], v84
	ds_read_b128 v[92:95], v85 offset:16384
	ds_read_b128 v[96:99], v85 offset:20480
	s_waitcnt lgkmcnt(0)
	v_mfma_f32_32x32x16_bf16 v[48:63], v[88:91], v[92:95], v[48:63]
	v_mfma_f32_32x32x16_bf16 v[32:47], v[88:91], v[96:99], v[32:47]
	ds_read_b128 v[88:91], v84 offset:4096
	s_waitcnt lgkmcnt(0)
	v_mfma_f32_32x32x16_bf16 v[16:31], v[88:91], v[92:95], v[16:31]
	v_mfma_f32_32x32x16_bf16 v[0:15], v[88:91], v[96:99], v[0:15]
	ds_read_b128 v[88:91], v86
	ds_read_b128 v[92:95], v87 offset:16384
	ds_read_b128 v[96:99], v87 offset:20480
	s_waitcnt lgkmcnt(0)
	v_mfma_f32_32x32x16_bf16 v[48:63], v[88:91], v[92:95], v[48:63]
	v_mfma_f32_32x32x16_bf16 v[32:47], v[88:91], v[96:99], v[32:47]
	ds_read_b128 v[88:91], v86 offset:4096
	s_waitcnt vmcnt(0)
	s_waitcnt vmcnt(0) lgkmcnt(0)
	s_barrier
	v_mfma_f32_32x32x16_bf16 v[16:31], v[88:91], v[92:95], v[16:31]
	v_mfma_f32_32x32x16_bf16 v[0:15], v[88:91], v[96:99], v[0:15]
	v_lshl_add_u64 v[88:89], v[64:65], 0, s[60:61]
	global_load_lds_dwordx4 v[88:89], off
	v_lshl_add_u64 v[88:89], v[66:67], 0, s[60:61]
	s_mov_b32 m0, s28
	s_nop 0
	global_load_lds_dwordx4 v[88:89], off
	v_lshl_add_u64 v[88:89], v[68:69], 0, s[60:61]
	s_mov_b32 m0, s29
	s_nop 0
	global_load_lds_dwordx4 v[88:89], off
	v_lshl_add_u64 v[88:89], v[70:71], 0, s[60:61]
	s_mov_b32 m0, s40
	s_nop 0
	global_load_lds_dwordx4 v[88:89], off
	v_lshl_add_u64 v[88:89], v[72:73], 0, s[60:61]
	s_mov_b32 m0, s41
	s_nop 0
	global_load_lds_dwordx4 v[88:89], off
	v_lshl_add_u64 v[88:89], v[74:75], 0, s[60:61]
	s_mov_b32 m0, s42
	s_nop 0
	global_load_lds_dwordx4 v[88:89], off
	v_lshl_add_u64 v[88:89], v[76:77], 0, s[60:61]
	s_mov_b32 m0, s43
	s_nop 0
	global_load_lds_dwordx4 v[88:89], off
	v_lshl_add_u64 v[88:89], v[78:79], 0, s[60:61]
	s_mov_b32 m0, s44
	s_nop 0
	global_load_lds_dwordx4 v[88:89], off
	ds_read_b128 v[88:91], v80 offset:32768
	ds_read_b128 v[92:95], v82 offset:49152
	ds_read_b128 v[96:99], v82 offset:53248
	s_waitcnt lgkmcnt(0)
	v_mfma_f32_32x32x16_bf16 v[48:63], v[88:91], v[92:95], v[48:63]
	s_mov_b32 m0, s20
	v_mfma_f32_32x32x16_bf16 v[32:47], v[88:91], v[96:99], v[32:47]
	ds_read_b128 v[88:91], v80 offset:36864
	s_waitcnt lgkmcnt(0)
	v_mfma_f32_32x32x16_bf16 v[16:31], v[88:91], v[92:95], v[16:31]
	v_mfma_f32_32x32x16_bf16 v[0:15], v[88:91], v[96:99], v[0:15]
	ds_read_b128 v[88:91], v81 offset:32768
	ds_read_b128 v[92:95], v83 offset:49152
	ds_read_b128 v[96:99], v83 offset:53248
	s_waitcnt lgkmcnt(0)
	v_mfma_f32_32x32x16_bf16 v[48:63], v[88:91], v[92:95], v[48:63]
	v_mfma_f32_32x32x16_bf16 v[32:47], v[88:91], v[96:99], v[32:47]
	ds_read_b128 v[88:91], v81 offset:36864
	s_waitcnt lgkmcnt(0)
	v_mfma_f32_32x32x16_bf16 v[16:31], v[88:91], v[92:95], v[16:31]
	v_mfma_f32_32x32x16_bf16 v[0:15], v[88:91], v[96:99], v[0:15]
	ds_read_b128 v[88:91], v84 offset:32768
	ds_read_b128 v[92:95], v85 offset:49152
	ds_read_b128 v[96:99], v85 offset:53248
	s_waitcnt lgkmcnt(0)
	v_mfma_f32_32x32x16_bf16 v[48:63], v[88:91], v[92:95], v[48:63]
	v_mfma_f32_32x32x16_bf16 v[32:47], v[88:91], v[96:99], v[32:47]
	ds_read_b128 v[88:91], v84 offset:36864
	s_waitcnt lgkmcnt(0)
	v_mfma_f32_32x32x16_bf16 v[16:31], v[88:91], v[92:95], v[16:31]
	v_mfma_f32_32x32x16_bf16 v[0:15], v[88:91], v[96:99], v[0:15]
	ds_read_b128 v[88:91], v86 offset:32768
	ds_read_b128 v[92:95], v87 offset:49152
	ds_read_b128 v[96:99], v87 offset:53248
	s_waitcnt lgkmcnt(0)
	v_mfma_f32_32x32x16_bf16 v[48:63], v[88:91], v[92:95], v[48:63]
	v_mfma_f32_32x32x16_bf16 v[32:47], v[88:91], v[96:99], v[32:47]
	ds_read_b128 v[88:91], v86 offset:36864
	s_waitcnt vmcnt(0)
	s_waitcnt vmcnt(0) lgkmcnt(0)
	s_barrier
; #define WAIT_V0() asm volatile("s_waitcnt vmcnt(0)" ::: "memory")
; DI void gemm_core(char* smem, int nk, const char* Ab, const char* Bb, const unsigned (&aoff)[4], const unsigned (&boff)[4],
;                   f32x16 (&acc)[2][2]) {
;     ...
;   for (int kt = 0; kt < nk; ++kt) {
;     const int cur = kt & 1;
;     if (kt + 1 < nk) stage(cur ^ 1, kt + 1);
;     const char* sb = smem + cur * STAGE_B;
; #pragma unroll
;     for (int ks = 0; ks < 4; ++ks) {
;       bf16x8 af[2], bfr[2];
; #pragma unroll
;       for (int mb = 0; mb < 2; ++mb) af[mb] = *(const bf16x8*)(sb + a_base + mb * 4096 + xo[ks]);
; #pragma unroll
;       for (int nb = 0; nb < 2; ++nb) bfr[nb] = *(const bf16x8*)(sb + b_base + nb * 4096 + xo[ks]);
; #pragma unroll
;       for (int mb = 0; mb < 2; ++mb)
; #pragma unroll
;         for (int nb = 0; nb < 2; ++nb)
;           acc[mb][nb] = __builtin_amdgcn_mfma_f32_32x32x16_bf16(af[mb], bfr[nb], acc[mb][nb], 0, 0, 0);
;     }
;     WAIT_V0();
;     __syncthreads();
;   }
	v_mfma_f32_32x32x16_bf16 v[16:31], v[88:91], v[92:95], v[16:31]
	v_mfma_f32_32x32x16_bf16 v[0:15], v[88:91], v[96:99], v[0:15]
	v_lshl_add_u64 v[88:89], v[64:65], 0, s[62:63]
	global_load_lds_dwordx4 v[88:89], off
	v_lshl_add_u64 v[88:89], v[66:67], 0, s[62:63]
	s_mov_b32 m0, s21
	s_nop 0
	global_load_lds_dwordx4 v[88:89], off
	v_lshl_add_u64 v[88:89], v[68:69], 0, s[62:63]
	s_mov_b32 m0, s22
	s_nop 0
	global_load_lds_dwordx4 v[88:89], off
	v_lshl_add_u64 v[88:89], v[70:71], 0, s[62:63]
	s_mov_b32 m0, s1
	s_nop 0
	global_load_lds_dwordx4 v[88:89], off
	v_lshl_add_u64 v[88:89], v[72:73], 0, s[62:63]
	s_mov_b32 m0, s16
	s_nop 0
	global_load_lds_dwordx4 v[88:89], off
	v_lshl_add_u64 v[88:89], v[74:75], 0, s[62:63]
	s_mov_b32 m0, s17
	s_nop 0
	global_load_lds_dwordx4 v[88:89], off
	v_lshl_add_u64 v[88:89], v[76:77], 0, s[62:63]
	s_mov_b32 m0, s18
	s_nop 0
	global_load_lds_dwordx4 v[88:89], off
	v_lshl_add_u64 v[88:89], v[78:79], 0, s[62:63]
	s_mov_b32 m0, s19
	s_nop 0
	global_load_lds_dwordx4 v[88:89], off
	ds_read_b128 v[88:91], v80
	ds_read_b128 v[92:95], v82 offset:16384
	ds_read_b128 v[96:99], v82 offset:20480
	s_waitcnt lgkmcnt(0)
	v_mfma_f32_32x32x16_bf16 v[48:63], v[88:91], v[92:95], v[48:63]
	s_mov_b32 m0, s23
	v_mfma_f32_32x32x16_bf16 v[32:47], v[88:91], v[96:99], v[32:47]
	ds_read_b128 v[88:91], v80 offset:4096
	s_waitcnt lgkmcnt(0)
	v_mfma_f32_32x32x16_bf16 v[16:31], v[88:91], v[92:95], v[16:31]
	v_mfma_f32_32x32x16_bf16 v[0:15], v[88:91], v[96:99], v[0:15]
	ds_read_b128 v[88:91], v81
	ds_read_b128 v[92:95], v83 offset:16384
	ds_read_b128 v[96:99], v83 offset:20480
	s_waitcnt lgkmcnt(0)
	v_mfma_f32_32x32x16_bf16 v[48:63], v[88:91], v[92:95], v[48:63]
	v_mfma_f32_32x32x16_bf16 v[32:47], v[88:91], v[96:99], v[32:47]
	ds_read_b128 v[88:91], v81 offset:4096
	s_waitcnt lgkmcnt(0)
	v_mfma_f32_32x32x16_bf16 v[16:31], v[88:91], v[92:95], v[16:31]
	v_mfma_f32_32x32x16_bf16 v[0:15], v[88:91], v[96:99], v[0:15]
	ds_read_b128 v[88:91], v84
	ds_read_b128 v[92:95], v85 offset:16384
	ds_read_b128 v[96:99], v85 offset:20480
	s_waitcnt lgkmcnt(0)
	v_mfma_f32_32x32x16_bf16 v[48:63], v[88:91], v[92:95], v[48:63]
	v_mfma_f32_32x32x16_bf16 v[32:47], v[88:91], v[96:99], v[32:47]
	ds_read_b128 v[88:91], v84 offset:4096
	s_waitcnt lgkmcnt(0)
	v_mfma_f32_32x32x16_bf16 v[16:31], v[88:91], v[92:95], v[16:31]
	v_mfma_f32_32x32x16_bf16 v[0:15], v[88:91], v[96:99], v[0:15]
	ds_read_b128 v[88:91], v86
	ds_read_b128 v[92:95], v87 offset:16384
	ds_read_b128 v[96:99], v87 offset:20480
	s_waitcnt lgkmcnt(0)
	v_mfma_f32_32x32x16_bf16 v[48:63], v[88:91], v[92:95], v[48:63]
	v_mfma_f32_32x32x16_bf16 v[32:47], v[88:91], v[96:99], v[32:47]
	ds_read_b128 v[88:91], v86 offset:4096
	s_waitcnt vmcnt(0)
	s_waitcnt vmcnt(0) lgkmcnt(0)
	s_barrier
	v_mfma_f32_32x32x16_bf16 v[16:31], v[88:91], v[92:95], v[16:31]
	v_mfma_f32_32x32x16_bf16 v[0:15], v[88:91], v[96:99], v[0:15]
	v_lshl_add_u64 v[88:89], v[64:65], 0, s[64:65]
	global_load_lds_dwordx4 v[88:89], off
	v_lshl_add_u64 v[88:89], v[66:67], 0, s[64:65]
	s_mov_b32 m0, s28
	v_lshl_add_u64 v[64:65], v[64:65], 0, s[66:67]
	global_load_lds_dwordx4 v[88:89], off
	v_lshl_add_u64 v[88:89], v[68:69], 0, s[64:65]
	s_mov_b32 m0, s29
	s_nop 0
	global_load_lds_dwordx4 v[88:89], off
	v_lshl_add_u64 v[88:89], v[70:71], 0, s[64:65]
	s_mov_b32 m0, s40
	s_nop 0
	global_load_lds_dwordx4 v[88:89], off
	v_lshl_add_u64 v[88:89], v[72:73], 0, s[64:65]
	s_mov_b32 m0, s41
	s_nop 0
	global_load_lds_dwordx4 v[88:89], off
	v_lshl_add_u64 v[88:89], v[74:75], 0, s[64:65]
	s_mov_b32 m0, s42
	s_nop 0
	global_load_lds_dwordx4 v[88:89], off
	v_lshl_add_u64 v[88:89], v[76:77], 0, s[64:65]
	s_mov_b32 m0, s43
	s_nop 0
	global_load_lds_dwordx4 v[88:89], off
	v_lshl_add_u64 v[88:89], v[78:79], 0, s[64:65]
	s_mov_b32 m0, s44
	s_nop 0
	global_load_lds_dwordx4 v[88:89], off
	ds_read_b128 v[88:91], v80 offset:32768
	ds_read_b128 v[92:95], v82 offset:49152
	ds_read_b128 v[96:99], v82 offset:53248
	s_waitcnt lgkmcnt(0)
	v_mfma_f32_32x32x16_bf16 v[48:63], v[88:91], v[92:95], v[48:63]
	s_mov_b32 m0, s20
	v_mfma_f32_32x32x16_bf16 v[32:47], v[88:91], v[96:99], v[32:47]
	ds_read_b128 v[88:91], v80 offset:36864
	s_waitcnt lgkmcnt(0)
	v_mfma_f32_32x32x16_bf16 v[16:31], v[88:91], v[92:95], v[16:31]
	v_mfma_f32_32x32x16_bf16 v[0:15], v[88:91], v[96:99], v[0:15]
	ds_read_b128 v[88:91], v81 offset:32768
	ds_read_b128 v[92:95], v83 offset:49152
	ds_read_b128 v[96:99], v83 offset:53248
	s_waitcnt lgkmcnt(0)
	v_mfma_f32_32x32x16_bf16 v[48:63], v[88:91], v[92:95], v[48:63]
	v_mfma_f32_32x32x16_bf16 v[32:47], v[88:91], v[96:99], v[32:47]
	ds_read_b128 v[88:91], v81 offset:36864
	s_waitcnt lgkmcnt(0)
	v_mfma_f32_32x32x16_bf16 v[16:31], v[88:91], v[92:95], v[16:31]
	v_mfma_f32_32x32x16_bf16 v[0:15], v[88:91], v[96:99], v[0:15]
	ds_read_b128 v[88:91], v84 offset:32768
	ds_read_b128 v[92:95], v85 offset:49152
	ds_read_b128 v[96:99], v85 offset:53248
	s_waitcnt lgkmcnt(0)
	v_mfma_f32_32x32x16_bf16 v[48:63], v[88:91], v[92:95], v[48:63]
	v_mfma_f32_32x32x16_bf16 v[32:47], v[88:91], v[96:99], v[32:47]
	ds_read_b128 v[88:91], v84 offset:36864
	s_waitcnt lgkmcnt(0)
	v_mfma_f32_32x32x16_bf16 v[16:31], v[88:91], v[92:95], v[16:31]
	v_mfma_f32_32x32x16_bf16 v[0:15], v[88:91], v[96:99], v[0:15]
	ds_read_b128 v[88:91], v86 offset:32768
	ds_read_b128 v[92:95], v87 offset:49152
	ds_read_b128 v[96:99], v87 offset:53248
	s_waitcnt lgkmcnt(0)
	v_mfma_f32_32x32x16_bf16 v[48:63], v[88:91], v[92:95], v[48:63]
	v_mfma_f32_32x32x16_bf16 v[32:47], v[88:91], v[96:99], v[32:47]
	ds_read_b128 v[88:91], v86 offset:36864
	s_waitcnt vmcnt(0)
	s_waitcnt vmcnt(0) lgkmcnt(0)
	s_barrier
; #define WAIT_V0() asm volatile("s_waitcnt vmcnt(0)" ::: "memory")
; DI void gemm_core(char* smem, int nk, const char* Ab, const char* Bb, const unsigned (&aoff)[4], const unsigned (&boff)[4],
;                   f32x16 (&acc)[2][2]) {
;     ...
;   for (int kt = 0; kt < nk; ++kt) {
;     const int cur = kt & 1;
;     if (kt + 1 < nk) stage(cur ^ 1, kt + 1);
;     const char* sb = smem + cur * STAGE_B;
; #pragma unroll
;     for (int ks = 0; ks < 4; ++ks) {
;       bf16x8 af[2], bfr[2];
; #pragma unroll
;       for (int mb = 0; mb < 2; ++mb) af[mb] = *(const bf16x8*)(sb + a_base + mb * 4096 + xo[ks]);
; #pragma unroll
;       for (int nb = 0; nb < 2; ++nb) bfr[nb] = *(const bf16x8*)(sb + b_base + nb * 4096 + xo[ks]);
; #pragma unroll
;       for (int mb = 0; mb < 2; ++mb)
; #pragma unroll
;         for (int nb = 0; nb < 2; ++nb)
;           acc[mb][nb] = __builtin_amdgcn_mfma_f32_32x32x16_bf16(af[mb], bfr[nb], acc[mb][nb], 0, 0, 0);
;     }
;     WAIT_V0();
;     __syncthreads();
;   }
; DI void phase_gemm_in(const Params& P, int layer, char* smem) {
;     ...
;     epi_foreach(acc, [&](int row, int col, float v) __attribute__((always_inline)) {
;       const int c = n0 + col;
;       Cs[row * 136 + col] = (c >= C_QI && c < C_CQ) ? f2h(v) : f2bf(v);
;     });
	global_load_lds_dwordx4 v[64:65], off
	v_lshl_add_u64 v[64:65], v[66:67], 0, s[66:67]
	s_mov_b32 m0, s21
	v_mfma_f32_32x32x16_bf16 v[16:31], v[88:91], v[92:95], v[16:31]
	global_load_lds_dwordx4 v[64:65], off
	v_lshl_add_u64 v[64:65], v[68:69], 0, s[66:67]
	s_mov_b32 m0, s22
	s_nop 0
	global_load_lds_dwordx4 v[64:65], off
	v_lshl_add_u64 v[64:65], v[70:71], 0, s[66:67]
	s_mov_b32 m0, s1
	v_mfma_f32_32x32x16_bf16 v[0:15], v[88:91], v[96:99], v[0:15]
	global_load_lds_dwordx4 v[64:65], off
	v_lshl_add_u64 v[64:65], v[72:73], 0, s[66:67]
	s_mov_b32 m0, s16
	v_mov_b32_e32 v96, v161
	global_load_lds_dwordx4 v[64:65], off
	v_lshl_add_u64 v[64:65], v[74:75], 0, s[66:67]
	s_mov_b32 m0, s17
	v_mov_b32_e32 v97, v161
	global_load_lds_dwordx4 v[64:65], off
	v_lshl_add_u64 v[64:65], v[76:77], 0, s[66:67]
	s_mov_b32 m0, s18
	s_add_i32 s1, s10, 0xfffffa00
	global_load_lds_dwordx4 v[64:65], off
	v_lshl_add_u64 v[64:65], v[78:79], 0, s[66:67]
	s_mov_b32 m0, s19
	s_nop 0
	global_load_lds_dwordx4 v[64:65], off
	ds_read_b128 v[64:67], v80
	ds_read_b128 v[68:71], v82 offset:16384
	ds_read_b128 v[72:75], v82 offset:20480
	s_waitcnt lgkmcnt(0)
	v_mfma_f32_32x32x16_bf16 v[48:63], v[64:67], v[68:71], v[48:63]
	v_mfma_f32_32x32x16_bf16 v[32:47], v[64:67], v[72:75], v[32:47]
	ds_read_b128 v[64:67], v80 offset:4096
	s_waitcnt lgkmcnt(0)
	v_mfma_f32_32x32x16_bf16 v[16:31], v[64:67], v[68:71], v[16:31]
	v_mfma_f32_32x32x16_bf16 v[0:15], v[64:67], v[72:75], v[0:15]
	ds_read_b128 v[64:67], v81
	ds_read_b128 v[68:71], v83 offset:16384
	ds_read_b128 v[72:75], v83 offset:20480
	s_waitcnt lgkmcnt(0)
	v_mfma_f32_32x32x16_bf16 v[48:63], v[64:67], v[68:71], v[48:63]
	v_mfma_f32_32x32x16_bf16 v[32:47], v[64:67], v[72:75], v[32:47]
	ds_read_b128 v[64:67], v81 offset:4096
	s_waitcnt lgkmcnt(0)
	v_mfma_f32_32x32x16_bf16 v[16:31], v[64:67], v[68:71], v[16:31]
	v_mfma_f32_32x32x16_bf16 v[0:15], v[64:67], v[72:75], v[0:15]
	ds_read_b128 v[64:67], v84
	ds_read_b128 v[68:71], v85 offset:16384
	ds_read_b128 v[72:75], v85 offset:20480
	s_waitcnt lgkmcnt(0)
	v_mfma_f32_32x32x16_bf16 v[48:63], v[64:67], v[68:71], v[48:63]
	v_mfma_f32_32x32x16_bf16 v[32:47], v[64:67], v[72:75], v[32:47]
	ds_read_b128 v[64:67], v84 offset:4096
	s_waitcnt lgkmcnt(0)
	v_mfma_f32_32x32x16_bf16 v[16:31], v[64:67], v[68:71], v[16:31]
	v_mfma_f32_32x32x16_bf16 v[0:15], v[64:67], v[72:75], v[0:15]
	ds_read_b128 v[64:67], v86
	ds_read_b128 v[68:71], v87 offset:16384
	ds_read_b128 v[72:75], v87 offset:20480
	s_waitcnt lgkmcnt(0)
	v_mfma_f32_32x32x16_bf16 v[48:63], v[64:67], v[68:71], v[48:63]
	v_mfma_f32_32x32x16_bf16 v[32:47], v[64:67], v[72:75], v[32:47]
	ds_read_b128 v[64:67], v86 offset:4096
	s_waitcnt vmcnt(0)
	s_waitcnt vmcnt(0) lgkmcnt(0)
	s_barrier
	v_mfma_f32_32x32x16_bf16 v[16:31], v[64:67], v[68:71], v[16:31]
	v_mfma_f32_32x32x16_bf16 v[0:15], v[64:67], v[72:75], v[0:15]
	ds_read_b128 v[64:67], v80 offset:32768
	ds_read_b128 v[68:71], v82 offset:49152
	ds_read_b128 v[72:75], v82 offset:53248
	s_waitcnt lgkmcnt(1)
	v_mfma_f32_32x32x16_bf16 v[48:63], v[64:67], v[68:71], v[48:63]
	s_waitcnt lgkmcnt(0)
	v_mfma_f32_32x32x16_bf16 v[32:47], v[64:67], v[72:75], v[32:47]
	ds_read_b128 v[64:67], v80 offset:36864
	s_waitcnt lgkmcnt(0)
	v_mfma_f32_32x32x16_bf16 v[16:31], v[64:67], v[68:71], v[16:31]
	v_mfma_f32_32x32x16_bf16 v[0:15], v[64:67], v[72:75], v[0:15]
	ds_read_b128 v[64:67], v81 offset:32768
	ds_read_b128 v[68:71], v83 offset:49152
	ds_read_b128 v[72:75], v83 offset:53248
	s_waitcnt lgkmcnt(1)
	v_mfma_f32_32x32x16_bf16 v[48:63], v[64:67], v[68:71], v[48:63]
	s_waitcnt lgkmcnt(0)
	v_mfma_f32_32x32x16_bf16 v[32:47], v[64:67], v[72:75], v[32:47]
	ds_read_b128 v[64:67], v81 offset:36864
	s_waitcnt lgkmcnt(0)
	v_mfma_f32_32x32x16_bf16 v[16:31], v[64:67], v[68:71], v[16:31]
	ds_read_b128 v[68:71], v84 offset:32768
	ds_read_b128 v[76:79], v84 offset:36864
	v_mfma_f32_32x32x16_bf16 v[0:15], v[64:67], v[72:75], v[0:15]
	ds_read_b128 v[64:67], v85 offset:49152
	ds_read_b128 v[72:75], v85 offset:53248
	ds_read_b128 v[80:83], v86 offset:32768
	ds_read_b128 v[88:91], v86 offset:36864
	ds_read_b128 v[92:95], v87 offset:49152
	ds_read_b128 v[84:87], v87 offset:53248
	s_waitcnt vmcnt(0)
	s_waitcnt lgkmcnt(0)
	s_barrier
	v_mfma_f32_32x32x16_bf16 v[48:63], v[68:71], v[64:67], v[48:63]
	v_mfma_f32_32x32x16_bf16 v[48:63], v[80:83], v[92:95], v[48:63]
	v_mfma_f32_32x32x16_bf16 v[32:47], v[68:71], v[72:75], v[32:47]
	v_lshrrev_b32_e32 v69, 3, v96
	v_lshrrev_b32_e32 v68, 1, v97
	v_and_b32_e32 v69, 4, v69
	v_and_b32_e32 v70, 31, v96
	v_and_or_b32 v68, v68, s7, v69
	s_nop 5
	v_cvt_f16_f32_e32 v69, v48
	v_and_or_b32 v70, v97, 64, v70
	v_or_b32_e32 v71, s1, v70
	v_cmp_gt_u32_e64 s[40:41], s45, v71
	v_cvt_pk_bf16_f32 v48, v48, s0
	v_mfma_f32_32x32x16_bf16 v[16:31], v[76:79], v[64:67], v[16:31]
	v_cndmask_b32_e64 v69, v48, v69, s[40:41]
	v_mul_lo_u32 v48, v68, s97
	v_cvt_f16_f32_e32 v68, v49
	v_cvt_pk_bf16_f32 v49, v49, s0
	v_lshl_add_u32 v48, v70, 1, v48
	v_cvt_f16_f32_e32 v64, v51
	v_cndmask_b32_e64 v49, v49, v68, s[40:41]
	ds_write_b16 v48, v49 offset:272
	v_cvt_f16_f32_e32 v49, v50
	v_cvt_pk_bf16_f32 v50, v50, s0
	v_mfma_f32_32x32x16_bf16 v[0:15], v[76:79], v[72:75], v[0:15]
	ds_write_b16 v48, v69
	v_cndmask_b32_e64 v49, v50, v49, s[40:41]
	ds_write_b16 v48, v49 offset:544
	v_cvt_pk_bf16_f32 v49, v51, s0
	v_cndmask_b32_e64 v49, v49, v64, s[40:41]
	ds_write_b16 v48, v49 offset:816
	v_cvt_f16_f32_e32 v49, v52
	v_cvt_f16_f32_e32 v51, v53
	v_cvt_pk_bf16_f32 v50, v52, s0
	v_mfma_f32_32x32x16_bf16 v[32:47], v[80:83], v[84:87], v[32:47]
	v_cndmask_b32_e64 v49, v50, v49, s[40:41]
	v_cvt_f16_f32_e32 v50, v54
	ds_write_b16 v48, v49 offset:2176
; template <class F>
; DI void epi_foreach(const f32x16 (&acc)[2][2], F f) {
;     ...
;   for (int mb = 0; mb < 2; ++mb)
; #pragma unroll
;     for (int nb = 0; nb < 2; ++nb)
; #pragma unroll
;       for (int r = 0; r < 16; ++r) {
;         const int row = wm * 64 + mb * 32 + (r & 3) + 8 * (r >> 2) + 4 * (lane >> 5);
;         const int col = wn * 64 + nb * 32 + (lane & 31);
;         f(row, col, acc[mb][nb][r]);
;         if ((r & 7) == 7) __builtin_amdgcn_sched_barrier(0);
;       }
; DI void phase_gemm_in(const Params& P, int layer, char* smem) {
;     ...
;     epi_foreach(acc, [&](int row, int col, float v) __attribute__((always_inline)) {
;       const int c = n0 + col;
;       Cs[row * 136 + col] = (c >= C_QI && c < C_CQ) ? f2h(v) : f2bf(v);
;     });
	v_cvt_pk_bf16_f32 v49, v53, s0
	v_cndmask_b32_e64 v49, v49, v51, s[40:41]
	v_cvt_f16_f32_e32 v51, v55
	ds_write_b16 v48, v49 offset:2448
	v_cvt_pk_bf16_f32 v49, v54, s0
	v_cndmask_b32_e64 v49, v49, v50, s[40:41]
	ds_write_b16 v48, v49 offset:2720
	v_cvt_pk_bf16_f32 v49, v55, s0
	v_cndmask_b32_e64 v49, v49, v51, s[40:41]
	v_mfma_f32_32x32x16_bf16 v[16:31], v[88:91], v[92:95], v[16:31]
	ds_write_b16 v48, v49 offset:2992
	v_mfma_f32_32x32x16_bf16 v[0:15], v[88:91], v[84:87], v[0:15]
	v_cvt_f16_f32_e32 v49, v56
	v_cvt_pk_bf16_f32 v50, v56, s0
	v_cndmask_b32_e64 v49, v50, v49, s[40:41]
	ds_write_b16 v48, v49 offset:4352
	v_cvt_f16_f32_e32 v49, v57
	v_cvt_pk_bf16_f32 v50, v57, s0
	v_cndmask_b32_e64 v49, v50, v49, s[40:41]
	ds_write_b16 v48, v49 offset:4624
	v_cvt_f16_f32_e32 v49, v58
	v_cvt_pk_bf16_f32 v50, v58, s0
	v_cndmask_b32_e64 v49, v50, v49, s[40:41]
	ds_write_b16 v48, v49 offset:4896
	v_cvt_f16_f32_e32 v49, v59
	v_cvt_pk_bf16_f32 v50, v59, s0
	v_cndmask_b32_e64 v49, v50, v49, s[40:41]
	ds_write_b16 v48, v49 offset:5168
	v_cvt_f16_f32_e32 v49, v60
	v_cvt_pk_bf16_f32 v50, v60, s0
	v_cndmask_b32_e64 v49, v50, v49, s[40:41]
	ds_write_b16 v48, v49 offset:6528
	v_cvt_f16_f32_e32 v49, v61
	v_cvt_pk_bf16_f32 v50, v61, s0
	v_cndmask_b32_e64 v49, v50, v49, s[40:41]
	ds_write_b16 v48, v49 offset:6800
	v_cvt_f16_f32_e32 v49, v62
	v_cvt_pk_bf16_f32 v50, v62, s0
	v_cndmask_b32_e64 v49, v50, v49, s[40:41]
	ds_write_b16 v48, v49 offset:7072
	v_cvt_f16_f32_e32 v49, v63
	v_cvt_pk_bf16_f32 v50, v63, s0
	v_cndmask_b32_e64 v49, v50, v49, s[40:41]
	ds_write_b16 v48, v49 offset:7344
	s_add_i32 s1, s10, 0xfffffa20
	v_or_b32_e32 v49, s1, v70
	v_cmp_gt_u32_e32 vcc, s45, v49
	v_cvt_f16_f32_e32 v49, v32
	v_cvt_pk_bf16_f32 v32, v32, s0
	v_cndmask_b32_e32 v32, v32, v49, vcc
	ds_write_b16 v48, v32 offset:64
	v_cvt_f16_f32_e32 v32, v33
	v_cvt_pk_bf16_f32 v33, v33, s0
	v_cndmask_b32_e32 v32, v33, v32, vcc
	ds_write_b16 v48, v32 offset:336
	v_cvt_f16_f32_e32 v32, v34
	v_cvt_pk_bf16_f32 v33, v34, s0
	v_cndmask_b32_e32 v32, v33, v32, vcc
	ds_write_b16 v48, v32 offset:608
	v_cvt_f16_f32_e32 v32, v35
	v_cvt_pk_bf16_f32 v33, v35, s0
	v_cndmask_b32_e32 v32, v33, v32, vcc
	ds_write_b16 v48, v32 offset:880
	v_cvt_f16_f32_e32 v32, v36
	v_cvt_pk_bf16_f32 v33, v36, s0
	v_cndmask_b32_e32 v32, v33, v32, vcc
	ds_write_b16 v48, v32 offset:2240
	v_cvt_f16_f32_e32 v32, v37
	v_cvt_pk_bf16_f32 v33, v37, s0
	v_cndmask_b32_e32 v32, v33, v32, vcc
	ds_write_b16 v48, v32 offset:2512
	v_cvt_f16_f32_e32 v32, v38
	v_cvt_pk_bf16_f32 v33, v38, s0
	v_cndmask_b32_e32 v32, v33, v32, vcc
	ds_write_b16 v48, v32 offset:2784
	v_cvt_f16_f32_e32 v32, v39
	v_cvt_pk_bf16_f32 v33, v39, s0
	v_cndmask_b32_e32 v32, v33, v32, vcc
	ds_write_b16 v48, v32 offset:3056
	v_cvt_f16_f32_e32 v32, v40
	v_cvt_pk_bf16_f32 v33, v40, s0
	v_cndmask_b32_e32 v32, v33, v32, vcc
	ds_write_b16 v48, v32 offset:4416
	v_cvt_f16_f32_e32 v32, v41
	v_cvt_pk_bf16_f32 v33, v41, s0
	v_cndmask_b32_e32 v32, v33, v32, vcc
	ds_write_b16 v48, v32 offset:4688
	v_cvt_f16_f32_e32 v32, v42
	v_cvt_pk_bf16_f32 v33, v42, s0
	v_cndmask_b32_e32 v32, v33, v32, vcc
	ds_write_b16 v48, v32 offset:4960
	v_cvt_f16_f32_e32 v32, v43
	v_cvt_pk_bf16_f32 v33, v43, s0
	v_cndmask_b32_e32 v32, v33, v32, vcc
	ds_write_b16 v48, v32 offset:5232
	v_cvt_f16_f32_e32 v32, v44
	v_cvt_pk_bf16_f32 v33, v44, s0
	v_cndmask_b32_e32 v32, v33, v32, vcc
	ds_write_b16 v48, v32 offset:6592
	v_cvt_f16_f32_e32 v32, v45
	v_cvt_pk_bf16_f32 v33, v45, s0
	v_cndmask_b32_e32 v32, v33, v32, vcc
	ds_write_b16 v48, v32 offset:6864
	v_cvt_f16_f32_e32 v32, v46
	v_cvt_pk_bf16_f32 v33, v46, s0
	v_cndmask_b32_e32 v32, v33, v32, vcc
	ds_write_b16 v48, v32 offset:7136
	v_cvt_f16_f32_e32 v32, v47
	v_cvt_pk_bf16_f32 v33, v47, s0
	v_cndmask_b32_e32 v32, v33, v32, vcc
	ds_write_b16 v48, v32 offset:7408
	v_cvt_f16_f32_e32 v32, v16
	v_cvt_pk_bf16_f32 v16, v16, s0
	v_cndmask_b32_e64 v16, v16, v32, s[40:41]
	ds_write_b16 v48, v16 offset:8704
	v_cvt_f16_f32_e32 v16, v17
	v_cvt_pk_bf16_f32 v17, v17, s0
	v_cndmask_b32_e64 v16, v17, v16, s[40:41]
	ds_write_b16 v48, v16 offset:8976
	v_cvt_f16_f32_e32 v16, v18
	v_cvt_pk_bf16_f32 v17, v18, s0
	v_cndmask_b32_e64 v16, v17, v16, s[40:41]
	ds_write_b16 v48, v16 offset:9248
	v_cvt_f16_f32_e32 v16, v19
	v_cvt_pk_bf16_f32 v17, v19, s0
	v_cndmask_b32_e64 v16, v17, v16, s[40:41]
	ds_write_b16 v48, v16 offset:9520
	v_cvt_f16_f32_e32 v16, v20
	v_cvt_pk_bf16_f32 v17, v20, s0
	v_cndmask_b32_e64 v16, v17, v16, s[40:41]
	ds_write_b16 v48, v16 offset:10880
	v_cvt_f16_f32_e32 v16, v21
	v_cvt_pk_bf16_f32 v17, v21, s0
	v_cndmask_b32_e64 v16, v17, v16, s[40:41]
	ds_write_b16 v48, v16 offset:11152
	v_cvt_f16_f32_e32 v16, v22
	v_cvt_pk_bf16_f32 v17, v22, s0
	v_cndmask_b32_e64 v16, v17, v16, s[40:41]
	ds_write_b16 v48, v16 offset:11424
	v_cvt_f16_f32_e32 v16, v23
	v_cvt_pk_bf16_f32 v17, v23, s0
	v_cndmask_b32_e64 v16, v17, v16, s[40:41]
	ds_write_b16 v48, v16 offset:11696
	v_cvt_f16_f32_e32 v16, v24
	v_cvt_pk_bf16_f32 v17, v24, s0
	v_cndmask_b32_e64 v16, v17, v16, s[40:41]
	ds_write_b16 v48, v16 offset:13056
	v_cvt_f16_f32_e32 v16, v25
	v_cvt_pk_bf16_f32 v17, v25, s0
	v_cndmask_b32_e64 v16, v17, v16, s[40:41]
	ds_write_b16 v48, v16 offset:13328
	v_cvt_f16_f32_e32 v16, v26
	v_cvt_pk_bf16_f32 v17, v26, s0
; DI int ltid() { int t = threadIdx.x; asm volatile("" : "+v"(t)); return t; }
; DI void store_tile16(const unsigned short* Cs, unsigned short* dst, int ldd) {
;   const int tid = ltid();
; #pragma unroll
;   for (int i = 0; i < 8; ++i) {
;     const int idx = tid + 256 * i;
;     const int row = idx >> 4, c8 = (idx & 15) * 8;
;     *(u32x4*)(dst + (size_t)row * ldd + c8) = *(const u32x4*)(Cs + row * 136 + c8);
;   }
; }
; DI void phase_gemm_in(const Params& P, int layer, char* smem) {
;     ...
;     epi_foreach(acc, [&](int row, int col, float v) __attribute__((always_inline)) {
;       const int c = n0 + col;
;       Cs[row * 136 + col] = (c >= C_QI && c < C_CQ) ? f2h(v) : f2bf(v);
;     });
;     __syncthreads();
;     store_tile16(Cs, Z + (size_t)m0 * ZLD + n0, ZLD);
;     __syncthreads();
	v_cndmask_b32_e64 v16, v17, v16, s[40:41]
	ds_write_b16 v48, v16 offset:13600
	v_cvt_f16_f32_e32 v16, v27
	v_cvt_pk_bf16_f32 v17, v27, s0
	v_cndmask_b32_e64 v16, v17, v16, s[40:41]
	ds_write_b16 v48, v16 offset:13872
	v_cvt_f16_f32_e32 v16, v28
	v_cvt_pk_bf16_f32 v17, v28, s0
	v_cndmask_b32_e64 v16, v17, v16, s[40:41]
	ds_write_b16 v48, v16 offset:15232
	v_cvt_f16_f32_e32 v16, v29
	v_cvt_pk_bf16_f32 v17, v29, s0
	v_cndmask_b32_e64 v16, v17, v16, s[40:41]
	ds_write_b16 v48, v16 offset:15504
	v_cvt_f16_f32_e32 v16, v30
	v_cvt_pk_bf16_f32 v17, v30, s0
	v_cndmask_b32_e64 v16, v17, v16, s[40:41]
	ds_write_b16 v48, v16 offset:15776
	v_cvt_f16_f32_e32 v16, v31
	v_cvt_pk_bf16_f32 v17, v31, s0
	v_cndmask_b32_e64 v16, v17, v16, s[40:41]
	ds_write_b16 v48, v16 offset:16048
	v_cvt_f16_f32_e32 v16, v0
	v_cvt_pk_bf16_f32 v0, v0, s0
	v_cndmask_b32_e32 v0, v0, v16, vcc
	ds_write_b16 v48, v0 offset:8768
	v_cvt_f16_f32_e32 v0, v1
	v_cvt_pk_bf16_f32 v1, v1, s0
	v_cndmask_b32_e32 v0, v1, v0, vcc
	ds_write_b16 v48, v0 offset:9040
	v_cvt_f16_f32_e32 v0, v2
	v_cvt_pk_bf16_f32 v1, v2, s0
	v_cndmask_b32_e32 v0, v1, v0, vcc
	ds_write_b16 v48, v0 offset:9312
	v_cvt_f16_f32_e32 v0, v3
	v_cvt_pk_bf16_f32 v1, v3, s0
	v_cndmask_b32_e32 v0, v1, v0, vcc
	ds_write_b16 v48, v0 offset:9584
	v_cvt_f16_f32_e32 v0, v4
	v_cvt_pk_bf16_f32 v1, v4, s0
	v_cndmask_b32_e32 v0, v1, v0, vcc
	ds_write_b16 v48, v0 offset:10944
	v_cvt_f16_f32_e32 v0, v5
	v_cvt_pk_bf16_f32 v1, v5, s0
	v_cndmask_b32_e32 v0, v1, v0, vcc
	ds_write_b16 v48, v0 offset:11216
	v_cvt_f16_f32_e32 v0, v6
	v_cvt_pk_bf16_f32 v1, v6, s0
	v_cndmask_b32_e32 v0, v1, v0, vcc
	ds_write_b16 v48, v0 offset:11488
	v_cvt_f16_f32_e32 v0, v7
	v_cvt_pk_bf16_f32 v1, v7, s0
	v_cndmask_b32_e32 v0, v1, v0, vcc
	ds_write_b16 v48, v0 offset:11760
	v_cvt_f16_f32_e32 v0, v8
	v_cvt_pk_bf16_f32 v1, v8, s0
	v_cndmask_b32_e32 v0, v1, v0, vcc
	ds_write_b16 v48, v0 offset:13120
	v_cvt_f16_f32_e32 v0, v9
	v_cvt_pk_bf16_f32 v1, v9, s0
	v_cndmask_b32_e32 v0, v1, v0, vcc
	ds_write_b16 v48, v0 offset:13392
	v_cvt_f16_f32_e32 v0, v10
	v_cvt_pk_bf16_f32 v1, v10, s0
	v_cndmask_b32_e32 v0, v1, v0, vcc
	ds_write_b16 v48, v0 offset:13664
	v_cvt_f16_f32_e32 v0, v11
	v_cvt_pk_bf16_f32 v1, v11, s0
	v_cndmask_b32_e32 v0, v1, v0, vcc
	ds_write_b16 v48, v0 offset:13936
	v_cvt_f16_f32_e32 v0, v12
	v_cvt_pk_bf16_f32 v1, v12, s0
	v_cndmask_b32_e32 v0, v1, v0, vcc
	ds_write_b16 v48, v0 offset:15296
	v_cvt_f16_f32_e32 v0, v13
	v_cvt_pk_bf16_f32 v1, v13, s0
	v_cndmask_b32_e32 v0, v1, v0, vcc
	ds_write_b16 v48, v0 offset:15568
	v_cvt_f16_f32_e32 v0, v14
	v_cvt_pk_bf16_f32 v1, v14, s0
	v_cndmask_b32_e32 v0, v1, v0, vcc
	ds_write_b16 v48, v0 offset:15840
	v_cvt_f16_f32_e32 v0, v15
	v_cvt_pk_bf16_f32 v1, v15, s0
	v_cndmask_b32_e32 v0, v1, v0, vcc
	ds_write_b16 v48, v0 offset:16112
	s_mul_i32 s15, s15, 0xb0000
	s_mul_hi_i32 s0, s0, 0x1600
	s_add_u32 s15, s86, s15
	s_addc_u32 s16, s87, s0
	s_lshl_b64 s[0:1], s[10:11], 1
	v_mov_b32_e32 v8, v161
	s_waitcnt lgkmcnt(0)
	s_barrier
	s_add_u32 s0, s15, s0
	s_addc_u32 s1, s16, s1
	v_lshlrev_b32_e32 v0, 4, v8
	v_and_b32_e32 v136, 0xf0, v0
	v_ashrrev_i32_e32 v6, 4, v8
	v_lshl_add_u64 v[4:5], s[0:1], 0, v[136:137]
	v_mad_u64_u32 v[0:1], s[0:1], v6, s97, v[136:137]
	ds_read_b128 v[0:3], v0
	v_mad_i64_i32 v[6:7], s[0:1], v6, s33, v[4:5]
	s_add_i32 s14, s14, s70
	s_add_i32 s13, s13, s3
	s_waitcnt lgkmcnt(0)
	global_store_dwordx4 v[6:7], v[0:3], off
	s_cmpk_gt_i32 s14, 0x15ff
	s_nop 0
	v_add_u32_e32 v0, 0x100, v8
	v_ashrrev_i32_e32 v6, 4, v0
	v_mad_u64_u32 v[0:1], s[0:1], v6, s97, v[136:137]
	ds_read_b128 v[0:3], v0
	v_mad_i64_i32 v[6:7], s[0:1], v6, s33, v[4:5]
	s_waitcnt lgkmcnt(0)
	global_store_dwordx4 v[6:7], v[0:3], off
	s_nop 1
	v_add_u32_e32 v0, 0x200, v8
	v_ashrrev_i32_e32 v6, 4, v0
	v_mad_u64_u32 v[0:1], s[0:1], v6, s97, v[136:137]
	ds_read_b128 v[0:3], v0
	v_mad_i64_i32 v[6:7], s[0:1], v6, s33, v[4:5]
	s_waitcnt lgkmcnt(0)
	global_store_dwordx4 v[6:7], v[0:3], off
	s_nop 1
	v_add_u32_e32 v0, 0x300, v8
	v_ashrrev_i32_e32 v6, 4, v0
	v_mad_u64_u32 v[0:1], s[0:1], v6, s97, v[136:137]
	ds_read_b128 v[0:3], v0
	v_mad_i64_i32 v[6:7], s[0:1], v6, s33, v[4:5]
	s_waitcnt lgkmcnt(0)
	global_store_dwordx4 v[6:7], v[0:3], off
	s_nop 1
	v_add_u32_e32 v0, 0x400, v8
	v_ashrrev_i32_e32 v6, 4, v0
	v_mad_u64_u32 v[0:1], s[0:1], v6, s97, v[136:137]
	ds_read_b128 v[0:3], v0
	v_mad_i64_i32 v[6:7], s[0:1], v6, s33, v[4:5]
	s_waitcnt lgkmcnt(0)
	global_store_dwordx4 v[6:7], v[0:3], off
	s_nop 1
	v_add_u32_e32 v0, 0x500, v8
	v_ashrrev_i32_e32 v6, 4, v0
	v_mad_u64_u32 v[0:1], s[0:1], v6, s97, v[136:137]
	ds_read_b128 v[0:3], v0
	v_mad_i64_i32 v[6:7], s[0:1], v6, s33, v[4:5]
	s_waitcnt lgkmcnt(0)
	global_store_dwordx4 v[6:7], v[0:3], off
	s_nop 1
	v_add_u32_e32 v0, 0x600, v8
	v_ashrrev_i32_e32 v6, 4, v0
	v_mad_u64_u32 v[0:1], s[0:1], v6, s97, v[136:137]
	ds_read_b128 v[0:3], v0
	v_mad_i64_i32 v[6:7], s[0:1], v6, s33, v[4:5]
	s_waitcnt lgkmcnt(0)
	global_store_dwordx4 v[6:7], v[0:3], off
	s_nop 1
	v_add_u32_e32 v0, 0x700, v8
	v_ashrrev_i32_e32 v6, 4, v0
	v_mad_u64_u32 v[0:1], s[0:1], v6, s97, v[136:137]
	ds_read_b128 v[0:3], v0
	v_mad_i64_i32 v[4:5], s[0:1], v6, s33, v[4:5]
	s_waitcnt lgkmcnt(0)
	global_store_dwordx4 v[4:5], v[0:3], off
	s_barrier
	s_cbranch_scc0 .LBB0_436
